# sc1 on the full-line stores whose consumers are on other CUs or nowhere: XB in P0, transposed weights, bf16 cache / p copies, rolled f32 rows, final-norm y (barrier / kernel-end L2 flush), on top of n
# baseline (speedup 1.0000x reference)
; #define LAS __attribute__((address_space(3)))
; __device__ __forceinline__ unsigned cvt_pk(float lo, float hi) { unsigned r; asm("v_cvt_pk_bf16_f32 %0, %1, %2" : "=v"(r) : "v"(lo), "v"(hi)); return r; }
; template <bool GU>
; __device__ __forceinline__ void transpose_item(const float* W, int K, int N, bf16* WT, const float* gs, LAS float* scr, int item, int lane) {
;     ...
;     const int c = lane & 7;
; #pragma unroll
;     for (int j = 0; j < 4; ++j) { const int n = (lane >> 3) + 8 * j; const LAS float* s = scr + (8 * c) * 33 + n;
;         v4u o; o.x = cvt_pk(s[0 * 33], s[1 * 33]); o.y = cvt_pk(s[2 * 33], s[3 * 33]); o.z = cvt_pk(s[4 * 33], s[5 * 33]); o.w = cvt_pk(s[6 * 33], s[7 * 33]);
;         *(v4u*)(WT + (size_t)(d0 + n) * K + k0 + 8 * c) = o; }
.LBB0_14:
	s_waitcnt lgkmcnt(0)
	ds_read2_b32 v[48:49], v56 offset0:33 offset1:41
	ds_read2_b32 v[50:51], v56 offset1:8
	ds_read2_b32 v[52:53], v56 offset0:66 offset1:74
	ds_read2_b32 v[94:95], v56 offset0:99 offset1:107
	ds_read2_b32 v[96:97], v56 offset0:132 offset1:140
	ds_read2_b32 v[98:99], v56 offset0:165 offset1:173
	ds_read2_b32 v[100:101], v56 offset0:198 offset1:206
	ds_read2_b32 v[102:103], v56 offset0:231 offset1:239
	v_add_u32_e32 v106, s12, v55
	v_ashrrev_i32_e32 v107, 31, v106
	v_lshl_add_u64 v[104:105], s[14:15], 1, v[6:7]
	v_lshlrev_b64 v[106:107], 11, v[106:107]
	s_waitcnt lgkmcnt(6)
	v_cvt_pk_bf16_f32 v44, v50, v48
	v_lshl_add_u64 v[106:107], v[104:105], 0, v[106:107]
	v_add_u32_e32 v48, s12, v57
	s_waitcnt lgkmcnt(4)
	v_cvt_pk_bf16_f32 v45, v52, v94
	s_waitcnt lgkmcnt(2)
	v_cvt_pk_bf16_f32 v46, v96, v98
	s_waitcnt lgkmcnt(0)
	v_cvt_pk_bf16_f32 v47, v100, v102
	global_store_dwordx4 v[106:107], v[44:47], off sc1
	s_nop 1
	v_cvt_pk_bf16_f32 v44, v51, v49
	v_ashrrev_i32_e32 v49, 31, v48
	v_lshlrev_b64 v[48:49], 11, v[48:49]
	v_cvt_pk_bf16_f32 v45, v53, v95
	v_cvt_pk_bf16_f32 v46, v97, v99
	v_cvt_pk_bf16_f32 v47, v101, v103
	v_lshl_add_u64 v[48:49], v[104:105], 0, v[48:49]
	ds_read2_b32 v[50:51], v56 offset0:16 offset1:24
	ds_read2_b32 v[52:53], v56 offset0:49 offset1:57
	ds_read2_b32 v[94:95], v56 offset0:82 offset1:90
	ds_read2_b32 v[96:97], v56 offset0:115 offset1:123
	ds_read2_b32 v[98:99], v56 offset0:148 offset1:156
	ds_read2_b32 v[100:101], v56 offset0:181 offset1:189
	ds_read2_b32 v[102:103], v56 offset0:214 offset1:222
	ds_read2_b32 v[106:107], v56 offset0:247 offset1:255
	global_store_dwordx4 v[48:49], v[44:47], off sc1
	v_add_u32_e32 v48, s12, v58
	v_ashrrev_i32_e32 v49, 31, v48
	v_lshlrev_b64 v[48:49], 11, v[48:49]
	v_lshl_add_u64 v[48:49], v[104:105], 0, v[48:49]
	s_waitcnt lgkmcnt(6)
	v_cvt_pk_bf16_f32 v44, v50, v52
	s_waitcnt lgkmcnt(4)
	v_cvt_pk_bf16_f32 v45, v94, v96
	s_waitcnt lgkmcnt(2)
	v_cvt_pk_bf16_f32 v46, v98, v100
	s_waitcnt lgkmcnt(0)
	v_cvt_pk_bf16_f32 v47, v102, v106
	global_store_dwordx4 v[48:49], v[44:47], off sc1
	v_add_u32_e32 v48, s12, v59
	v_ashrrev_i32_e32 v49, 31, v48
	v_lshlrev_b64 v[48:49], 11, v[48:49]
	v_lshl_add_u64 v[48:49], v[104:105], 0, v[48:49]
	v_cvt_pk_bf16_f32 v44, v51, v53
	v_cvt_pk_bf16_f32 v45, v95, v97
	v_cvt_pk_bf16_f32 v46, v99, v101
	v_cvt_pk_bf16_f32 v47, v103, v107
	global_store_dwordx4 v[48:49], v[44:47], off sc1
	s_waitcnt lgkmcnt(0)

; template <bool GU>
; __device__ __forceinline__ void transpose_item(const float* W, int K, int N, bf16* WT, const float* gs, LAS float* scr, int item, int lane) {
;     const int nblk = N / 32, kb = item / nblk, nb = item % nblk, k0 = 64 * kb, n0 = 32 * nb;
; #pragma unroll 16
;     for (int i = 0; i < 32; ++i) { const int kk = 2 * i + (lane >> 5); float w = W[(size_t)(k0 + kk) * N + n0 + (lane & 31)]; if (gs) w *= gs[k0 + kk]; scr[kk * 33 + (lane & 31)] = w; }
.LBB0_18:
	s_lshl_b32 s4, s3, 1
	s_add_i32 s4, s4, 0x1f700
	s_and_b32 s5, s4, 0x1ffc0
	s_lshl_b32 s4, s3, 5
	s_and_b32 s4, s4, 0x3e0
	v_add_u32_e32 v46, s5, v1
	v_add_u32_e32 v48, s5, v2
	s_lshl_b32 s6, s4, 2
	v_ashrrev_i32_e32 v49, 31, v48
	v_ashrrev_i32_e32 v47, 31, v46
	v_add_u32_e32 v50, s5, v3
	v_add_u32_e32 v52, s5, v12
	v_add_u32_e32 v94, s5, v13
	v_add_u32_e32 v96, s5, v16
	v_add_u32_e32 v98, s5, v17
	v_add_u32_e32 v100, s5, v18
	v_lshl_add_u64 v[44:45], v[8:9], 0, s[6:7]
	v_lshlrev_b64 v[46:47], 12, v[46:47]
	v_lshlrev_b64 v[48:49], 12, v[48:49]
	v_ashrrev_i32_e32 v53, 31, v52
	v_ashrrev_i32_e32 v51, 31, v50
	v_ashrrev_i32_e32 v97, 31, v96
	v_ashrrev_i32_e32 v95, 31, v94
	v_ashrrev_i32_e32 v101, 31, v100
	v_ashrrev_i32_e32 v99, 31, v98
	v_lshl_add_u64 v[48:49], v[44:45], 0, v[48:49]
	v_lshl_add_u64 v[46:47], v[44:45], 0, v[46:47]
	v_lshlrev_b64 v[50:51], 12, v[50:51]
	v_lshlrev_b64 v[52:53], 12, v[52:53]
	v_lshlrev_b64 v[94:95], 12, v[94:95]
	v_lshlrev_b64 v[96:97], 12, v[96:97]
	v_lshlrev_b64 v[98:99], 12, v[98:99]
	v_lshlrev_b64 v[100:101], 12, v[100:101]
	v_lshl_add_u64 v[52:53], v[44:45], 0, v[52:53]
	v_lshl_add_u64 v[50:51], v[44:45], 0, v[50:51]
	v_lshl_add_u64 v[96:97], v[44:45], 0, v[96:97]
	v_lshl_add_u64 v[94:95], v[44:45], 0, v[94:95]
	v_lshl_add_u64 v[100:101], v[44:45], 0, v[100:101]
	v_lshl_add_u64 v[98:99], v[44:45], 0, v[98:99]
	global_load_dword v93, v[48:49], off nt
	global_load_dword v102, v[46:47], off nt
	global_load_dword v103, v[52:53], off nt
	global_load_dword v104, v[50:51], off nt
	global_load_dword v105, v[96:97], off nt
	global_load_dword v106, v[94:95], off nt
	global_load_dword v107, v[100:101], off nt
	global_load_dword v108, v[98:99], off nt
	v_add_u32_e32 v46, s5, v19
	v_add_u32_e32 v48, s5, v20
	v_ashrrev_i32_e32 v49, 31, v48
	v_ashrrev_i32_e32 v47, 31, v46
	v_add_u32_e32 v50, s5, v21
	v_add_u32_e32 v52, s5, v22
	v_add_u32_e32 v94, s5, v23
	v_add_u32_e32 v96, s5, v24
	v_add_u32_e32 v98, s5, v25
	v_add_u32_e32 v100, s5, v26
	v_lshlrev_b64 v[46:47], 12, v[46:47]
	v_lshlrev_b64 v[48:49], 12, v[48:49]
	v_ashrrev_i32_e32 v53, 31, v52
	v_ashrrev_i32_e32 v51, 31, v50
	v_ashrrev_i32_e32 v97, 31, v96
	v_ashrrev_i32_e32 v95, 31, v94
	v_ashrrev_i32_e32 v101, 31, v100
	v_ashrrev_i32_e32 v99, 31, v98
	v_lshl_add_u64 v[48:49], v[44:45], 0, v[48:49]
	v_lshl_add_u64 v[46:47], v[44:45], 0, v[46:47]
	v_lshlrev_b64 v[50:51], 12, v[50:51]
	v_lshlrev_b64 v[52:53], 12, v[52:53]
	v_lshlrev_b64 v[94:95], 12, v[94:95]
	v_lshlrev_b64 v[96:97], 12, v[96:97]
	v_lshlrev_b64 v[98:99], 12, v[98:99]
	v_lshlrev_b64 v[100:101], 12, v[100:101]
	v_lshl_add_u64 v[52:53], v[44:45], 0, v[52:53]
	v_lshl_add_u64 v[50:51], v[44:45], 0, v[50:51]
	v_lshl_add_u64 v[96:97], v[44:45], 0, v[96:97]
	v_lshl_add_u64 v[94:95], v[44:45], 0, v[94:95]
	v_lshl_add_u64 v[100:101], v[44:45], 0, v[100:101]
	v_lshl_add_u64 v[98:99], v[44:45], 0, v[98:99]
	global_load_dword v109, v[48:49], off nt
	global_load_dword v110, v[46:47], off nt
	global_load_dword v111, v[52:53], off nt
	global_load_dword v112, v[50:51], off nt
	global_load_dword v113, v[96:97], off nt
	global_load_dword v114, v[94:95], off nt
	global_load_dword v115, v[100:101], off nt
	global_load_dword v116, v[98:99], off nt
	v_add_u32_e32 v46, s5, v27
	v_add_u32_e32 v48, s5, v28
	v_ashrrev_i32_e32 v49, 31, v48
	v_ashrrev_i32_e32 v47, 31, v46
	v_add_u32_e32 v50, s5, v29
	v_add_u32_e32 v52, s5, v30
	v_add_u32_e32 v94, s5, v31
	v_add_u32_e32 v96, s5, v32
	v_add_u32_e32 v98, s5, v33
	v_add_u32_e32 v100, s5, v34
	v_lshlrev_b64 v[46:47], 12, v[46:47]
	v_lshlrev_b64 v[48:49], 12, v[48:49]
	v_ashrrev_i32_e32 v53, 31, v52
	v_ashrrev_i32_e32 v51, 31, v50
	v_ashrrev_i32_e32 v97, 31, v96
	v_ashrrev_i32_e32 v95, 31, v94
	v_ashrrev_i32_e32 v101, 31, v100
	v_ashrrev_i32_e32 v99, 31, v98
	v_lshl_add_u64 v[48:49], v[44:45], 0, v[48:49]
	v_lshl_add_u64 v[46:47], v[44:45], 0, v[46:47]
	v_lshlrev_b64 v[50:51], 12, v[50:51]
	v_lshlrev_b64 v[52:53], 12, v[52:53]
	v_lshlrev_b64 v[94:95], 12, v[94:95]
	v_lshlrev_b64 v[96:97], 12, v[96:97]
	v_lshlrev_b64 v[98:99], 12, v[98:99]
	v_lshlrev_b64 v[100:101], 12, v[100:101]
	v_lshl_add_u64 v[52:53], v[44:45], 0, v[52:53]
	v_lshl_add_u64 v[50:51], v[44:45], 0, v[50:51]
	v_lshl_add_u64 v[96:97], v[44:45], 0, v[96:97]
	v_lshl_add_u64 v[94:95], v[44:45], 0, v[94:95]
	v_lshl_add_u64 v[100:101], v[44:45], 0, v[100:101]
	v_lshl_add_u64 v[98:99], v[44:45], 0, v[98:99]
	global_load_dword v117, v[48:49], off nt
	global_load_dword v118, v[46:47], off nt
	global_load_dword v119, v[52:53], off nt
	global_load_dword v120, v[50:51], off nt
	global_load_dword v121, v[96:97], off nt
	global_load_dword v122, v[94:95], off nt
	global_load_dword v123, v[100:101], off nt
	global_load_dword v124, v[98:99], off nt
	v_add_u32_e32 v46, s5, v35
	v_add_u32_e32 v48, s5, v36
	v_ashrrev_i32_e32 v49, 31, v48
	v_ashrrev_i32_e32 v47, 31, v46
	v_add_u32_e32 v50, s5, v37
	v_add_u32_e32 v52, s5, v38
	v_add_u32_e32 v94, s5, v39
	v_add_u32_e32 v96, s5, v40
	v_add_u32_e32 v98, s5, v41
	v_add_u32_e32 v100, s5, v42
	v_lshlrev_b64 v[46:47], 12, v[46:47]
	v_lshlrev_b64 v[48:49], 12, v[48:49]
	v_ashrrev_i32_e32 v53, 31, v52
	v_ashrrev_i32_e32 v51, 31, v50
	v_ashrrev_i32_e32 v97, 31, v96
	v_ashrrev_i32_e32 v95, 31, v94
	v_ashrrev_i32_e32 v101, 31, v100
	v_ashrrev_i32_e32 v99, 31, v98
	v_lshl_add_u64 v[48:49], v[44:45], 0, v[48:49]
	v_lshl_add_u64 v[46:47], v[44:45], 0, v[46:47]
	v_lshlrev_b64 v[50:51], 12, v[50:51]
	v_lshlrev_b64 v[52:53], 12, v[52:53]
	v_lshlrev_b64 v[94:95], 12, v[94:95]
	v_lshlrev_b64 v[96:97], 12, v[96:97]
	v_lshlrev_b64 v[98:99], 12, v[98:99]
	v_lshlrev_b64 v[100:101], 12, v[100:101]
	v_lshl_add_u64 v[52:53], v[44:45], 0, v[52:53]
	v_lshl_add_u64 v[50:51], v[44:45], 0, v[50:51]
	v_lshl_add_u64 v[96:97], v[44:45], 0, v[96:97]
	v_lshl_add_u64 v[94:95], v[44:45], 0, v[94:95]
	v_lshl_add_u64 v[100:101], v[44:45], 0, v[100:101]
	v_lshl_add_u64 v[44:45], v[44:45], 0, v[98:99]
	global_load_dword v98, v[48:49], off nt
	global_load_dword v99, v[46:47], off nt
	global_load_dword v125, v[52:53], off nt
	global_load_dword v126, v[50:51], off nt
	s_nop 0
	global_load_dword v46, v[96:97], off nt
	global_load_dword v47, v[94:95], off nt
	global_load_dword v48, v[100:101], off nt
	global_load_dword v49, v[44:45], off nt
	v_add_u32_e32 v44, v54, v60
	s_waitcnt vmcnt(31)
; #define LAS __attribute__((address_space(3)))
; __device__ __forceinline__ unsigned cvt_pk(float lo, float hi) { unsigned r; asm("v_cvt_pk_bf16_f32 %0, %1, %2" : "=v"(r) : "v"(lo), "v"(hi)); return r; }
; template <bool GU>
; __device__ __forceinline__ void transpose_item(const float* W, int K, int N, bf16* WT, const float* gs, LAS float* scr, int item, int lane) {
;     ...
;     for (int i = 0; i < 32; ++i) { const int kk = 2 * i + (lane >> 5); float w = W[(size_t)(k0 + kk) * N + n0 + (lane & 31)]; if (gs) w *= gs[k0 + kk]; scr[kk * 33 + (lane & 31)] = w; }
;     asm volatile("s_waitcnt lgkmcnt(0)" ::: "memory");
;     int d0 = n0;
;     if (GU) { const int f = (n0 < FF) ? n0 : n0 - FF; d0 = 256 * (f >> 7) + (f & 127) + ((n0 < FF) ? 0 : 128); }
;     const int c = lane & 7;
; #pragma unroll
;     for (int j = 0; j < 4; ++j) { const int n = (lane >> 3) + 8 * j; const LAS float* s = scr + (8 * c) * 33 + n;
;         v4u o; o.x = cvt_pk(s[0 * 33], s[1 * 33]); o.y = cvt_pk(s[2 * 33], s[3 * 33]); o.z = cvt_pk(s[4 * 33], s[5 * 33]); o.w = cvt_pk(s[6 * 33], s[7 * 33]);
;         *(v4u*)(WT + (size_t)(d0 + n) * K + k0 + 8 * c) = o; }
	ds_write_b32 v44, v93
	s_waitcnt vmcnt(30)
	ds_write_b32 v62, v102
	s_waitcnt vmcnt(29)
	ds_write_b32 v63, v103
	s_waitcnt vmcnt(28)
	ds_write_b32 v64, v104
	s_waitcnt vmcnt(27)
	ds_write_b32 v65, v105
	s_waitcnt vmcnt(26)
	ds_write_b32 v66, v106
	s_waitcnt vmcnt(25)
	ds_write_b32 v67, v107
	s_waitcnt vmcnt(24)
	ds_write_b32 v68, v108
	s_waitcnt vmcnt(23)
	ds_write_b32 v69, v109
	s_waitcnt vmcnt(22)
	ds_write_b32 v70, v110
	s_waitcnt vmcnt(21)
	ds_write_b32 v71, v111
	s_waitcnt vmcnt(20)
	ds_write_b32 v72, v112
	s_waitcnt vmcnt(19)
	ds_write_b32 v73, v113
	s_waitcnt vmcnt(18)
	ds_write_b32 v74, v114
	s_waitcnt vmcnt(17)
	ds_write_b32 v75, v115
	s_waitcnt vmcnt(16)
	ds_write_b32 v76, v116
	s_waitcnt vmcnt(15)
	ds_write_b32 v77, v117
	s_waitcnt vmcnt(14)
	ds_write_b32 v78, v118
	s_waitcnt vmcnt(13)
	ds_write_b32 v79, v119
	s_waitcnt vmcnt(12)
	ds_write_b32 v80, v120
	s_waitcnt vmcnt(11)
	ds_write_b32 v81, v121
	s_waitcnt vmcnt(10)
	ds_write_b32 v82, v122
	s_waitcnt vmcnt(9)
	ds_write_b32 v83, v123
	s_waitcnt vmcnt(8)
	ds_write_b32 v84, v124
	s_waitcnt vmcnt(7)
	ds_write_b32 v85, v98
	s_waitcnt vmcnt(6)
	ds_write_b32 v86, v99
	s_waitcnt vmcnt(5)
	ds_write_b32 v87, v125
	s_waitcnt vmcnt(4)
	ds_write_b32 v88, v126
	s_waitcnt vmcnt(3)
	ds_write_b32 v89, v46
	s_waitcnt vmcnt(2)
	ds_write_b32 v90, v47
	s_waitcnt vmcnt(1)
	ds_write_b32 v91, v48
	s_waitcnt vmcnt(0)
	ds_write_b32 v92, v49
	s_waitcnt lgkmcnt(0)
	ds_read2_b32 v[48:49], v56 offset0:33 offset1:41
	ds_read2_b32 v[50:51], v56 offset1:8
	ds_read2_b32 v[52:53], v56 offset0:66 offset1:74
	ds_read2_b32 v[94:95], v56 offset0:99 offset1:107
	ds_read2_b32 v[96:97], v56 offset0:132 offset1:140
	ds_read2_b32 v[98:99], v56 offset0:165 offset1:173
	ds_read2_b32 v[100:101], v56 offset0:198 offset1:206
	ds_read2_b32 v[102:103], v56 offset0:231 offset1:239
	v_add_u32_e32 v106, s4, v55
	s_lshl_b32 s6, s5, 1
	v_ashrrev_i32_e32 v107, 31, v106
	v_lshl_add_u64 v[104:105], v[4:5], 0, s[6:7]
	v_lshlrev_b64 v[106:107], 11, v[106:107]
	s_waitcnt lgkmcnt(6)
	v_cvt_pk_bf16_f32 v44, v50, v48
	v_lshl_add_u64 v[106:107], v[104:105], 0, v[106:107]
	v_add_u32_e32 v48, s4, v57
	s_waitcnt lgkmcnt(4)
	v_cvt_pk_bf16_f32 v45, v52, v94
	s_waitcnt lgkmcnt(2)
	v_cvt_pk_bf16_f32 v46, v96, v98
	s_waitcnt lgkmcnt(0)
	v_cvt_pk_bf16_f32 v47, v100, v102
	global_store_dwordx4 v[106:107], v[44:47], off sc1
	s_nop 1
	v_cvt_pk_bf16_f32 v44, v51, v49
	v_ashrrev_i32_e32 v49, 31, v48
	v_lshlrev_b64 v[48:49], 11, v[48:49]
	v_cvt_pk_bf16_f32 v45, v53, v95
	v_cvt_pk_bf16_f32 v46, v97, v99
	v_cvt_pk_bf16_f32 v47, v101, v103
	v_lshl_add_u64 v[48:49], v[104:105], 0, v[48:49]
	ds_read2_b32 v[50:51], v56 offset0:16 offset1:24
	ds_read2_b32 v[52:53], v56 offset0:49 offset1:57
	ds_read2_b32 v[94:95], v56 offset0:82 offset1:90
	ds_read2_b32 v[96:97], v56 offset0:115 offset1:123
	ds_read2_b32 v[98:99], v56 offset0:148 offset1:156
	ds_read2_b32 v[100:101], v56 offset0:181 offset1:189
	ds_read2_b32 v[102:103], v56 offset0:214 offset1:222
	ds_read2_b32 v[106:107], v56 offset0:247 offset1:255
	global_store_dwordx4 v[48:49], v[44:47], off sc1
	v_add_u32_e32 v48, s4, v58
	v_ashrrev_i32_e32 v49, 31, v48
	v_lshlrev_b64 v[48:49], 11, v[48:49]
	v_lshl_add_u64 v[48:49], v[104:105], 0, v[48:49]
	s_waitcnt lgkmcnt(6)
	v_cvt_pk_bf16_f32 v44, v50, v52
	s_waitcnt lgkmcnt(4)
	v_cvt_pk_bf16_f32 v45, v94, v96
	s_waitcnt lgkmcnt(2)
	v_cvt_pk_bf16_f32 v46, v98, v100
	s_waitcnt lgkmcnt(0)
	v_cvt_pk_bf16_f32 v47, v102, v106
	global_store_dwordx4 v[48:49], v[44:47], off sc1
	v_add_u32_e32 v48, s4, v59
	v_ashrrev_i32_e32 v49, 31, v48
	v_lshlrev_b64 v[48:49], 11, v[48:49]
	v_lshl_add_u64 v[48:49], v[104:105], 0, v[48:49]
	v_cvt_pk_bf16_f32 v44, v51, v53
	v_cvt_pk_bf16_f32 v45, v95, v97
	v_cvt_pk_bf16_f32 v46, v99, v101
	v_cvt_pk_bf16_f32 v47, v103, v107
	global_store_dwordx4 v[48:49], v[44:47], off sc1
	s_waitcnt lgkmcnt(0)
	s_cbranch_execnz .LBB0_15

; __device__ __forceinline__ unsigned cvt_pk(float lo, float hi) { unsigned r; asm("v_cvt_pk_bf16_f32 %0, %1, %2" : "=v"(r) : "v"(lo), "v"(hi)); return r; }
; __global__ void __launch_bounds__(NWAVES * 64, 2) mega_fwd(Args args) {
;     ...
;         for (int m0 = gw; m0 < MT; m0 += 2 * NGW) {
;             const int m1 = m0 + NGW; const bool has1 = m1 < MT;
;             const float* xr0 = (m0 < MP) ? x_p + (size_t)m0 * DM : x_s + (size_t)(m0 - MP) * DM;
;             const float* xr1 = has1 ? ((m1 < MP) ? x_p + (size_t)m1 * DM : x_s + (size_t)(m1 - MP) * DM) : xr0;
;             f32x4 a[2][4];
; #pragma unroll
;             for (int j = 0; j < 2; ++j) { a[0][2 * j] = *(const f32x4*)(xr0 + j * 512 + lane * 8); a[0][2 * j + 1] = *(const f32x4*)(xr0 + j * 512 + lane * 8 + 4);
;                                           a[1][2 * j] = *(const f32x4*)(xr1 + j * 512 + lane * 8); a[1][2 * j + 1] = *(const f32x4*)(xr1 + j * 512 + lane * 8 + 4); }
; #pragma unroll
;             for (int r = 0; r < 2; ++r) {
;                 const int m = r ? m1 : m0; float ss = 0.f;
; #pragma unroll
;                 for (int j = 0; j < 2; ++j) { const f32x4 p = a[r][2 * j], q = a[r][2 * j + 1];
;                     ss += (p[0] * p[0] + p[1] * p[1]) + (p[2] * p[2] + p[3] * p[3]) + (q[0] * q[0] + q[1] * q[1]) + (q[2] * q[2] + q[3] * q[3]);
;                     v4u w; w.x = cvt_pk(p[0], p[1]); w.y = cvt_pk(p[2], p[3]); w.z = cvt_pk(q[0], q[1]); w.w = cvt_pk(q[2], q[3]);
;                     if (r == 0 || has1) *(v4u*)(XB + (size_t)m * DM + j * 512 + lane * 8) = w; }
; #pragma unroll
;                 for (int o = 1; o < 64; o <<= 1) ss += __shfl_xor(ss, o);
;                 if (lane == 0 && (r == 0 || has1)) ssqb[m] = ss;
.LBB0_61:
	s_waitcnt lgkmcnt(0)
	v_lshl_add_u64 v[0:1], s[30:31], 0, v[22:23]
	global_load_dwordx4 v[16:19], v[0:1], off nt
	global_load_dwordx4 v[34:37], v[0:1], off offset:16 nt
	global_load_dwordx4 v[38:41], v[0:1], off offset:2048 nt
	global_load_dwordx4 v[44:47], v[0:1], off offset:2064 nt
	v_lshl_add_u64 v[8:9], s[28:29], 0, v[22:23]
	global_load_dwordx4 v[4:7], v[8:9], off offset:16 nt
	global_load_dwordx4 v[12:15], v[8:9], off nt
	global_load_dwordx4 v[0:3], v[8:9], off offset:2064 nt
	s_nop 0
	global_load_dwordx4 v[8:11], v[8:9], off offset:2048 nt
	s_lshl_b64 s[28:29], s[4:5], 11
	s_waitcnt vmcnt(7)
	v_mul_f32_e32 v24, v17, v17
	v_mul_f32_e32 v25, v19, v19
	s_waitcnt vmcnt(5)
	v_mul_f32_e32 v48, v39, v39
	v_mul_f32_e32 v49, v41, v41
	v_mul_f32_e32 v33, v35, v35
	s_waitcnt vmcnt(4)
	v_mul_f32_e32 v50, v45, v45
	v_fmac_f32_e32 v24, v16, v16
	v_fmac_f32_e32 v25, v18, v18
	v_fmac_f32_e32 v48, v38, v38
	v_fmac_f32_e32 v49, v40, v40
	v_mul_f32_e32 v42, v37, v37
	v_mul_f32_e32 v51, v47, v47
	v_fmac_f32_e32 v33, v34, v34
	v_fmac_f32_e32 v50, v44, v44
	v_add_f32_e32 v24, v24, v25
	v_add_f32_e32 v25, v48, v49
	v_fmac_f32_e32 v42, v36, v36
	v_fmac_f32_e32 v51, v46, v46
	v_add_f32_e32 v24, v24, v33
	v_add_f32_e32 v25, v25, v50
	v_add_f32_e32 v24, v42, v24
	v_add_f32_e32 v25, v51, v25
	v_add_f32_e32 v24, v24, v25
	ds_bpermute_b32 v25, v26, v24
	v_cvt_pk_bf16_f32 v16, v16, v17
	v_cvt_pk_bf16_f32 v17, v18, v19
	v_cvt_pk_bf16_f32 v18, v34, v35
	v_cvt_pk_bf16_f32 v19, v36, v37
	s_waitcnt lgkmcnt(0)
	v_add_f32_e32 v24, v24, v25
	ds_bpermute_b32 v25, v27, v24
	v_cvt_pk_bf16_f32 v34, v38, v39
	v_cvt_pk_bf16_f32 v35, v40, v41
	v_cvt_pk_bf16_f32 v36, v44, v45
	v_cvt_pk_bf16_f32 v37, v46, v47
	s_waitcnt lgkmcnt(0)
	v_add_f32_e32 v24, v24, v25
	ds_bpermute_b32 v25, v28, v24
	s_waitcnt lgkmcnt(0)
	v_add_f32_e32 v33, v24, v25
	ds_bpermute_b32 v42, v29, v33
	v_lshl_add_u64 v[24:25], v[20:21], 0, s[28:29]
	global_store_dwordx4 v[24:25], v[16:19], off sc1
	global_store_dwordx4 v[24:25], v[34:37], off offset:1024 sc1
	s_waitcnt lgkmcnt(0)
	v_add_f32_e32 v33, v33, v42
	ds_bpermute_b32 v42, v30, v33
	s_waitcnt lgkmcnt(0)
	v_add_f32_e32 v16, v33, v42
	ds_bpermute_b32 v17, v31, v16
	s_and_saveexec_b64 s[28:29], s[0:1]
	s_cbranch_execz .LBB0_63
	s_lshl_b64 s[4:5], s[4:5], 2
	s_add_u32 s4, s2, s4
	s_waitcnt lgkmcnt(0)
	v_add_f32_e32 v16, v16, v17
	s_addc_u32 s5, s3, s5
	global_store_dword v32, v16, s[4:5]
.LBB0_63:
	s_or_b64 exec, exec, s[28:29]
	s_ashr_i32 s9, s8, 31
	s_lshl_b64 s[4:5], s[8:9], 11
	v_cndmask_b32_e64 v19, 0, 1, s[10:11]
	v_lshl_add_u64 v[24:25], v[20:21], 0, s[4:5]
	v_cmp_ne_u32_e64 s[4:5], 1, v19
	s_andn2_b64 vcc, exec, s[10:11]
	s_waitcnt vmcnt(4)
	v_cvt_pk_bf16_f32 v16, v12, v13
	s_waitcnt lgkmcnt(0)
	v_cvt_pk_bf16_f32 v17, v14, v15
	v_cvt_pk_bf16_f32 v18, v4, v5
	v_cvt_pk_bf16_f32 v19, v6, v7
	s_cbranch_vccnz .LBB0_65
	global_store_dwordx4 v[24:25], v[16:19], off sc1
.LBB0_65:
	s_and_b64 vcc, exec, s[4:5]
	s_waitcnt vmcnt(2)
	v_cvt_pk_bf16_f32 v16, v8, v9
	v_cvt_pk_bf16_f32 v17, v10, v11
	v_cvt_pk_bf16_f32 v18, v0, v1
	v_cvt_pk_bf16_f32 v19, v2, v3
	s_cbranch_vccnz .LBB0_67
	global_store_dwordx4 v[24:25], v[16:19], off offset:1024 sc1

; __device__ __forceinline__ unsigned cvt_pk(float lo, float hi) { unsigned r; asm("v_cvt_pk_bf16_f32 %0, %1, %2" : "=v"(r) : "v"(lo), "v"(hi)); return r; }
;     ...
;     for (size_t i = gtid * 8; i < NA; i += gth * 8) {
;         const size_t gi = (size_t)l * NA + i;
;         const f32x4 a = *(const f32x4*)(I.cak + gi), b = *(const f32x4*)(I.cak + gi + 4), c = *(const f32x4*)(I.cav + gi), d = *(const f32x4*)(I.cav + gi + 4);
;         v4u w; w.x = cvt_pk(a[0], a[1]); w.y = cvt_pk(a[2], a[3]); w.z = cvt_pk(b[0], b[1]); w.w = cvt_pk(b[2], b[3]);
;         *(v4u*)((bf16*)(ws + WS_CKA) + gi) = w;
;         w.x = cvt_pk(c[0], c[1]); w.y = cvt_pk(c[2], c[3]); w.z = cvt_pk(d[0], d[1]); w.w = cvt_pk(d[2], d[3]);
;         *(v4u*)((bf16*)(ws + WS_CVA) + gi) = w;
;         if (((i >> 9) & 511) >= 64) { float* dk = out + O_AKS + gi - 32768; float* dv = out + O_AVS + gi - 32768;
;             *(f32x4*)dk = a; *(f32x4*)(dk + 4) = b; *(f32x4*)dv = c; *(f32x4*)(dv + 4) = d; }
;     }
.LBB0_294:
	v_lshl_add_u64 v[0:1], s[12:13], 0, v[18:19]
	global_load_dwordx4 v[4:7], v[0:1], off offset:-16 nt
	s_nop 0
	global_load_dwordx4 v[0:3], v[0:1], off nt
	v_lshl_add_u64 v[8:9], s[14:15], 0, v[18:19]
	s_waitcnt lgkmcnt(0)
	global_load_dwordx4 v[12:15], v[8:9], off offset:-16 nt
	s_nop 0
	global_load_dwordx4 v[8:11], v[8:9], off nt
	v_add_co_u32_e32 v36, vcc, 0x1000000, v22
	v_and_b32_e32 v24, 0x38000, v26
	s_nop 0
	v_addc_co_u32_e32 v37, vcc, 0, v23, vcc
	v_cmp_ne_u64_e32 vcc, 0, v[24:25]
	s_waitcnt vmcnt(3)
	v_cvt_pk_bf16_f32 v28, v4, v5
	v_cvt_pk_bf16_f32 v29, v6, v7
	s_waitcnt vmcnt(2)
	v_cvt_pk_bf16_f32 v30, v0, v1
	v_cvt_pk_bf16_f32 v31, v2, v3
	s_waitcnt vmcnt(1)
	v_cvt_pk_bf16_f32 v32, v12, v13
	v_cvt_pk_bf16_f32 v33, v14, v15
	s_waitcnt vmcnt(0)
	v_cvt_pk_bf16_f32 v34, v8, v9
	v_cvt_pk_bf16_f32 v35, v10, v11
	global_store_dwordx4 v[22:23], v[28:31], off sc1
	global_store_dwordx4 v[36:37], v[32:35], off sc1
	s_and_saveexec_b64 s[52:53], vcc
	s_cbranch_execz .LBB0_293
	v_lshl_add_u64 v[28:29], s[42:43], 0, v[18:19]
	v_add_co_u32_e32 v30, vcc, 0x8c60000, v28
	s_nop 1
	v_addc_co_u32_e32 v31, vcc, 0, v29, vcc
	global_store_dwordx4 v[30:31], v[4:7], off sc1
	global_store_dwordx4 v[30:31], v[0:3], off offset:16 sc1
	s_nop 1
	v_add_co_u32_e32 v0, vcc, 0xac60000, v28
	s_nop 1
	v_addc_co_u32_e32 v1, vcc, 0, v29, vcc
	global_store_dwordx4 v[0:1], v[12:15], off sc1
	global_store_dwordx4 v[0:1], v[8:11], off offset:16 sc1
	s_branch .LBB0_293

; __device__ __forceinline__ unsigned cvt_pk(float lo, float hi) { unsigned r; asm("v_cvt_pk_bf16_f32 %0, %1, %2" : "=v"(r) : "v"(lo), "v"(hi)); return r; }
;     ...
;     for (size_t i = gtid * 8; i < NB; i += gth * 8) {
;         const size_t gi = (size_t)l * NB + i;
;         const f32x4 a = *(const f32x4*)(I.cbk + gi), b = *(const f32x4*)(I.cbk + gi + 4), c = *(const f32x4*)(I.cbv + gi), d = *(const f32x4*)(I.cbv + gi + 4);
;         v4u w; w.x = cvt_pk(a[0], a[1]); w.y = cvt_pk(a[2], a[3]); w.z = cvt_pk(b[0], b[1]); w.w = cvt_pk(b[2], b[3]);
;         *(v4u*)((bf16*)(ws + WS_CKB) + gi) = w;
;         w.x = cvt_pk(c[0], c[1]); w.y = cvt_pk(c[2], c[3]); w.z = cvt_pk(d[0], d[1]); w.w = cvt_pk(d[2], d[3]);
;         *(v4u*)((bf16*)(ws + WS_CVB) + gi) = w;
;         if (((i >> 7) & 127) >= 64) { float* dk = out + O_BKS + gi - 8192; float* dv = out + O_BVS + gi - 8192;
;             *(f32x4*)dk = a; *(f32x4*)(dk + 4) = b; *(f32x4*)dv = c; *(f32x4*)(dv + 4) = d; }
;     }
.LBB0_299:
	v_lshl_add_u64 v[0:1], s[12:13], 0, v[18:19]
	global_load_dwordx4 v[4:7], v[0:1], off offset:-16 nt
	s_nop 0
	global_load_dwordx4 v[0:3], v[0:1], off nt
	v_lshl_add_u64 v[8:9], s[6:7], 0, v[18:19]
	s_waitcnt lgkmcnt(0)
	global_load_dwordx4 v[12:15], v[8:9], off offset:-16 nt
	s_nop 0
	global_load_dwordx4 v[8:11], v[8:9], off nt
	v_add_co_u32_e32 v30, vcc, 0x100000, v20
	v_and_b32_e32 v32, 0x2000, v16
	s_nop 0
	v_addc_co_u32_e32 v31, vcc, 0, v21, vcc
	v_cmp_ne_u32_e32 vcc, 0, v32
	s_waitcnt vmcnt(3)
	v_cvt_pk_bf16_f32 v22, v4, v5
	v_cvt_pk_bf16_f32 v23, v6, v7
	s_waitcnt vmcnt(2)
	v_cvt_pk_bf16_f32 v24, v0, v1
	v_cvt_pk_bf16_f32 v25, v2, v3
	s_waitcnt vmcnt(1)
	v_cvt_pk_bf16_f32 v26, v12, v13
	v_cvt_pk_bf16_f32 v27, v14, v15
	s_waitcnt vmcnt(0)
	v_cvt_pk_bf16_f32 v28, v8, v9
	v_cvt_pk_bf16_f32 v29, v10, v11
	global_store_dwordx4 v[20:21], v[22:25], off sc1
	global_store_dwordx4 v[30:31], v[26:29], off sc1
	s_and_saveexec_b64 s[42:43], vcc
	s_cbranch_execz .LBB0_298
	v_lshl_add_u64 v[22:23], s[40:41], 0, v[18:19]
	v_add_co_u32_e32 v24, vcc, 0xcc78000, v22
	s_nop 1
	v_addc_co_u32_e32 v25, vcc, 0, v23, vcc
	global_store_dwordx4 v[24:25], v[4:7], off sc1
	global_store_dwordx4 v[24:25], v[0:3], off offset:16 sc1
	s_nop 1
	v_add_co_u32_e32 v0, vcc, 0xce78000, v22
	s_nop 1
	v_addc_co_u32_e32 v1, vcc, 0, v23, vcc
	global_store_dwordx4 v[0:1], v[12:15], off sc1
	global_store_dwordx4 v[0:1], v[8:11], off offset:16 sc1
	s_branch .LBB0_298

; __device__ __forceinline__ unsigned cvt_pk(float lo, float hi) { unsigned r; asm("v_cvt_pk_bf16_f32 %0, %1, %2" : "=v"(r) : "v"(lo), "v"(hi)); return r; }
; __device__ __forceinline__ void convert_flat(const float* src, bf16* dst, size_t n, size_t gtid, size_t gthreads) {
;     for (size_t i = gtid * 8; i < n; i += gthreads * 8) {
;         const f32x4 a = *(const f32x4*)(src + i), b = *(const f32x4*)(src + i + 4);
;         v4u w; w.x = cvt_pk(a[0], a[1]); w.y = cvt_pk(a[2], a[3]); w.z = cvt_pk(b[0], b[1]); w.w = cvt_pk(b[2], b[3]);
;         *(v4u*)(dst + i) = w;
;     }
.LBB0_414:
	global_load_dwordx4 v[12:15], v[6:7], off offset:-16 nt
	global_load_dwordx4 v[16:19], v[6:7], off nt
	v_lshl_add_u64 v[10:11], v[10:11], 0, s[6:7]
	v_cmp_lt_u64_e32 vcc, s[28:29], v[10:11]
	v_lshl_add_u64 v[6:7], v[6:7], 0, s[10:11]
	s_or_b64 s[14:15], vcc, s[14:15]
	s_waitcnt vmcnt(1)
	v_cvt_pk_bf16_f32 v12, v12, v13
	v_cvt_pk_bf16_f32 v13, v14, v15
	s_waitcnt vmcnt(0)
	v_cvt_pk_bf16_f32 v14, v16, v17
	v_cvt_pk_bf16_f32 v15, v18, v19
	global_store_dwordx4 v[8:9], v[12:15], off sc1
	v_lshl_add_u64 v[8:9], v[8:9], 0, s[12:13]
	s_andn2_b64 exec, exec, s[14:15]
	s_cbranch_execnz .LBB0_414

; __device__ __forceinline__ unsigned cvt_pk(float lo, float hi) { unsigned r; asm("v_cvt_pk_bf16_f32 %0, %1, %2" : "=v"(r) : "v"(lo), "v"(hi)); return r; }
; __device__ __forceinline__ void convert_flat(const float* src, bf16* dst, size_t n, size_t gtid, size_t gthreads) {
;     for (size_t i = gtid * 8; i < n; i += gthreads * 8) {
;         const f32x4 a = *(const f32x4*)(src + i), b = *(const f32x4*)(src + i + 4);
;         v4u w; w.x = cvt_pk(a[0], a[1]); w.y = cvt_pk(a[2], a[3]); w.z = cvt_pk(b[0], b[1]); w.w = cvt_pk(b[2], b[3]);
;         *(v4u*)(dst + i) = w;
;     }
.LBB0_417:
	global_load_dwordx4 v[6:9], v[4:5], off offset:-16 nt
	global_load_dwordx4 v[10:13], v[4:5], off nt
	v_lshl_add_u64 v[0:1], v[0:1], 0, s[6:7]
	v_cmp_lt_u64_e32 vcc, s[28:29], v[0:1]
	v_lshl_add_u64 v[4:5], v[4:5], 0, s[10:11]
	s_or_b64 s[14:15], vcc, s[14:15]
	s_waitcnt vmcnt(1)
	v_cvt_pk_bf16_f32 v6, v6, v7
	v_cvt_pk_bf16_f32 v7, v8, v9
	s_waitcnt vmcnt(0)
	v_cvt_pk_bf16_f32 v8, v10, v11
	v_cvt_pk_bf16_f32 v9, v12, v13
	global_store_dwordx4 v[2:3], v[6:9], off sc1
	v_lshl_add_u64 v[2:3], v[2:3], 0, s[12:13]
	s_andn2_b64 exec, exec, s[14:15]
	s_cbranch_execnz .LBB0_417

; #define LAS __attribute__((address_space(3)))
; __device__ __forceinline__ unsigned cvt_pk(float lo, float hi) { unsigned r; asm("v_cvt_pk_bf16_f32 %0, %1, %2" : "=v"(r) : "v"(lo), "v"(hi)); return r; }
; template <bool GU>
; __device__ __forceinline__ void transpose_item(const float* W, int K, int N, bf16* WT, const float* gs, LAS float* scr, int item, int lane) {
;     ...
;     const int c = lane & 7;
; #pragma unroll
;     for (int j = 0; j < 4; ++j) { const int n = (lane >> 3) + 8 * j; const LAS float* s = scr + (8 * c) * 33 + n;
;         v4u o; o.x = cvt_pk(s[0 * 33], s[1 * 33]); o.y = cvt_pk(s[2 * 33], s[3 * 33]); o.z = cvt_pk(s[4 * 33], s[5 * 33]); o.w = cvt_pk(s[6 * 33], s[7 * 33]);
;         *(v4u*)(WT + (size_t)(d0 + n) * K + k0 + 8 * c) = o; }
;     asm volatile("s_waitcnt lgkmcnt(0)" ::: "memory");
.LBB0_482:
	s_waitcnt lgkmcnt(0)
	ds_read2_b32 v[64:65], v100 offset0:33 offset1:41
	ds_read2_b32 v[66:67], v100 offset1:8
	ds_read2_b32 v[68:69], v100 offset0:66 offset1:74
	ds_read2_b32 v[70:71], v100 offset0:99 offset1:107
	ds_read2_b32 v[72:73], v100 offset0:132 offset1:140
	ds_read2_b32 v[74:75], v100 offset0:165 offset1:173
	ds_read2_b32 v[76:77], v100 offset0:198 offset1:206
	ds_read2_b32 v[78:79], v100 offset0:231 offset1:239
	v_add_u32_e32 v82, s30, v99
	v_ashrrev_i32_e32 v83, 31, v82
	v_lshl_add_u64 v[80:81], s[42:43], 1, v[12:13]
	v_lshlrev_b64 v[82:83], 11, v[82:83]
	s_waitcnt lgkmcnt(6)
	v_cvt_pk_bf16_f32 v60, v66, v64
	v_lshl_add_u64 v[82:83], v[80:81], 0, v[82:83]
	v_add_u32_e32 v64, s30, v101
	s_waitcnt lgkmcnt(4)
	v_cvt_pk_bf16_f32 v61, v68, v70
	s_waitcnt lgkmcnt(2)
	v_cvt_pk_bf16_f32 v62, v72, v74
	s_waitcnt lgkmcnt(0)
	v_cvt_pk_bf16_f32 v63, v76, v78
	global_store_dwordx4 v[82:83], v[60:63], off sc1
	s_nop 1
	v_cvt_pk_bf16_f32 v60, v67, v65
	v_ashrrev_i32_e32 v65, 31, v64
	v_lshlrev_b64 v[64:65], 11, v[64:65]
	v_cvt_pk_bf16_f32 v61, v69, v71
	v_cvt_pk_bf16_f32 v62, v73, v75
	v_cvt_pk_bf16_f32 v63, v77, v79
	v_lshl_add_u64 v[64:65], v[80:81], 0, v[64:65]
	ds_read2_b32 v[66:67], v100 offset0:16 offset1:24
	ds_read2_b32 v[68:69], v100 offset0:49 offset1:57
	ds_read2_b32 v[70:71], v100 offset0:82 offset1:90
	ds_read2_b32 v[72:73], v100 offset0:115 offset1:123
	ds_read2_b32 v[74:75], v100 offset0:148 offset1:156
	ds_read2_b32 v[76:77], v100 offset0:181 offset1:189
	ds_read2_b32 v[78:79], v100 offset0:214 offset1:222
	ds_read2_b32 v[82:83], v100 offset0:247 offset1:255
	global_store_dwordx4 v[64:65], v[60:63], off sc1
	v_add_u32_e32 v64, s30, v102
	v_ashrrev_i32_e32 v65, 31, v64
	v_lshlrev_b64 v[64:65], 11, v[64:65]
	v_lshl_add_u64 v[64:65], v[80:81], 0, v[64:65]
	s_waitcnt lgkmcnt(6)
	v_cvt_pk_bf16_f32 v60, v66, v68
	s_waitcnt lgkmcnt(4)
	v_cvt_pk_bf16_f32 v61, v70, v72
	s_waitcnt lgkmcnt(2)
	v_cvt_pk_bf16_f32 v62, v74, v76
	s_waitcnt lgkmcnt(0)
	v_cvt_pk_bf16_f32 v63, v78, v82
	global_store_dwordx4 v[64:65], v[60:63], off sc1
	v_add_u32_e32 v64, s30, v103
	v_ashrrev_i32_e32 v65, 31, v64
	v_lshlrev_b64 v[64:65], 11, v[64:65]
	v_lshl_add_u64 v[64:65], v[80:81], 0, v[64:65]
	v_cvt_pk_bf16_f32 v60, v67, v69
	v_cvt_pk_bf16_f32 v61, v71, v73
	v_cvt_pk_bf16_f32 v62, v75, v77
	v_cvt_pk_bf16_f32 v63, v79, v83
	global_store_dwordx4 v[64:65], v[60:63], off sc1
	s_waitcnt lgkmcnt(0)

; template <bool GU>
; __device__ __forceinline__ void transpose_item(const float* W, int K, int N, bf16* WT, const float* gs, LAS float* scr, int item, int lane) {
;     const int nblk = N / 32, kb = item / nblk, nb = item % nblk, k0 = 64 * kb, n0 = 32 * nb;
; #pragma unroll 16
;     for (int i = 0; i < 32; ++i) { const int kk = 2 * i + (lane >> 5); float w = W[(size_t)(k0 + kk) * N + n0 + (lane & 31)]; if (gs) w *= gs[k0 + kk]; scr[kk * 33 + (lane & 31)] = w; }
;     asm volatile("s_waitcnt lgkmcnt(0)" ::: "memory");
; __device__ __forceinline__ void conv_weights(LAS unsigned char* lds, unsigned char* ws, const PIn& I, const int l, const int wave, const int lane, const int gw, const int NGW, const int r_lo, const int r_hi) {
;     ...
;     for (int it = r_lo + gw; it < (r_hi < I_LAYER ? r_hi : I_LAYER); it += NGW) {
;         int r = it;
;         if (r < I_IN) { transpose_item<false>(I.w_in + (size_t)l * DM * NIN, DM, NIN, (bf16*)(wb + W_IN), I.g_mix + l * DM, scr, r, lane); continue; } r -= I_IN;
;         if (r < I_OUT) { transpose_item<false>(I.w_out + (size_t)l * DM * DM, DM, DM, (bf16*)(wb + W_OUT), nullptr, scr, r, lane); continue; } r -= I_OUT;
;         if (r < I_GU) { transpose_item<true>(I.w_gu + (size_t)l * DM * 2 * FF, DM, 2 * FF, (bf16*)(wb + W_GU), I.g_ffn + l * DM, scr, r, lane); continue; } r -= I_GU;
;         if (r < I_D) { transpose_item<false>(I.w_d + (size_t)l * FF * DM, FF, DM, (bf16*)(wb + W_D), nullptr, scr, r, lane); continue; } r -= I_D;
;         if (r < I_PP) { transpose_item<false>(I.w_pp + (size_t)l * DPLE * DM, DPLE, DM, (bf16*)(wb + W_PP), nullptr, scr, r, lane); continue; } r -= I_PP;
;         transpose_item<false>(I.w_pg + (size_t)l * DM * DM, DM, DM, (bf16*)(wb + W_PG), nullptr, scr, r, lane);
.LBB0_486:
	s_cmpk_gt_u32 s1, 0x67f
	s_cbranch_scc0 .LBB0_534
	s_cmpk_gt_u32 s1, 0x117f
	s_cbranch_scc0 .LBB0_497
	s_cmpk_gt_u32 s1, 0x16ff
	s_cbranch_scc0 .LBB0_494
	s_lshl_b32 s9, s1, 1
	s_cmpk_gt_u32 s1, 0x177f
	s_cbranch_scc0 .LBB0_491
	s_add_i32 s6, s9, 0x1d100
	s_and_b32 s7, s6, 0x1ffc0
	s_lshl_b32 s6, s1, 5
	s_and_b32 s6, s6, 0x3e0
	v_add_u32_e32 v64, s7, v0
	s_lshl_b32 s10, s6, 2
	v_add_u32_e32 v62, s7, v1
	v_ashrrev_i32_e32 v65, 31, v64
	v_add_u32_e32 v66, s7, v25
	v_add_u32_e32 v68, s7, v24
	v_add_u32_e32 v70, s7, v27
	v_add_u32_e32 v72, s7, v26
	v_add_u32_e32 v74, s7, v29
	v_add_u32_e32 v76, s7, v28
	v_lshl_add_u64 v[60:61], v[14:15], 0, s[10:11]
	v_ashrrev_i32_e32 v63, 31, v62
	v_lshlrev_b64 v[64:65], 12, v[64:65]
	v_ashrrev_i32_e32 v69, 31, v68
	v_ashrrev_i32_e32 v67, 31, v66
	v_ashrrev_i32_e32 v73, 31, v72
	v_ashrrev_i32_e32 v71, 31, v70
	v_ashrrev_i32_e32 v77, 31, v76
	v_ashrrev_i32_e32 v75, 31, v74
	v_lshlrev_b64 v[62:63], 12, v[62:63]
	v_lshl_add_u64 v[64:65], v[60:61], 0, v[64:65]
	v_lshlrev_b64 v[66:67], 12, v[66:67]
	v_lshlrev_b64 v[68:69], 12, v[68:69]
	v_lshlrev_b64 v[70:71], 12, v[70:71]
	v_lshlrev_b64 v[72:73], 12, v[72:73]
	v_lshlrev_b64 v[74:75], 12, v[74:75]
	v_lshlrev_b64 v[76:77], 12, v[76:77]
	v_lshl_add_u64 v[62:63], v[60:61], 0, v[62:63]
	v_lshl_add_u64 v[68:69], v[60:61], 0, v[68:69]
	v_lshl_add_u64 v[66:67], v[60:61], 0, v[66:67]
	v_lshl_add_u64 v[72:73], v[60:61], 0, v[72:73]
	v_lshl_add_u64 v[70:71], v[60:61], 0, v[70:71]
	v_lshl_add_u64 v[76:77], v[60:61], 0, v[76:77]
	v_lshl_add_u64 v[74:75], v[60:61], 0, v[74:75]
	global_load_dword v78, v[64:65], off nt
	global_load_dword v79, v[62:63], off nt
	global_load_dword v80, v[68:69], off nt
	global_load_dword v81, v[66:67], off nt
	global_load_dword v82, v[72:73], off nt
	global_load_dword v83, v[70:71], off nt
	global_load_dword v84, v[76:77], off nt
	global_load_dword v85, v[74:75], off nt
	v_add_u32_e32 v64, s7, v30
	v_add_u32_e32 v62, s7, v31
	v_ashrrev_i32_e32 v65, 31, v64
	v_add_u32_e32 v66, s7, v33
	v_add_u32_e32 v68, s7, v32
	v_add_u32_e32 v70, s7, v35
	v_add_u32_e32 v72, s7, v34
	v_add_u32_e32 v74, s7, v37
	v_add_u32_e32 v76, s7, v36
	v_ashrrev_i32_e32 v63, 31, v62
	v_lshlrev_b64 v[64:65], 12, v[64:65]
	v_ashrrev_i32_e32 v69, 31, v68
	v_ashrrev_i32_e32 v67, 31, v66
	v_ashrrev_i32_e32 v73, 31, v72
	v_ashrrev_i32_e32 v71, 31, v70
	v_ashrrev_i32_e32 v77, 31, v76
	v_ashrrev_i32_e32 v75, 31, v74
	v_lshlrev_b64 v[62:63], 12, v[62:63]
	v_lshl_add_u64 v[64:65], v[60:61], 0, v[64:65]
	v_lshlrev_b64 v[66:67], 12, v[66:67]
	v_lshlrev_b64 v[68:69], 12, v[68:69]
	v_lshlrev_b64 v[70:71], 12, v[70:71]
	v_lshlrev_b64 v[72:73], 12, v[72:73]
	v_lshlrev_b64 v[74:75], 12, v[74:75]
	v_lshlrev_b64 v[76:77], 12, v[76:77]
	v_lshl_add_u64 v[62:63], v[60:61], 0, v[62:63]
	v_lshl_add_u64 v[68:69], v[60:61], 0, v[68:69]
	v_lshl_add_u64 v[66:67], v[60:61], 0, v[66:67]
	v_lshl_add_u64 v[72:73], v[60:61], 0, v[72:73]
	v_lshl_add_u64 v[70:71], v[60:61], 0, v[70:71]
	v_lshl_add_u64 v[76:77], v[60:61], 0, v[76:77]
	v_lshl_add_u64 v[74:75], v[60:61], 0, v[74:75]
	global_load_dword v86, v[64:65], off nt
	global_load_dword v87, v[62:63], off nt
	global_load_dword v88, v[68:69], off nt
	global_load_dword v89, v[66:67], off nt
	global_load_dword v90, v[72:73], off nt
	global_load_dword v91, v[70:71], off nt
	global_load_dword v92, v[76:77], off nt
	global_load_dword v93, v[74:75], off nt
	v_add_u32_e32 v64, s7, v38
	v_add_u32_e32 v66, s7, v41
	v_add_u32_e32 v68, s7, v40
	v_add_u32_e32 v74, s7, v45
	v_add_u32_e32 v76, s7, v44
	v_add_u32_e32 v62, s7, v39
	v_ashrrev_i32_e32 v65, 31, v64
	v_ashrrev_i32_e32 v69, 31, v68
	v_ashrrev_i32_e32 v67, 31, v66
	v_add_u32_e32 v70, s7, v43
	v_add_u32_e32 v72, s7, v42
	v_ashrrev_i32_e32 v77, 31, v76
	v_ashrrev_i32_e32 v75, 31, v74
	v_ashrrev_i32_e32 v63, 31, v62
	v_lshlrev_b64 v[64:65], 12, v[64:65]
	v_lshlrev_b64 v[66:67], 12, v[66:67]
	v_lshlrev_b64 v[68:69], 12, v[68:69]
	v_ashrrev_i32_e32 v73, 31, v72
	v_ashrrev_i32_e32 v71, 31, v70
	v_lshlrev_b64 v[74:75], 12, v[74:75]
	v_lshlrev_b64 v[76:77], 12, v[76:77]
	v_lshlrev_b64 v[62:63], 12, v[62:63]
	v_lshl_add_u64 v[64:65], v[60:61], 0, v[64:65]
	v_lshl_add_u64 v[68:69], v[60:61], 0, v[68:69]
	v_lshl_add_u64 v[66:67], v[60:61], 0, v[66:67]
	v_lshlrev_b64 v[70:71], 12, v[70:71]
	v_lshlrev_b64 v[72:73], 12, v[72:73]
	v_lshl_add_u64 v[76:77], v[60:61], 0, v[76:77]
	v_lshl_add_u64 v[74:75], v[60:61], 0, v[74:75]
	v_lshl_add_u64 v[62:63], v[60:61], 0, v[62:63]
	v_lshl_add_u64 v[72:73], v[60:61], 0, v[72:73]
	v_lshl_add_u64 v[70:71], v[60:61], 0, v[70:71]
	global_load_dword v94, v[64:65], off nt
	global_load_dword v95, v[62:63], off nt
	global_load_dword v96, v[68:69], off nt
	global_load_dword v97, v[66:67], off nt
	global_load_dword v137, v[72:73], off nt
	global_load_dword v138, v[70:71], off nt
	s_nop 0
	global_load_dword v76, v[76:77], off nt
	s_nop 0
	global_load_dword v74, v[74:75], off nt
	v_add_u32_e32 v64, s7, v46
	v_add_u32_e32 v66, s7, v49
	v_add_u32_e32 v68, s7, v48
	v_add_u32_e32 v62, s7, v47
	v_ashrrev_i32_e32 v65, 31, v64
	v_ashrrev_i32_e32 v69, 31, v68
	v_ashrrev_i32_e32 v67, 31, v66
	v_add_u32_e32 v70, s7, v51
	v_add_u32_e32 v72, s7, v50
	v_ashrrev_i32_e32 v63, 31, v62
	v_lshlrev_b64 v[64:65], 12, v[64:65]
	v_lshlrev_b64 v[66:67], 12, v[66:67]
	v_lshlrev_b64 v[68:69], 12, v[68:69]
	v_ashrrev_i32_e32 v73, 31, v72
	v_ashrrev_i32_e32 v71, 31, v70
	v_lshlrev_b64 v[62:63], 12, v[62:63]
	v_lshl_add_u64 v[64:65], v[60:61], 0, v[64:65]
	v_lshl_add_u64 v[68:69], v[60:61], 0, v[68:69]
	v_lshl_add_u64 v[66:67], v[60:61], 0, v[66:67]
	v_lshlrev_b64 v[70:71], 12, v[70:71]
	v_lshlrev_b64 v[72:73], 12, v[72:73]
	v_lshl_add_u64 v[62:63], v[60:61], 0, v[62:63]
	v_lshl_add_u64 v[72:73], v[60:61], 0, v[72:73]
	v_lshl_add_u64 v[70:71], v[60:61], 0, v[70:71]
	global_load_dword v75, v[64:65], off nt
	global_load_dword v77, v[62:63], off nt
	s_nop 0
	global_load_dword v68, v[68:69], off nt
	s_nop 0
	global_load_dword v66, v[66:67], off nt
	s_nop 0
	global_load_dword v67, v[72:73], off nt
	global_load_dword v69, v[70:71], off nt
	v_add_u32_e32 v64, s7, v52
	v_add_u32_e32 v62, s7, v53
	v_ashrrev_i32_e32 v65, 31, v64
	v_ashrrev_i32_e32 v63, 31, v62
	v_lshlrev_b64 v[64:65], 12, v[64:65]
	v_lshlrev_b64 v[62:63], 12, v[62:63]
	v_lshl_add_u64 v[64:65], v[60:61], 0, v[64:65]
	global_load_dword v64, v[64:65], off nt
	v_lshl_add_u64 v[60:61], v[60:61], 0, v[62:63]
	global_load_dword v60, v[60:61], off nt
	v_add_u32_e32 v61, v98, v104
	s_waitcnt vmcnt(31)
; #define LAS __attribute__((address_space(3)))
; __device__ __forceinline__ unsigned cvt_pk(float lo, float hi) { unsigned r; asm("v_cvt_pk_bf16_f32 %0, %1, %2" : "=v"(r) : "v"(lo), "v"(hi)); return r; }
; template <bool GU>
; __device__ __forceinline__ void transpose_item(const float* W, int K, int N, bf16* WT, const float* gs, LAS float* scr, int item, int lane) {
;     ...
;     for (int i = 0; i < 32; ++i) { const int kk = 2 * i + (lane >> 5); float w = W[(size_t)(k0 + kk) * N + n0 + (lane & 31)]; if (gs) w *= gs[k0 + kk]; scr[kk * 33 + (lane & 31)] = w; }
;     asm volatile("s_waitcnt lgkmcnt(0)" ::: "memory");
;     int d0 = n0;
;     if (GU) { const int f = (n0 < FF) ? n0 : n0 - FF; d0 = 256 * (f >> 7) + (f & 127) + ((n0 < FF) ? 0 : 128); }
;     const int c = lane & 7;
; #pragma unroll
;     for (int j = 0; j < 4; ++j) { const int n = (lane >> 3) + 8 * j; const LAS float* s = scr + (8 * c) * 33 + n;
;         v4u o; o.x = cvt_pk(s[0 * 33], s[1 * 33]); o.y = cvt_pk(s[2 * 33], s[3 * 33]); o.z = cvt_pk(s[4 * 33], s[5 * 33]); o.w = cvt_pk(s[6 * 33], s[7 * 33]);
;         *(v4u*)(WT + (size_t)(d0 + n) * K + k0 + 8 * c) = o; }
;     asm volatile("s_waitcnt lgkmcnt(0)" ::: "memory");
	ds_write_b32 v61, v78
	v_add_u32_e32 v61, v98, v105
	s_waitcnt vmcnt(30)
	ds_write_b32 v61, v79
	v_add_u32_e32 v61, v98, v106
	s_waitcnt vmcnt(29)
	ds_write_b32 v61, v80
	v_add_u32_e32 v61, v98, v107
	s_waitcnt vmcnt(28)
	ds_write_b32 v61, v81
	v_add_u32_e32 v61, v98, v108
	s_waitcnt vmcnt(27)
	ds_write_b32 v61, v82
	v_add_u32_e32 v61, v98, v109
	s_waitcnt vmcnt(26)
	ds_write_b32 v61, v83
	v_add_u32_e32 v61, v98, v110
	s_waitcnt vmcnt(25)
	ds_write_b32 v61, v84
	v_add_u32_e32 v61, v98, v111
	s_waitcnt vmcnt(24)
	ds_write_b32 v61, v85
	v_add_u32_e32 v61, v98, v112
	s_waitcnt vmcnt(23)
	ds_write_b32 v61, v86
	v_add_u32_e32 v61, v98, v113
	s_waitcnt vmcnt(22)
	ds_write_b32 v61, v87
	v_add_u32_e32 v61, v98, v114
	s_waitcnt vmcnt(21)
	ds_write_b32 v61, v88
	v_add_u32_e32 v61, v98, v115
	s_waitcnt vmcnt(20)
	ds_write_b32 v61, v89
	v_add_u32_e32 v61, v98, v116
	s_waitcnt vmcnt(19)
	ds_write_b32 v61, v90
	v_add_u32_e32 v61, v98, v117
	s_waitcnt vmcnt(18)
	ds_write_b32 v61, v91
	v_add_u32_e32 v61, v98, v118
	s_waitcnt vmcnt(17)
	ds_write_b32 v61, v92
	v_add_u32_e32 v61, v98, v119
	s_waitcnt vmcnt(16)
	ds_write_b32 v61, v93
	v_add_u32_e32 v61, v98, v120
	v_add_u32_e32 v82, s6, v99
	s_lshl_b32 s10, s7, 1
	v_ashrrev_i32_e32 v83, 31, v82
	v_lshl_add_u64 v[80:81], v[2:3], 0, s[10:11]
	s_waitcnt vmcnt(15)
	ds_write_b32 v61, v94
	v_add_u32_e32 v61, v98, v121
	s_waitcnt vmcnt(14)
	ds_write_b32 v61, v95
	v_add_u32_e32 v61, v98, v122
	s_waitcnt vmcnt(13)
	ds_write_b32 v61, v96
	v_add_u32_e32 v61, v98, v123
	s_waitcnt vmcnt(12)
	ds_write_b32 v61, v97
	v_add_u32_e32 v61, v98, v124
	s_waitcnt vmcnt(11)
	ds_write_b32 v61, v137
	v_add_u32_e32 v61, v98, v125
	s_waitcnt vmcnt(10)
	ds_write_b32 v61, v138
	v_add_u32_e32 v61, v98, v126
	s_waitcnt vmcnt(9)
	ds_write_b32 v61, v76
	v_add_u32_e32 v61, v98, v127
	s_waitcnt vmcnt(8)
	ds_write_b32 v61, v74
	v_add_u32_e32 v61, v98, v128
	v_lshlrev_b64 v[82:83], 11, v[82:83]
	v_lshl_add_u64 v[82:83], v[80:81], 0, v[82:83]
	s_waitcnt vmcnt(7)
	ds_write_b32 v61, v75
	v_add_u32_e32 v61, v98, v129
	s_waitcnt vmcnt(6)
	ds_write_b32 v61, v77
	v_add_u32_e32 v61, v98, v130
	s_waitcnt vmcnt(5)
	ds_write_b32 v61, v68
	v_add_u32_e32 v61, v98, v131
	s_waitcnt vmcnt(4)
	ds_write_b32 v61, v66
	v_add_u32_e32 v61, v98, v132
	s_waitcnt vmcnt(3)
	ds_write_b32 v61, v67
	v_add_u32_e32 v61, v98, v133
	s_waitcnt vmcnt(2)
	ds_write_b32 v61, v69
	v_add_u32_e32 v61, v98, v134
	s_waitcnt vmcnt(1)
	ds_write_b32 v61, v64
	v_add_u32_e32 v61, v98, v135
	s_waitcnt vmcnt(0)
	ds_write_b32 v61, v60
	s_waitcnt lgkmcnt(0)
	ds_read2_b32 v[64:65], v100 offset0:33 offset1:41
	ds_read2_b32 v[66:67], v100 offset1:8
	ds_read2_b32 v[68:69], v100 offset0:66 offset1:74
	ds_read2_b32 v[70:71], v100 offset0:99 offset1:107
	ds_read2_b32 v[72:73], v100 offset0:132 offset1:140
	ds_read2_b32 v[74:75], v100 offset0:165 offset1:173
	ds_read2_b32 v[76:77], v100 offset0:198 offset1:206
	ds_read2_b32 v[78:79], v100 offset0:231 offset1:239
	s_waitcnt lgkmcnt(6)
	v_cvt_pk_bf16_f32 v60, v66, v64
	v_add_u32_e32 v64, s6, v101
	s_waitcnt lgkmcnt(4)
	v_cvt_pk_bf16_f32 v61, v68, v70
	s_waitcnt lgkmcnt(2)
	v_cvt_pk_bf16_f32 v62, v72, v74
	s_waitcnt lgkmcnt(0)
	v_cvt_pk_bf16_f32 v63, v76, v78
	global_store_dwordx4 v[82:83], v[60:63], off sc1
	s_nop 1
	v_cvt_pk_bf16_f32 v60, v67, v65
	v_ashrrev_i32_e32 v65, 31, v64
	v_lshlrev_b64 v[64:65], 11, v[64:65]
	v_cvt_pk_bf16_f32 v61, v69, v71
	v_cvt_pk_bf16_f32 v62, v73, v75
	v_cvt_pk_bf16_f32 v63, v77, v79
	v_lshl_add_u64 v[64:65], v[80:81], 0, v[64:65]
	ds_read2_b32 v[66:67], v100 offset0:16 offset1:24
	ds_read2_b32 v[68:69], v100 offset0:49 offset1:57
	ds_read2_b32 v[70:71], v100 offset0:82 offset1:90
	ds_read2_b32 v[72:73], v100 offset0:115 offset1:123
	ds_read2_b32 v[74:75], v100 offset0:148 offset1:156
	ds_read2_b32 v[76:77], v100 offset0:181 offset1:189
	ds_read2_b32 v[78:79], v100 offset0:214 offset1:222
	ds_read2_b32 v[82:83], v100 offset0:247 offset1:255
	global_store_dwordx4 v[64:65], v[60:63], off sc1
	v_add_u32_e32 v64, s6, v102
	v_ashrrev_i32_e32 v65, 31, v64
	v_lshlrev_b64 v[64:65], 11, v[64:65]
	v_lshl_add_u64 v[64:65], v[80:81], 0, v[64:65]
	s_waitcnt lgkmcnt(6)
	v_cvt_pk_bf16_f32 v60, v66, v68
	s_waitcnt lgkmcnt(4)
	v_cvt_pk_bf16_f32 v61, v70, v72
	s_waitcnt lgkmcnt(2)
	v_cvt_pk_bf16_f32 v62, v74, v76
	s_waitcnt lgkmcnt(0)
	v_cvt_pk_bf16_f32 v63, v78, v82
	global_store_dwordx4 v[64:65], v[60:63], off sc1
	v_add_u32_e32 v64, s6, v103
	v_ashrrev_i32_e32 v65, 31, v64
	v_lshlrev_b64 v[64:65], 11, v[64:65]
	v_lshl_add_u64 v[64:65], v[80:81], 0, v[64:65]
	v_cvt_pk_bf16_f32 v60, v67, v69
	v_cvt_pk_bf16_f32 v61, v71, v73
	v_cvt_pk_bf16_f32 v62, v75, v77
	v_cvt_pk_bf16_f32 v63, v79, v83
	global_store_dwordx4 v[64:65], v[60:63], off sc1
	s_waitcnt lgkmcnt(0)
	s_mov_b64 s[6:7], 0
; template <bool GU>
; __device__ __forceinline__ void transpose_item(const float* W, int K, int N, bf16* WT, const float* gs, LAS float* scr, int item, int lane) {
;     const int nblk = N / 32, kb = item / nblk, nb = item % nblk, k0 = 64 * kb, n0 = 32 * nb;
; #pragma unroll 16
;     for (int i = 0; i < 32; ++i) { const int kk = 2 * i + (lane >> 5); float w = W[(size_t)(k0 + kk) * N + n0 + (lane & 31)]; if (gs) w *= gs[k0 + kk]; scr[kk * 33 + (lane & 31)] = w; }
; __device__ __forceinline__ void conv_weights(LAS unsigned char* lds, unsigned char* ws, const PIn& I, const int l, const int wave, const int lane, const int gw, const int NGW, const int r_lo, const int r_hi) {
;     ...
;         if (r < I_PP) { transpose_item<false>(I.w_pp + (size_t)l * DPLE * DM, DPLE, DM, (bf16*)(wb + W_PP), nullptr, scr, r, lane); continue; } r -= I_PP;
.LBB0_491:
	s_andn2_b64 vcc, exec, s[6:7]
	s_cbranch_vccnz .LBB0_493
	s_and_b32 s7, s9, 0x1c0
	s_lshl_b32 s6, s1, 5
	s_and_b32 s6, s6, 0x3e0
	v_add_u32_e32 v64, s7, v0
	s_lshl_b32 s10, s6, 2
	v_add_u32_e32 v62, s7, v1
	v_ashrrev_i32_e32 v65, 31, v64
	v_add_u32_e32 v66, s7, v25
	v_add_u32_e32 v68, s7, v24
	v_add_u32_e32 v70, s7, v27
	v_add_u32_e32 v72, s7, v26
	v_add_u32_e32 v74, s7, v29
	v_add_u32_e32 v76, s7, v28
	v_lshl_add_u64 v[60:61], v[16:17], 0, s[10:11]
	v_ashrrev_i32_e32 v63, 31, v62
	v_lshlrev_b64 v[64:65], 12, v[64:65]
	v_ashrrev_i32_e32 v69, 31, v68
	v_ashrrev_i32_e32 v67, 31, v66
	v_ashrrev_i32_e32 v73, 31, v72
	v_ashrrev_i32_e32 v71, 31, v70
	v_ashrrev_i32_e32 v77, 31, v76
	v_ashrrev_i32_e32 v75, 31, v74
	v_lshlrev_b64 v[62:63], 12, v[62:63]
	v_lshl_add_u64 v[64:65], v[60:61], 0, v[64:65]
	v_lshlrev_b64 v[66:67], 12, v[66:67]
	v_lshlrev_b64 v[68:69], 12, v[68:69]
	v_lshlrev_b64 v[70:71], 12, v[70:71]
	v_lshlrev_b64 v[72:73], 12, v[72:73]
	v_lshlrev_b64 v[74:75], 12, v[74:75]
	v_lshlrev_b64 v[76:77], 12, v[76:77]
	v_lshl_add_u64 v[62:63], v[60:61], 0, v[62:63]
	v_lshl_add_u64 v[68:69], v[60:61], 0, v[68:69]
	v_lshl_add_u64 v[66:67], v[60:61], 0, v[66:67]
	v_lshl_add_u64 v[72:73], v[60:61], 0, v[72:73]
	v_lshl_add_u64 v[70:71], v[60:61], 0, v[70:71]
	v_lshl_add_u64 v[76:77], v[60:61], 0, v[76:77]
	v_lshl_add_u64 v[74:75], v[60:61], 0, v[74:75]
	global_load_dword v78, v[64:65], off nt
	global_load_dword v79, v[62:63], off nt
	global_load_dword v80, v[68:69], off nt
	global_load_dword v81, v[66:67], off nt
	global_load_dword v82, v[72:73], off nt
	global_load_dword v83, v[70:71], off nt
	global_load_dword v84, v[76:77], off nt
	global_load_dword v85, v[74:75], off nt
	v_add_u32_e32 v64, s7, v30
	v_add_u32_e32 v62, s7, v31
	v_ashrrev_i32_e32 v65, 31, v64
	v_add_u32_e32 v66, s7, v33
	v_add_u32_e32 v68, s7, v32
	v_add_u32_e32 v70, s7, v35
	v_add_u32_e32 v72, s7, v34
	v_add_u32_e32 v74, s7, v37
	v_add_u32_e32 v76, s7, v36
	v_ashrrev_i32_e32 v63, 31, v62
	v_lshlrev_b64 v[64:65], 12, v[64:65]
	v_ashrrev_i32_e32 v69, 31, v68
	v_ashrrev_i32_e32 v67, 31, v66
	v_ashrrev_i32_e32 v73, 31, v72
	v_ashrrev_i32_e32 v71, 31, v70
	v_ashrrev_i32_e32 v77, 31, v76
	v_ashrrev_i32_e32 v75, 31, v74
	v_lshlrev_b64 v[62:63], 12, v[62:63]
	v_lshl_add_u64 v[64:65], v[60:61], 0, v[64:65]
	v_lshlrev_b64 v[66:67], 12, v[66:67]
	v_lshlrev_b64 v[68:69], 12, v[68:69]
	v_lshlrev_b64 v[70:71], 12, v[70:71]
	v_lshlrev_b64 v[72:73], 12, v[72:73]
	v_lshlrev_b64 v[74:75], 12, v[74:75]
	v_lshlrev_b64 v[76:77], 12, v[76:77]
	v_lshl_add_u64 v[62:63], v[60:61], 0, v[62:63]
	v_lshl_add_u64 v[68:69], v[60:61], 0, v[68:69]
	v_lshl_add_u64 v[66:67], v[60:61], 0, v[66:67]
	v_lshl_add_u64 v[72:73], v[60:61], 0, v[72:73]
	v_lshl_add_u64 v[70:71], v[60:61], 0, v[70:71]
	v_lshl_add_u64 v[76:77], v[60:61], 0, v[76:77]
	v_lshl_add_u64 v[74:75], v[60:61], 0, v[74:75]
	global_load_dword v86, v[64:65], off nt
	global_load_dword v87, v[62:63], off nt
	global_load_dword v88, v[68:69], off nt
	global_load_dword v89, v[66:67], off nt
	global_load_dword v90, v[72:73], off nt
	global_load_dword v91, v[70:71], off nt
	global_load_dword v92, v[76:77], off nt
	global_load_dword v93, v[74:75], off nt
	v_add_u32_e32 v64, s7, v38
	v_add_u32_e32 v66, s7, v41
	v_add_u32_e32 v68, s7, v40
	v_add_u32_e32 v74, s7, v45
	v_add_u32_e32 v76, s7, v44
	v_add_u32_e32 v62, s7, v39
	v_ashrrev_i32_e32 v65, 31, v64
	v_ashrrev_i32_e32 v69, 31, v68
	v_ashrrev_i32_e32 v67, 31, v66
	v_add_u32_e32 v70, s7, v43
	v_add_u32_e32 v72, s7, v42
	v_ashrrev_i32_e32 v77, 31, v76
	v_ashrrev_i32_e32 v75, 31, v74
	v_ashrrev_i32_e32 v63, 31, v62
	v_lshlrev_b64 v[64:65], 12, v[64:65]
	v_lshlrev_b64 v[66:67], 12, v[66:67]
	v_lshlrev_b64 v[68:69], 12, v[68:69]
	v_ashrrev_i32_e32 v73, 31, v72
	v_ashrrev_i32_e32 v71, 31, v70
	v_lshlrev_b64 v[74:75], 12, v[74:75]
	v_lshlrev_b64 v[76:77], 12, v[76:77]
	v_lshlrev_b64 v[62:63], 12, v[62:63]
	v_lshl_add_u64 v[64:65], v[60:61], 0, v[64:65]
	v_lshl_add_u64 v[68:69], v[60:61], 0, v[68:69]
	v_lshl_add_u64 v[66:67], v[60:61], 0, v[66:67]
	v_lshlrev_b64 v[70:71], 12, v[70:71]
	v_lshlrev_b64 v[72:73], 12, v[72:73]
	v_lshl_add_u64 v[76:77], v[60:61], 0, v[76:77]
	v_lshl_add_u64 v[74:75], v[60:61], 0, v[74:75]
	v_lshl_add_u64 v[62:63], v[60:61], 0, v[62:63]
	v_lshl_add_u64 v[72:73], v[60:61], 0, v[72:73]
	v_lshl_add_u64 v[70:71], v[60:61], 0, v[70:71]
	global_load_dword v94, v[64:65], off nt
	global_load_dword v95, v[62:63], off nt
	global_load_dword v96, v[68:69], off nt
	global_load_dword v97, v[66:67], off nt
	global_load_dword v137, v[72:73], off nt
	global_load_dword v138, v[70:71], off nt
	s_nop 0
	global_load_dword v76, v[76:77], off nt
	s_nop 0
	global_load_dword v74, v[74:75], off nt
	v_add_u32_e32 v64, s7, v46
	v_add_u32_e32 v66, s7, v49
	v_add_u32_e32 v68, s7, v48
	v_add_u32_e32 v62, s7, v47
	v_ashrrev_i32_e32 v65, 31, v64
	v_ashrrev_i32_e32 v69, 31, v68
	v_ashrrev_i32_e32 v67, 31, v66
	v_add_u32_e32 v70, s7, v51
	v_add_u32_e32 v72, s7, v50
	v_ashrrev_i32_e32 v63, 31, v62
	v_lshlrev_b64 v[64:65], 12, v[64:65]
	v_lshlrev_b64 v[66:67], 12, v[66:67]
	v_lshlrev_b64 v[68:69], 12, v[68:69]
	v_ashrrev_i32_e32 v73, 31, v72
	v_ashrrev_i32_e32 v71, 31, v70
	v_lshlrev_b64 v[62:63], 12, v[62:63]
	v_lshl_add_u64 v[64:65], v[60:61], 0, v[64:65]
	v_lshl_add_u64 v[68:69], v[60:61], 0, v[68:69]
	v_lshl_add_u64 v[66:67], v[60:61], 0, v[66:67]
	v_lshlrev_b64 v[70:71], 12, v[70:71]
	v_lshlrev_b64 v[72:73], 12, v[72:73]
	v_lshl_add_u64 v[62:63], v[60:61], 0, v[62:63]
	v_lshl_add_u64 v[72:73], v[60:61], 0, v[72:73]
	v_lshl_add_u64 v[70:71], v[60:61], 0, v[70:71]
	global_load_dword v75, v[64:65], off nt
	global_load_dword v77, v[62:63], off nt
	s_nop 0
	global_load_dword v68, v[68:69], off nt
	s_nop 0
	global_load_dword v66, v[66:67], off nt
	s_nop 0
	global_load_dword v67, v[72:73], off nt
	global_load_dword v69, v[70:71], off nt
	v_add_u32_e32 v64, s7, v52
	v_add_u32_e32 v62, s7, v53
	v_ashrrev_i32_e32 v65, 31, v64
	v_ashrrev_i32_e32 v63, 31, v62
	v_lshlrev_b64 v[64:65], 12, v[64:65]
	v_lshlrev_b64 v[62:63], 12, v[62:63]
	v_lshl_add_u64 v[64:65], v[60:61], 0, v[64:65]
	global_load_dword v64, v[64:65], off nt
	v_lshl_add_u64 v[60:61], v[60:61], 0, v[62:63]
	global_load_dword v60, v[60:61], off nt
	v_add_u32_e32 v61, v98, v104
	s_waitcnt vmcnt(31)
; #define LAS __attribute__((address_space(3)))
; __device__ __forceinline__ unsigned cvt_pk(float lo, float hi) { unsigned r; asm("v_cvt_pk_bf16_f32 %0, %1, %2" : "=v"(r) : "v"(lo), "v"(hi)); return r; }
; template <bool GU>
; __device__ __forceinline__ void transpose_item(const float* W, int K, int N, bf16* WT, const float* gs, LAS float* scr, int item, int lane) {
;     ...
;     for (int i = 0; i < 32; ++i) { const int kk = 2 * i + (lane >> 5); float w = W[(size_t)(k0 + kk) * N + n0 + (lane & 31)]; if (gs) w *= gs[k0 + kk]; scr[kk * 33 + (lane & 31)] = w; }
;     asm volatile("s_waitcnt lgkmcnt(0)" ::: "memory");
;     int d0 = n0;
;     if (GU) { const int f = (n0 < FF) ? n0 : n0 - FF; d0 = 256 * (f >> 7) + (f & 127) + ((n0 < FF) ? 0 : 128); }
;     const int c = lane & 7;
; #pragma unroll
;     for (int j = 0; j < 4; ++j) { const int n = (lane >> 3) + 8 * j; const LAS float* s = scr + (8 * c) * 33 + n;
;         v4u o; o.x = cvt_pk(s[0 * 33], s[1 * 33]); o.y = cvt_pk(s[2 * 33], s[3 * 33]); o.z = cvt_pk(s[4 * 33], s[5 * 33]); o.w = cvt_pk(s[6 * 33], s[7 * 33]);
;         *(v4u*)(WT + (size_t)(d0 + n) * K + k0 + 8 * c) = o; }
;     asm volatile("s_waitcnt lgkmcnt(0)" ::: "memory");
	ds_write_b32 v61, v78
	v_add_u32_e32 v61, v98, v105
	s_waitcnt vmcnt(30)
	ds_write_b32 v61, v79
	v_add_u32_e32 v61, v98, v106
	s_waitcnt vmcnt(29)
	ds_write_b32 v61, v80
	v_add_u32_e32 v61, v98, v107
	s_waitcnt vmcnt(28)
	ds_write_b32 v61, v81
	v_add_u32_e32 v61, v98, v108
	s_waitcnt vmcnt(27)
	ds_write_b32 v61, v82
	v_add_u32_e32 v61, v98, v109
	s_waitcnt vmcnt(26)
	ds_write_b32 v61, v83
	v_add_u32_e32 v61, v98, v110
	s_waitcnt vmcnt(25)
	ds_write_b32 v61, v84
	v_add_u32_e32 v61, v98, v111
	s_waitcnt vmcnt(24)
	ds_write_b32 v61, v85
	v_add_u32_e32 v61, v98, v112
	s_waitcnt vmcnt(23)
	ds_write_b32 v61, v86
	v_add_u32_e32 v61, v98, v113
	s_waitcnt vmcnt(22)
	ds_write_b32 v61, v87
	v_add_u32_e32 v61, v98, v114
	s_waitcnt vmcnt(21)
	ds_write_b32 v61, v88
	v_add_u32_e32 v61, v98, v115
	s_waitcnt vmcnt(20)
	ds_write_b32 v61, v89
	v_add_u32_e32 v61, v98, v116
	s_waitcnt vmcnt(19)
	ds_write_b32 v61, v90
	v_add_u32_e32 v61, v98, v117
	s_waitcnt vmcnt(18)
	ds_write_b32 v61, v91
	v_add_u32_e32 v61, v98, v118
	s_waitcnt vmcnt(17)
	ds_write_b32 v61, v92
	v_add_u32_e32 v61, v98, v119
	s_waitcnt vmcnt(16)
	ds_write_b32 v61, v93
	v_add_u32_e32 v61, v98, v120
	v_add_u32_e32 v82, s6, v99
	s_lshl_b32 s10, s7, 1
	v_ashrrev_i32_e32 v83, 31, v82
	v_lshl_add_u64 v[80:81], v[4:5], 0, s[10:11]
	s_waitcnt vmcnt(15)
	ds_write_b32 v61, v94
	v_add_u32_e32 v61, v98, v121
	s_waitcnt vmcnt(14)
	ds_write_b32 v61, v95
	v_add_u32_e32 v61, v98, v122
	s_waitcnt vmcnt(13)
	ds_write_b32 v61, v96
	v_add_u32_e32 v61, v98, v123
	s_waitcnt vmcnt(12)
	ds_write_b32 v61, v97
	v_add_u32_e32 v61, v98, v124
	s_waitcnt vmcnt(11)
	ds_write_b32 v61, v137
	v_add_u32_e32 v61, v98, v125
	s_waitcnt vmcnt(10)
	ds_write_b32 v61, v138
	v_add_u32_e32 v61, v98, v126
	s_waitcnt vmcnt(9)
	ds_write_b32 v61, v76
	v_add_u32_e32 v61, v98, v127
	s_waitcnt vmcnt(8)
	ds_write_b32 v61, v74
	v_add_u32_e32 v61, v98, v128
	v_lshlrev_b64 v[82:83], 9, v[82:83]
	v_lshl_add_u64 v[82:83], v[80:81], 0, v[82:83]
	s_waitcnt vmcnt(7)
	ds_write_b32 v61, v75
	v_add_u32_e32 v61, v98, v129
	s_waitcnt vmcnt(6)
	ds_write_b32 v61, v77
	v_add_u32_e32 v61, v98, v130
	s_waitcnt vmcnt(5)
	ds_write_b32 v61, v68
	v_add_u32_e32 v61, v98, v131
	s_waitcnt vmcnt(4)
	ds_write_b32 v61, v66
	v_add_u32_e32 v61, v98, v132
	s_waitcnt vmcnt(3)
	ds_write_b32 v61, v67
	v_add_u32_e32 v61, v98, v133
	s_waitcnt vmcnt(2)
	ds_write_b32 v61, v69
	v_add_u32_e32 v61, v98, v134
	s_waitcnt vmcnt(1)
	ds_write_b32 v61, v64
	v_add_u32_e32 v61, v98, v135
	s_waitcnt vmcnt(0)
	ds_write_b32 v61, v60
	s_waitcnt lgkmcnt(0)
	ds_read2_b32 v[64:65], v100 offset0:33 offset1:41
	ds_read2_b32 v[66:67], v100 offset1:8
	ds_read2_b32 v[68:69], v100 offset0:66 offset1:74
	ds_read2_b32 v[70:71], v100 offset0:99 offset1:107
	ds_read2_b32 v[72:73], v100 offset0:132 offset1:140
	ds_read2_b32 v[74:75], v100 offset0:165 offset1:173
	ds_read2_b32 v[76:77], v100 offset0:198 offset1:206
	ds_read2_b32 v[78:79], v100 offset0:231 offset1:239
	s_waitcnt lgkmcnt(6)
	v_cvt_pk_bf16_f32 v60, v66, v64
	v_add_u32_e32 v64, s6, v101
	s_waitcnt lgkmcnt(4)
	v_cvt_pk_bf16_f32 v61, v68, v70
	s_waitcnt lgkmcnt(2)
	v_cvt_pk_bf16_f32 v62, v72, v74
	s_waitcnt lgkmcnt(0)
	v_cvt_pk_bf16_f32 v63, v76, v78
	global_store_dwordx4 v[82:83], v[60:63], off sc1
	s_nop 1
	v_cvt_pk_bf16_f32 v60, v67, v65
	v_ashrrev_i32_e32 v65, 31, v64
	v_lshlrev_b64 v[64:65], 9, v[64:65]
	v_cvt_pk_bf16_f32 v61, v69, v71
	v_cvt_pk_bf16_f32 v62, v73, v75
	v_cvt_pk_bf16_f32 v63, v77, v79
	v_lshl_add_u64 v[64:65], v[80:81], 0, v[64:65]
	ds_read2_b32 v[66:67], v100 offset0:16 offset1:24
	ds_read2_b32 v[68:69], v100 offset0:49 offset1:57
	ds_read2_b32 v[70:71], v100 offset0:82 offset1:90
	ds_read2_b32 v[72:73], v100 offset0:115 offset1:123
	ds_read2_b32 v[74:75], v100 offset0:148 offset1:156
	ds_read2_b32 v[76:77], v100 offset0:181 offset1:189
	ds_read2_b32 v[78:79], v100 offset0:214 offset1:222
	ds_read2_b32 v[82:83], v100 offset0:247 offset1:255
	global_store_dwordx4 v[64:65], v[60:63], off sc1
	v_add_u32_e32 v64, s6, v102
	v_ashrrev_i32_e32 v65, 31, v64
	v_lshlrev_b64 v[64:65], 9, v[64:65]
	v_lshl_add_u64 v[64:65], v[80:81], 0, v[64:65]
	s_waitcnt lgkmcnt(6)
	v_cvt_pk_bf16_f32 v60, v66, v68
	s_waitcnt lgkmcnt(4)
	v_cvt_pk_bf16_f32 v61, v70, v72
	s_waitcnt lgkmcnt(2)
	v_cvt_pk_bf16_f32 v62, v74, v76
	s_waitcnt lgkmcnt(0)
	v_cvt_pk_bf16_f32 v63, v78, v82
	global_store_dwordx4 v[64:65], v[60:63], off sc1
	v_add_u32_e32 v64, s6, v103
	v_ashrrev_i32_e32 v65, 31, v64
	v_lshlrev_b64 v[64:65], 9, v[64:65]
	v_lshl_add_u64 v[64:65], v[80:81], 0, v[64:65]
	v_cvt_pk_bf16_f32 v60, v67, v69
	v_cvt_pk_bf16_f32 v61, v71, v73
	v_cvt_pk_bf16_f32 v62, v75, v77
	v_cvt_pk_bf16_f32 v63, v79, v83
	global_store_dwordx4 v[64:65], v[60:63], off sc1
	s_waitcnt lgkmcnt(0)

; template <bool GU>
; __device__ __forceinline__ void transpose_item(const float* W, int K, int N, bf16* WT, const float* gs, LAS float* scr, int item, int lane) {
;     const int nblk = N / 32, kb = item / nblk, nb = item % nblk, k0 = 64 * kb, n0 = 32 * nb;
; #pragma unroll 16
;     for (int i = 0; i < 32; ++i) { const int kk = 2 * i + (lane >> 5); float w = W[(size_t)(k0 + kk) * N + n0 + (lane & 31)]; if (gs) w *= gs[k0 + kk]; scr[kk * 33 + (lane & 31)] = w; }
; __device__ __forceinline__ void conv_weights(LAS unsigned char* lds, unsigned char* ws, const PIn& I, const int l, const int wave, const int lane, const int gw, const int NGW, const int r_lo, const int r_hi) {
;     ...
;         if (r < I_D) { transpose_item<false>(I.w_d + (size_t)l * FF * DM, FF, DM, (bf16*)(wb + W_D), nullptr, scr, r, lane); continue; } r -= I_D;
.LBB0_494:
	s_andn2_b64 vcc, exec, s[6:7]
	s_cbranch_vccnz .LBB0_496
	s_lshl_b32 s6, s1, 1
	s_add_i32 s6, s6, 0x1dd00
	s_and_b32 s7, s6, 0x1ffc0
	s_lshl_b32 s6, s1, 5
	s_and_b32 s6, s6, 0x3e0
	v_add_u32_e32 v64, s7, v0
	s_lshl_b32 s10, s6, 2
	v_add_u32_e32 v62, s7, v1
	v_ashrrev_i32_e32 v65, 31, v64
	v_add_u32_e32 v66, s7, v25
	v_add_u32_e32 v68, s7, v24
	v_add_u32_e32 v70, s7, v27
	v_add_u32_e32 v72, s7, v26
	v_add_u32_e32 v74, s7, v29
	v_add_u32_e32 v76, s7, v28
	v_lshl_add_u64 v[60:61], v[18:19], 0, s[10:11]
	v_ashrrev_i32_e32 v63, 31, v62
	v_lshlrev_b64 v[64:65], 12, v[64:65]
	v_ashrrev_i32_e32 v69, 31, v68
	v_ashrrev_i32_e32 v67, 31, v66
	v_ashrrev_i32_e32 v73, 31, v72
	v_ashrrev_i32_e32 v71, 31, v70
	v_ashrrev_i32_e32 v77, 31, v76
	v_ashrrev_i32_e32 v75, 31, v74
	v_lshlrev_b64 v[62:63], 12, v[62:63]
	v_lshl_add_u64 v[64:65], v[60:61], 0, v[64:65]
	v_lshlrev_b64 v[66:67], 12, v[66:67]
	v_lshlrev_b64 v[68:69], 12, v[68:69]
	v_lshlrev_b64 v[70:71], 12, v[70:71]
	v_lshlrev_b64 v[72:73], 12, v[72:73]
	v_lshlrev_b64 v[74:75], 12, v[74:75]
	v_lshlrev_b64 v[76:77], 12, v[76:77]
	v_lshl_add_u64 v[62:63], v[60:61], 0, v[62:63]
	v_lshl_add_u64 v[68:69], v[60:61], 0, v[68:69]
	v_lshl_add_u64 v[66:67], v[60:61], 0, v[66:67]
	v_lshl_add_u64 v[72:73], v[60:61], 0, v[72:73]
	v_lshl_add_u64 v[70:71], v[60:61], 0, v[70:71]
	v_lshl_add_u64 v[76:77], v[60:61], 0, v[76:77]
	v_lshl_add_u64 v[74:75], v[60:61], 0, v[74:75]
	global_load_dword v78, v[64:65], off nt
	global_load_dword v79, v[62:63], off nt
	global_load_dword v80, v[68:69], off nt
	global_load_dword v81, v[66:67], off nt
	global_load_dword v82, v[72:73], off nt
	global_load_dword v83, v[70:71], off nt
	global_load_dword v84, v[76:77], off nt
	global_load_dword v85, v[74:75], off nt
	v_add_u32_e32 v64, s7, v30
	v_add_u32_e32 v62, s7, v31
	v_ashrrev_i32_e32 v65, 31, v64
	v_add_u32_e32 v66, s7, v33
	v_add_u32_e32 v68, s7, v32
	v_add_u32_e32 v70, s7, v35
	v_add_u32_e32 v72, s7, v34
	v_add_u32_e32 v74, s7, v37
	v_add_u32_e32 v76, s7, v36
	v_ashrrev_i32_e32 v63, 31, v62
	v_lshlrev_b64 v[64:65], 12, v[64:65]
	v_ashrrev_i32_e32 v69, 31, v68
	v_ashrrev_i32_e32 v67, 31, v66
	v_ashrrev_i32_e32 v73, 31, v72
	v_ashrrev_i32_e32 v71, 31, v70
	v_ashrrev_i32_e32 v77, 31, v76
	v_ashrrev_i32_e32 v75, 31, v74
	v_lshlrev_b64 v[62:63], 12, v[62:63]
	v_lshl_add_u64 v[64:65], v[60:61], 0, v[64:65]
	v_lshlrev_b64 v[66:67], 12, v[66:67]
	v_lshlrev_b64 v[68:69], 12, v[68:69]
	v_lshlrev_b64 v[70:71], 12, v[70:71]
	v_lshlrev_b64 v[72:73], 12, v[72:73]
	v_lshlrev_b64 v[74:75], 12, v[74:75]
	v_lshlrev_b64 v[76:77], 12, v[76:77]
	v_lshl_add_u64 v[62:63], v[60:61], 0, v[62:63]
	v_lshl_add_u64 v[68:69], v[60:61], 0, v[68:69]
	v_lshl_add_u64 v[66:67], v[60:61], 0, v[66:67]
	v_lshl_add_u64 v[72:73], v[60:61], 0, v[72:73]
	v_lshl_add_u64 v[70:71], v[60:61], 0, v[70:71]
	v_lshl_add_u64 v[76:77], v[60:61], 0, v[76:77]
	v_lshl_add_u64 v[74:75], v[60:61], 0, v[74:75]
	global_load_dword v86, v[64:65], off nt
	global_load_dword v87, v[62:63], off nt
	global_load_dword v88, v[68:69], off nt
	global_load_dword v89, v[66:67], off nt
	global_load_dword v90, v[72:73], off nt
	global_load_dword v91, v[70:71], off nt
	global_load_dword v92, v[76:77], off nt
	global_load_dword v93, v[74:75], off nt
	v_add_u32_e32 v64, s7, v38
	v_add_u32_e32 v66, s7, v41
	v_add_u32_e32 v68, s7, v40
	v_add_u32_e32 v74, s7, v45
	v_add_u32_e32 v76, s7, v44
	v_add_u32_e32 v62, s7, v39
	v_ashrrev_i32_e32 v65, 31, v64
	v_ashrrev_i32_e32 v69, 31, v68
	v_ashrrev_i32_e32 v67, 31, v66
	v_add_u32_e32 v70, s7, v43
	v_add_u32_e32 v72, s7, v42
	v_ashrrev_i32_e32 v77, 31, v76
	v_ashrrev_i32_e32 v75, 31, v74
	v_ashrrev_i32_e32 v63, 31, v62
	v_lshlrev_b64 v[64:65], 12, v[64:65]
	v_lshlrev_b64 v[66:67], 12, v[66:67]
	v_lshlrev_b64 v[68:69], 12, v[68:69]
	v_ashrrev_i32_e32 v73, 31, v72
	v_ashrrev_i32_e32 v71, 31, v70
	v_lshlrev_b64 v[74:75], 12, v[74:75]
	v_lshlrev_b64 v[76:77], 12, v[76:77]
	v_lshlrev_b64 v[62:63], 12, v[62:63]
	v_lshl_add_u64 v[64:65], v[60:61], 0, v[64:65]
	v_lshl_add_u64 v[68:69], v[60:61], 0, v[68:69]
	v_lshl_add_u64 v[66:67], v[60:61], 0, v[66:67]
	v_lshlrev_b64 v[70:71], 12, v[70:71]
	v_lshlrev_b64 v[72:73], 12, v[72:73]
	v_lshl_add_u64 v[76:77], v[60:61], 0, v[76:77]
	v_lshl_add_u64 v[74:75], v[60:61], 0, v[74:75]
	v_lshl_add_u64 v[62:63], v[60:61], 0, v[62:63]
	v_lshl_add_u64 v[72:73], v[60:61], 0, v[72:73]
	v_lshl_add_u64 v[70:71], v[60:61], 0, v[70:71]
	global_load_dword v94, v[64:65], off nt
	global_load_dword v95, v[62:63], off nt
	global_load_dword v96, v[68:69], off nt
	global_load_dword v97, v[66:67], off nt
	global_load_dword v137, v[72:73], off nt
	global_load_dword v138, v[70:71], off nt
	s_nop 0
	global_load_dword v76, v[76:77], off nt
	s_nop 0
	global_load_dword v74, v[74:75], off nt
	v_add_u32_e32 v64, s7, v46
	v_add_u32_e32 v66, s7, v49
	v_add_u32_e32 v68, s7, v48
	v_add_u32_e32 v62, s7, v47
	v_ashrrev_i32_e32 v65, 31, v64
	v_ashrrev_i32_e32 v69, 31, v68
	v_ashrrev_i32_e32 v67, 31, v66
	v_add_u32_e32 v70, s7, v51
	v_add_u32_e32 v72, s7, v50
	v_ashrrev_i32_e32 v63, 31, v62
	v_lshlrev_b64 v[64:65], 12, v[64:65]
	v_lshlrev_b64 v[66:67], 12, v[66:67]
	v_lshlrev_b64 v[68:69], 12, v[68:69]
	v_ashrrev_i32_e32 v73, 31, v72
	v_ashrrev_i32_e32 v71, 31, v70
	v_lshlrev_b64 v[62:63], 12, v[62:63]
	v_lshl_add_u64 v[64:65], v[60:61], 0, v[64:65]
	v_lshl_add_u64 v[68:69], v[60:61], 0, v[68:69]
	v_lshl_add_u64 v[66:67], v[60:61], 0, v[66:67]
	v_lshlrev_b64 v[70:71], 12, v[70:71]
	v_lshlrev_b64 v[72:73], 12, v[72:73]
	v_lshl_add_u64 v[62:63], v[60:61], 0, v[62:63]
	v_lshl_add_u64 v[72:73], v[60:61], 0, v[72:73]
	v_lshl_add_u64 v[70:71], v[60:61], 0, v[70:71]
	global_load_dword v75, v[64:65], off nt
	global_load_dword v77, v[62:63], off nt
	s_nop 0
	global_load_dword v68, v[68:69], off nt
	s_nop 0
	global_load_dword v66, v[66:67], off nt
	s_nop 0
	global_load_dword v67, v[72:73], off nt
	global_load_dword v69, v[70:71], off nt
	v_add_u32_e32 v64, s7, v52
	v_add_u32_e32 v62, s7, v53
	v_ashrrev_i32_e32 v65, 31, v64
	v_ashrrev_i32_e32 v63, 31, v62
	v_lshlrev_b64 v[64:65], 12, v[64:65]
	v_lshlrev_b64 v[62:63], 12, v[62:63]
	v_lshl_add_u64 v[64:65], v[60:61], 0, v[64:65]
	global_load_dword v64, v[64:65], off nt
	v_lshl_add_u64 v[60:61], v[60:61], 0, v[62:63]
	global_load_dword v60, v[60:61], off nt
	v_add_u32_e32 v61, v98, v104
	s_waitcnt vmcnt(31)
; #define LAS __attribute__((address_space(3)))
; __device__ __forceinline__ unsigned cvt_pk(float lo, float hi) { unsigned r; asm("v_cvt_pk_bf16_f32 %0, %1, %2" : "=v"(r) : "v"(lo), "v"(hi)); return r; }
; template <bool GU>
; __device__ __forceinline__ void transpose_item(const float* W, int K, int N, bf16* WT, const float* gs, LAS float* scr, int item, int lane) {
;     ...
;     for (int i = 0; i < 32; ++i) { const int kk = 2 * i + (lane >> 5); float w = W[(size_t)(k0 + kk) * N + n0 + (lane & 31)]; if (gs) w *= gs[k0 + kk]; scr[kk * 33 + (lane & 31)] = w; }
;     asm volatile("s_waitcnt lgkmcnt(0)" ::: "memory");
;     int d0 = n0;
;     if (GU) { const int f = (n0 < FF) ? n0 : n0 - FF; d0 = 256 * (f >> 7) + (f & 127) + ((n0 < FF) ? 0 : 128); }
;     const int c = lane & 7;
; #pragma unroll
;     for (int j = 0; j < 4; ++j) { const int n = (lane >> 3) + 8 * j; const LAS float* s = scr + (8 * c) * 33 + n;
;         v4u o; o.x = cvt_pk(s[0 * 33], s[1 * 33]); o.y = cvt_pk(s[2 * 33], s[3 * 33]); o.z = cvt_pk(s[4 * 33], s[5 * 33]); o.w = cvt_pk(s[6 * 33], s[7 * 33]);
;         *(v4u*)(WT + (size_t)(d0 + n) * K + k0 + 8 * c) = o; }
;     asm volatile("s_waitcnt lgkmcnt(0)" ::: "memory");
	ds_write_b32 v61, v78
	v_add_u32_e32 v61, v98, v105
	s_waitcnt vmcnt(30)
	ds_write_b32 v61, v79
	v_add_u32_e32 v61, v98, v106
	s_waitcnt vmcnt(29)
	ds_write_b32 v61, v80
	v_add_u32_e32 v61, v98, v107
	s_waitcnt vmcnt(28)
	ds_write_b32 v61, v81
	v_add_u32_e32 v61, v98, v108
	s_waitcnt vmcnt(27)
	ds_write_b32 v61, v82
	v_add_u32_e32 v61, v98, v109
	s_waitcnt vmcnt(26)
	ds_write_b32 v61, v83
	v_add_u32_e32 v61, v98, v110
	s_waitcnt vmcnt(25)
	ds_write_b32 v61, v84
	v_add_u32_e32 v61, v98, v111
	s_waitcnt vmcnt(24)
	ds_write_b32 v61, v85
	v_add_u32_e32 v61, v98, v112
	s_waitcnt vmcnt(23)
	ds_write_b32 v61, v86
	v_add_u32_e32 v61, v98, v113
	s_waitcnt vmcnt(22)
	ds_write_b32 v61, v87
	v_add_u32_e32 v61, v98, v114
	s_waitcnt vmcnt(21)
	ds_write_b32 v61, v88
	v_add_u32_e32 v61, v98, v115
	s_waitcnt vmcnt(20)
	ds_write_b32 v61, v89
	v_add_u32_e32 v61, v98, v116
	s_waitcnt vmcnt(19)
	ds_write_b32 v61, v90
	v_add_u32_e32 v61, v98, v117
	s_waitcnt vmcnt(18)
	ds_write_b32 v61, v91
	v_add_u32_e32 v61, v98, v118
	s_waitcnt vmcnt(17)
	ds_write_b32 v61, v92
	v_add_u32_e32 v61, v98, v119
	s_waitcnt vmcnt(16)
	ds_write_b32 v61, v93
	v_add_u32_e32 v61, v98, v120
	s_lshl_b32 s10, s7, 1
	v_lshl_add_u64 v[80:81], v[6:7], 0, s[10:11]
	s_waitcnt vmcnt(15)
	ds_write_b32 v61, v94
	v_add_u32_e32 v61, v98, v121
	s_waitcnt vmcnt(14)
	ds_write_b32 v61, v95
	v_add_u32_e32 v61, v98, v122
	s_waitcnt vmcnt(13)
	ds_write_b32 v61, v96
	v_add_u32_e32 v61, v98, v123
	s_waitcnt vmcnt(12)
	ds_write_b32 v61, v97
	v_add_u32_e32 v61, v98, v124
	s_waitcnt vmcnt(11)
	ds_write_b32 v61, v137
	v_add_u32_e32 v61, v98, v125
	s_waitcnt vmcnt(10)
	ds_write_b32 v61, v138
	v_add_u32_e32 v61, v98, v126
	s_waitcnt vmcnt(9)
	ds_write_b32 v61, v76
	v_add_u32_e32 v61, v98, v127
	s_waitcnt vmcnt(8)
	ds_write_b32 v61, v74
	v_add_u32_e32 v61, v98, v128
	s_waitcnt vmcnt(7)
	ds_write_b32 v61, v75
	v_add_u32_e32 v61, v98, v129
	s_waitcnt vmcnt(6)
	ds_write_b32 v61, v77
	v_add_u32_e32 v61, v98, v130
	s_waitcnt vmcnt(5)
	ds_write_b32 v61, v68
	v_add_u32_e32 v61, v98, v131
	s_waitcnt vmcnt(4)
	ds_write_b32 v61, v66
	v_add_u32_e32 v61, v98, v132
	s_waitcnt vmcnt(3)
	ds_write_b32 v61, v67
	v_add_u32_e32 v61, v98, v133
	s_waitcnt vmcnt(2)
	ds_write_b32 v61, v69
	v_add_u32_e32 v61, v98, v134
	s_waitcnt vmcnt(1)
	ds_write_b32 v61, v64
	v_add_u32_e32 v61, v98, v135
	s_waitcnt vmcnt(0)
	ds_write_b32 v61, v60
	s_waitcnt lgkmcnt(0)
	ds_read2_b32 v[64:65], v100 offset0:33 offset1:41
	ds_read2_b32 v[66:67], v100 offset1:8
	ds_read2_b32 v[68:69], v100 offset0:66 offset1:74
	ds_read2_b32 v[70:71], v100 offset0:99 offset1:107
	ds_read2_b32 v[72:73], v100 offset0:132 offset1:140
	ds_read2_b32 v[74:75], v100 offset0:165 offset1:173
	ds_read2_b32 v[76:77], v100 offset0:198 offset1:206
	ds_read2_b32 v[78:79], v100 offset0:231 offset1:239
	s_waitcnt lgkmcnt(6)
	v_cvt_pk_bf16_f32 v60, v66, v64
	v_add_u32_e32 v64, s6, v99
	v_mad_i64_i32 v[82:83], s[30:31], v64, s2, v[80:81]
	s_waitcnt lgkmcnt(4)
	v_cvt_pk_bf16_f32 v61, v68, v70
	s_waitcnt lgkmcnt(2)
	v_cvt_pk_bf16_f32 v62, v72, v74
	s_waitcnt lgkmcnt(0)
	v_cvt_pk_bf16_f32 v63, v76, v78
	global_store_dwordx4 v[82:83], v[60:63], off sc1
	v_add_u32_e32 v64, s6, v101
	s_nop 0
	v_cvt_pk_bf16_f32 v60, v67, v65
	v_cvt_pk_bf16_f32 v61, v69, v71
	v_cvt_pk_bf16_f32 v62, v73, v75
	v_cvt_pk_bf16_f32 v63, v77, v79
	ds_read2_b32 v[66:67], v100 offset0:16 offset1:24
	ds_read2_b32 v[68:69], v100 offset0:49 offset1:57
	ds_read2_b32 v[70:71], v100 offset0:82 offset1:90
	ds_read2_b32 v[72:73], v100 offset0:115 offset1:123
	ds_read2_b32 v[74:75], v100 offset0:148 offset1:156
	ds_read2_b32 v[76:77], v100 offset0:181 offset1:189
	ds_read2_b32 v[78:79], v100 offset0:214 offset1:222
	ds_read2_b32 v[82:83], v100 offset0:247 offset1:255
	v_mad_i64_i32 v[64:65], s[30:31], v64, s2, v[80:81]
	global_store_dwordx4 v[64:65], v[60:63], off sc1
	v_add_u32_e32 v64, s6, v102
	v_mad_i64_i32 v[64:65], s[30:31], v64, s2, v[80:81]
	s_waitcnt lgkmcnt(6)
	v_cvt_pk_bf16_f32 v60, v66, v68
	s_waitcnt lgkmcnt(4)
	v_cvt_pk_bf16_f32 v61, v70, v72
	s_waitcnt lgkmcnt(2)
	v_cvt_pk_bf16_f32 v62, v74, v76
	s_waitcnt lgkmcnt(0)
	v_cvt_pk_bf16_f32 v63, v78, v82
	global_store_dwordx4 v[64:65], v[60:63], off sc1
	v_add_u32_e32 v64, s6, v103
	v_mad_i64_i32 v[64:65], s[6:7], v64, s2, v[80:81]
	v_cvt_pk_bf16_f32 v60, v67, v69
	v_cvt_pk_bf16_f32 v61, v71, v73
	v_cvt_pk_bf16_f32 v62, v75, v77
	v_cvt_pk_bf16_f32 v63, v79, v83
	global_store_dwordx4 v[64:65], v[60:63], off sc1
	s_waitcnt lgkmcnt(0)

; #define LAS __attribute__((address_space(3)))
; __device__ __forceinline__ unsigned cvt_pk(float lo, float hi) { unsigned r; asm("v_cvt_pk_bf16_f32 %0, %1, %2" : "=v"(r) : "v"(lo), "v"(hi)); return r; }
; template <bool GU>
; __device__ __forceinline__ void transpose_item(const float* W, int K, int N, bf16* WT, const float* gs, LAS float* scr, int item, int lane) {
;     ...
;     int d0 = n0;
;     if (GU) { const int f = (n0 < FF) ? n0 : n0 - FF; d0 = 256 * (f >> 7) + (f & 127) + ((n0 < FF) ? 0 : 128); }
;     const int c = lane & 7;
; #pragma unroll
;     for (int j = 0; j < 4; ++j) { const int n = (lane >> 3) + 8 * j; const LAS float* s = scr + (8 * c) * 33 + n;
;         v4u o; o.x = cvt_pk(s[0 * 33], s[1 * 33]); o.y = cvt_pk(s[2 * 33], s[3 * 33]); o.z = cvt_pk(s[4 * 33], s[5 * 33]); o.w = cvt_pk(s[6 * 33], s[7 * 33]);
;         *(v4u*)(WT + (size_t)(d0 + n) * K + k0 + 8 * c) = o; }
;     asm volatile("s_waitcnt lgkmcnt(0)" ::: "memory");
.LBB0_532:
	s_and_b32 s6, 0xffff, s36
	s_and_b32 s7, 0xffff, s29
	s_add_i32 s10, s6, 0xfffff500
	s_cmpk_lt_u32 s7, 0x58
	s_cselect_b32 s6, s6, s10
	s_cselect_b32 s7, 0, 0x80
	s_lshl_b32 s10, s6, 1
	s_and_b32 s6, s6, 0x60
	s_waitcnt lgkmcnt(0)
	s_and_b32 s10, s10, 0xffffff00
	s_or_b32 s6, s6, s7
	s_or_b32 s6, s6, s10
	ds_read2_b32 v[64:65], v100 offset0:33 offset1:41
	ds_read2_b32 v[66:67], v100 offset1:8
	ds_read2_b32 v[68:69], v100 offset0:66 offset1:74
	ds_read2_b32 v[70:71], v100 offset0:99 offset1:107
	ds_read2_b32 v[72:73], v100 offset0:132 offset1:140
	ds_read2_b32 v[74:75], v100 offset0:165 offset1:173
	ds_read2_b32 v[76:77], v100 offset0:198 offset1:206
	ds_read2_b32 v[78:79], v100 offset0:231 offset1:239
	s_and_b32 s7, 0xffff, s9
	v_add_u32_e32 v82, s6, v99
	s_lshl_b32 s10, s7, 1
	v_ashrrev_i32_e32 v83, 31, v82
	v_lshl_add_u64 v[80:81], v[8:9], 0, s[10:11]
	v_lshlrev_b64 v[82:83], 11, v[82:83]
	s_waitcnt lgkmcnt(6)
	v_cvt_pk_bf16_f32 v60, v66, v64
	v_lshl_add_u64 v[82:83], v[80:81], 0, v[82:83]
	v_add_u32_e32 v64, s6, v101
	s_waitcnt lgkmcnt(4)
	v_cvt_pk_bf16_f32 v61, v68, v70
	s_waitcnt lgkmcnt(2)
	v_cvt_pk_bf16_f32 v62, v72, v74
	s_waitcnt lgkmcnt(0)
	v_cvt_pk_bf16_f32 v63, v76, v78
	global_store_dwordx4 v[82:83], v[60:63], off sc1
	s_nop 1
	v_cvt_pk_bf16_f32 v60, v67, v65
	v_ashrrev_i32_e32 v65, 31, v64
	v_lshlrev_b64 v[64:65], 11, v[64:65]
	v_cvt_pk_bf16_f32 v61, v69, v71
	v_cvt_pk_bf16_f32 v62, v73, v75
	v_cvt_pk_bf16_f32 v63, v77, v79
	v_lshl_add_u64 v[64:65], v[80:81], 0, v[64:65]
	ds_read2_b32 v[66:67], v100 offset0:16 offset1:24
	ds_read2_b32 v[68:69], v100 offset0:49 offset1:57
	ds_read2_b32 v[70:71], v100 offset0:82 offset1:90
	ds_read2_b32 v[72:73], v100 offset0:115 offset1:123
	ds_read2_b32 v[74:75], v100 offset0:148 offset1:156
	ds_read2_b32 v[76:77], v100 offset0:181 offset1:189
	ds_read2_b32 v[78:79], v100 offset0:214 offset1:222
	ds_read2_b32 v[82:83], v100 offset0:247 offset1:255
	global_store_dwordx4 v[64:65], v[60:63], off sc1
	v_add_u32_e32 v64, s6, v102
	v_ashrrev_i32_e32 v65, 31, v64
	v_lshlrev_b64 v[64:65], 11, v[64:65]
	v_lshl_add_u64 v[64:65], v[80:81], 0, v[64:65]
	s_waitcnt lgkmcnt(6)
	v_cvt_pk_bf16_f32 v60, v66, v68
	s_waitcnt lgkmcnt(4)
	v_cvt_pk_bf16_f32 v61, v70, v72
	s_waitcnt lgkmcnt(2)
	v_cvt_pk_bf16_f32 v62, v74, v76
	s_waitcnt lgkmcnt(0)
	v_cvt_pk_bf16_f32 v63, v78, v82
	global_store_dwordx4 v[64:65], v[60:63], off sc1
	v_add_u32_e32 v64, s6, v103
	v_ashrrev_i32_e32 v65, 31, v64
	v_lshlrev_b64 v[64:65], 11, v[64:65]
	v_lshl_add_u64 v[64:65], v[80:81], 0, v[64:65]
	v_cvt_pk_bf16_f32 v60, v67, v69
	v_cvt_pk_bf16_f32 v61, v71, v73
	v_cvt_pk_bf16_f32 v62, v75, v77
	v_cvt_pk_bf16_f32 v63, v79, v83
	global_store_dwordx4 v[64:65], v[60:63], off sc1
	s_waitcnt lgkmcnt(0)

; template <bool GU>
; __device__ __forceinline__ void transpose_item(const float* W, int K, int N, bf16* WT, const float* gs, LAS float* scr, int item, int lane) {
;     const int nblk = N / 32, kb = item / nblk, nb = item % nblk, k0 = 64 * kb, n0 = 32 * nb;
; #pragma unroll 16
;     for (int i = 0; i < 32; ++i) { const int kk = 2 * i + (lane >> 5); float w = W[(size_t)(k0 + kk) * N + n0 + (lane & 31)]; if (gs) w *= gs[k0 + kk]; scr[kk * 33 + (lane & 31)] = w; }
; __device__ __forceinline__ void conv_weights(LAS unsigned char* lds, unsigned char* ws, const PIn& I, const int l, const int wave, const int lane, const int gw, const int NGW, const int r_lo, const int r_hi) {
;     ...
;         if (r < I_OUT) { transpose_item<false>(I.w_out + (size_t)l * DM * DM, DM, DM, (bf16*)(wb + W_OUT), nullptr, scr, r, lane); continue; } r -= I_OUT;
.LBB0_534:
	s_andn2_b64 vcc, exec, s[6:7]
	s_cbranch_vccnz .LBB0_536
	s_lshl_b32 s6, s1, 1
	s_add_i32 s6, s6, 0x1f700
	s_and_b32 s7, s6, 0x1ffc0
	s_lshl_b32 s6, s1, 5
	s_and_b32 s6, s6, 0x3e0
	v_add_u32_e32 v64, s7, v0
	s_lshl_b32 s10, s6, 2
	v_add_u32_e32 v62, s7, v1
	v_ashrrev_i32_e32 v65, 31, v64
	v_add_u32_e32 v66, s7, v25
	v_add_u32_e32 v68, s7, v24
	v_add_u32_e32 v70, s7, v27
	v_add_u32_e32 v72, s7, v26
	v_add_u32_e32 v74, s7, v29
	v_add_u32_e32 v76, s7, v28
	v_lshl_add_u64 v[60:61], v[20:21], 0, s[10:11]
	v_ashrrev_i32_e32 v63, 31, v62
	v_lshlrev_b64 v[64:65], 12, v[64:65]
	v_ashrrev_i32_e32 v69, 31, v68
	v_ashrrev_i32_e32 v67, 31, v66
	v_ashrrev_i32_e32 v73, 31, v72
	v_ashrrev_i32_e32 v71, 31, v70
	v_ashrrev_i32_e32 v77, 31, v76
	v_ashrrev_i32_e32 v75, 31, v74
	v_lshlrev_b64 v[62:63], 12, v[62:63]
	v_lshl_add_u64 v[64:65], v[60:61], 0, v[64:65]
	v_lshlrev_b64 v[66:67], 12, v[66:67]
	v_lshlrev_b64 v[68:69], 12, v[68:69]
	v_lshlrev_b64 v[70:71], 12, v[70:71]
	v_lshlrev_b64 v[72:73], 12, v[72:73]
	v_lshlrev_b64 v[74:75], 12, v[74:75]
	v_lshlrev_b64 v[76:77], 12, v[76:77]
	v_lshl_add_u64 v[62:63], v[60:61], 0, v[62:63]
	v_lshl_add_u64 v[68:69], v[60:61], 0, v[68:69]
	v_lshl_add_u64 v[66:67], v[60:61], 0, v[66:67]
	v_lshl_add_u64 v[72:73], v[60:61], 0, v[72:73]
	v_lshl_add_u64 v[70:71], v[60:61], 0, v[70:71]
	v_lshl_add_u64 v[76:77], v[60:61], 0, v[76:77]
	v_lshl_add_u64 v[74:75], v[60:61], 0, v[74:75]
	global_load_dword v78, v[64:65], off nt
	global_load_dword v79, v[62:63], off nt
	global_load_dword v80, v[68:69], off nt
	global_load_dword v81, v[66:67], off nt
	global_load_dword v82, v[72:73], off nt
	global_load_dword v83, v[70:71], off nt
	global_load_dword v84, v[76:77], off nt
	global_load_dword v85, v[74:75], off nt
	v_add_u32_e32 v64, s7, v30
	v_add_u32_e32 v62, s7, v31
	v_ashrrev_i32_e32 v65, 31, v64
	v_add_u32_e32 v66, s7, v33
	v_add_u32_e32 v68, s7, v32
	v_add_u32_e32 v70, s7, v35
	v_add_u32_e32 v72, s7, v34
	v_add_u32_e32 v74, s7, v37
	v_add_u32_e32 v76, s7, v36
	v_ashrrev_i32_e32 v63, 31, v62
	v_lshlrev_b64 v[64:65], 12, v[64:65]
	v_ashrrev_i32_e32 v69, 31, v68
	v_ashrrev_i32_e32 v67, 31, v66
	v_ashrrev_i32_e32 v73, 31, v72
	v_ashrrev_i32_e32 v71, 31, v70
	v_ashrrev_i32_e32 v77, 31, v76
	v_ashrrev_i32_e32 v75, 31, v74
	v_lshlrev_b64 v[62:63], 12, v[62:63]
	v_lshl_add_u64 v[64:65], v[60:61], 0, v[64:65]
	v_lshlrev_b64 v[66:67], 12, v[66:67]
	v_lshlrev_b64 v[68:69], 12, v[68:69]
	v_lshlrev_b64 v[70:71], 12, v[70:71]
	v_lshlrev_b64 v[72:73], 12, v[72:73]
	v_lshlrev_b64 v[74:75], 12, v[74:75]
	v_lshlrev_b64 v[76:77], 12, v[76:77]
	v_lshl_add_u64 v[62:63], v[60:61], 0, v[62:63]
	v_lshl_add_u64 v[68:69], v[60:61], 0, v[68:69]
	v_lshl_add_u64 v[66:67], v[60:61], 0, v[66:67]
	v_lshl_add_u64 v[72:73], v[60:61], 0, v[72:73]
	v_lshl_add_u64 v[70:71], v[60:61], 0, v[70:71]
	v_lshl_add_u64 v[76:77], v[60:61], 0, v[76:77]
	v_lshl_add_u64 v[74:75], v[60:61], 0, v[74:75]
	global_load_dword v86, v[64:65], off nt
	global_load_dword v87, v[62:63], off nt
	global_load_dword v88, v[68:69], off nt
	global_load_dword v89, v[66:67], off nt
	global_load_dword v90, v[72:73], off nt
	global_load_dword v91, v[70:71], off nt
	global_load_dword v92, v[76:77], off nt
	global_load_dword v93, v[74:75], off nt
	v_add_u32_e32 v64, s7, v38
	v_add_u32_e32 v66, s7, v41
	v_add_u32_e32 v68, s7, v40
	v_add_u32_e32 v74, s7, v45
	v_add_u32_e32 v76, s7, v44
	v_add_u32_e32 v62, s7, v39
	v_ashrrev_i32_e32 v65, 31, v64
	v_ashrrev_i32_e32 v69, 31, v68
	v_ashrrev_i32_e32 v67, 31, v66
	v_add_u32_e32 v70, s7, v43
	v_add_u32_e32 v72, s7, v42
	v_ashrrev_i32_e32 v77, 31, v76
	v_ashrrev_i32_e32 v75, 31, v74
	v_ashrrev_i32_e32 v63, 31, v62
	v_lshlrev_b64 v[64:65], 12, v[64:65]
	v_lshlrev_b64 v[66:67], 12, v[66:67]
	v_lshlrev_b64 v[68:69], 12, v[68:69]
	v_ashrrev_i32_e32 v73, 31, v72
	v_ashrrev_i32_e32 v71, 31, v70
	v_lshlrev_b64 v[74:75], 12, v[74:75]
	v_lshlrev_b64 v[76:77], 12, v[76:77]
	v_lshlrev_b64 v[62:63], 12, v[62:63]
	v_lshl_add_u64 v[64:65], v[60:61], 0, v[64:65]
	v_lshl_add_u64 v[68:69], v[60:61], 0, v[68:69]
	v_lshl_add_u64 v[66:67], v[60:61], 0, v[66:67]
	v_lshlrev_b64 v[70:71], 12, v[70:71]
	v_lshlrev_b64 v[72:73], 12, v[72:73]
	v_lshl_add_u64 v[76:77], v[60:61], 0, v[76:77]
	v_lshl_add_u64 v[74:75], v[60:61], 0, v[74:75]
	v_lshl_add_u64 v[62:63], v[60:61], 0, v[62:63]
	v_lshl_add_u64 v[72:73], v[60:61], 0, v[72:73]
	v_lshl_add_u64 v[70:71], v[60:61], 0, v[70:71]
	global_load_dword v94, v[64:65], off nt
	global_load_dword v95, v[62:63], off nt
	global_load_dword v96, v[68:69], off nt
	global_load_dword v97, v[66:67], off nt
	global_load_dword v137, v[72:73], off nt
	global_load_dword v138, v[70:71], off nt
	s_nop 0
	global_load_dword v76, v[76:77], off nt
	s_nop 0
	global_load_dword v74, v[74:75], off nt
	v_add_u32_e32 v64, s7, v46
	v_add_u32_e32 v66, s7, v49
	v_add_u32_e32 v68, s7, v48
	v_add_u32_e32 v62, s7, v47
	v_ashrrev_i32_e32 v65, 31, v64
	v_ashrrev_i32_e32 v69, 31, v68
	v_ashrrev_i32_e32 v67, 31, v66
	v_add_u32_e32 v70, s7, v51
	v_add_u32_e32 v72, s7, v50
	v_ashrrev_i32_e32 v63, 31, v62
	v_lshlrev_b64 v[64:65], 12, v[64:65]
	v_lshlrev_b64 v[66:67], 12, v[66:67]
	v_lshlrev_b64 v[68:69], 12, v[68:69]
	v_ashrrev_i32_e32 v73, 31, v72
	v_ashrrev_i32_e32 v71, 31, v70
	v_lshlrev_b64 v[62:63], 12, v[62:63]
	v_lshl_add_u64 v[64:65], v[60:61], 0, v[64:65]
	v_lshl_add_u64 v[68:69], v[60:61], 0, v[68:69]
	v_lshl_add_u64 v[66:67], v[60:61], 0, v[66:67]
	v_lshlrev_b64 v[70:71], 12, v[70:71]
	v_lshlrev_b64 v[72:73], 12, v[72:73]
	v_lshl_add_u64 v[62:63], v[60:61], 0, v[62:63]
	v_lshl_add_u64 v[72:73], v[60:61], 0, v[72:73]
	v_lshl_add_u64 v[70:71], v[60:61], 0, v[70:71]
	global_load_dword v75, v[64:65], off nt
	global_load_dword v77, v[62:63], off nt
	s_nop 0
	global_load_dword v68, v[68:69], off nt
	s_nop 0
	global_load_dword v66, v[66:67], off nt
	s_nop 0
	global_load_dword v67, v[72:73], off nt
	global_load_dword v69, v[70:71], off nt
	v_add_u32_e32 v64, s7, v52
	v_add_u32_e32 v62, s7, v53
	v_ashrrev_i32_e32 v65, 31, v64
	v_ashrrev_i32_e32 v63, 31, v62
	v_lshlrev_b64 v[64:65], 12, v[64:65]
	v_lshlrev_b64 v[62:63], 12, v[62:63]
	v_lshl_add_u64 v[64:65], v[60:61], 0, v[64:65]
	global_load_dword v64, v[64:65], off nt
	v_lshl_add_u64 v[60:61], v[60:61], 0, v[62:63]
	global_load_dword v60, v[60:61], off nt
	v_add_u32_e32 v61, v98, v104
	s_waitcnt vmcnt(31)
; #define LAS __attribute__((address_space(3)))
; __device__ __forceinline__ unsigned cvt_pk(float lo, float hi) { unsigned r; asm("v_cvt_pk_bf16_f32 %0, %1, %2" : "=v"(r) : "v"(lo), "v"(hi)); return r; }
; template <bool GU>
; __device__ __forceinline__ void transpose_item(const float* W, int K, int N, bf16* WT, const float* gs, LAS float* scr, int item, int lane) {
;     ...
;     for (int i = 0; i < 32; ++i) { const int kk = 2 * i + (lane >> 5); float w = W[(size_t)(k0 + kk) * N + n0 + (lane & 31)]; if (gs) w *= gs[k0 + kk]; scr[kk * 33 + (lane & 31)] = w; }
;     asm volatile("s_waitcnt lgkmcnt(0)" ::: "memory");
;     int d0 = n0;
;     if (GU) { const int f = (n0 < FF) ? n0 : n0 - FF; d0 = 256 * (f >> 7) + (f & 127) + ((n0 < FF) ? 0 : 128); }
;     const int c = lane & 7;
; #pragma unroll
;     for (int j = 0; j < 4; ++j) { const int n = (lane >> 3) + 8 * j; const LAS float* s = scr + (8 * c) * 33 + n;
;         v4u o; o.x = cvt_pk(s[0 * 33], s[1 * 33]); o.y = cvt_pk(s[2 * 33], s[3 * 33]); o.z = cvt_pk(s[4 * 33], s[5 * 33]); o.w = cvt_pk(s[6 * 33], s[7 * 33]);
;         *(v4u*)(WT + (size_t)(d0 + n) * K + k0 + 8 * c) = o; }
;     asm volatile("s_waitcnt lgkmcnt(0)" ::: "memory");
	ds_write_b32 v61, v78
	v_add_u32_e32 v61, v98, v105
	s_waitcnt vmcnt(30)
	ds_write_b32 v61, v79
	v_add_u32_e32 v61, v98, v106
	s_waitcnt vmcnt(29)
	ds_write_b32 v61, v80
	v_add_u32_e32 v61, v98, v107
	s_waitcnt vmcnt(28)
	ds_write_b32 v61, v81
	v_add_u32_e32 v61, v98, v108
	s_waitcnt vmcnt(27)
	ds_write_b32 v61, v82
	v_add_u32_e32 v61, v98, v109
	s_waitcnt vmcnt(26)
	ds_write_b32 v61, v83
	v_add_u32_e32 v61, v98, v110
	s_waitcnt vmcnt(25)
	ds_write_b32 v61, v84
	v_add_u32_e32 v61, v98, v111
	s_waitcnt vmcnt(24)
	ds_write_b32 v61, v85
	v_add_u32_e32 v61, v98, v112
	s_waitcnt vmcnt(23)
	ds_write_b32 v61, v86
	v_add_u32_e32 v61, v98, v113
	s_waitcnt vmcnt(22)
	ds_write_b32 v61, v87
	v_add_u32_e32 v61, v98, v114
	s_waitcnt vmcnt(21)
	ds_write_b32 v61, v88
	v_add_u32_e32 v61, v98, v115
	s_waitcnt vmcnt(20)
	ds_write_b32 v61, v89
	v_add_u32_e32 v61, v98, v116
	s_waitcnt vmcnt(19)
	ds_write_b32 v61, v90
	v_add_u32_e32 v61, v98, v117
	s_waitcnt vmcnt(18)
	ds_write_b32 v61, v91
	v_add_u32_e32 v61, v98, v118
	s_waitcnt vmcnt(17)
	ds_write_b32 v61, v92
	v_add_u32_e32 v61, v98, v119
	s_waitcnt vmcnt(16)
	ds_write_b32 v61, v93
	v_add_u32_e32 v61, v98, v120
	v_add_u32_e32 v82, s6, v99
	s_lshl_b32 s10, s7, 1
	v_ashrrev_i32_e32 v83, 31, v82
	v_lshl_add_u64 v[80:81], v[10:11], 0, s[10:11]
	s_waitcnt vmcnt(15)
	ds_write_b32 v61, v94
	v_add_u32_e32 v61, v98, v121
	s_waitcnt vmcnt(14)
	ds_write_b32 v61, v95
	v_add_u32_e32 v61, v98, v122
	s_waitcnt vmcnt(13)
	ds_write_b32 v61, v96
	v_add_u32_e32 v61, v98, v123
	s_waitcnt vmcnt(12)
	ds_write_b32 v61, v97
	v_add_u32_e32 v61, v98, v124
	s_waitcnt vmcnt(11)
	ds_write_b32 v61, v137
	v_add_u32_e32 v61, v98, v125
	s_waitcnt vmcnt(10)
	ds_write_b32 v61, v138
	v_add_u32_e32 v61, v98, v126
	s_waitcnt vmcnt(9)
	ds_write_b32 v61, v76
	v_add_u32_e32 v61, v98, v127
	s_waitcnt vmcnt(8)
	ds_write_b32 v61, v74
	v_add_u32_e32 v61, v98, v128
	v_lshlrev_b64 v[82:83], 11, v[82:83]
	v_lshl_add_u64 v[82:83], v[80:81], 0, v[82:83]
	s_waitcnt vmcnt(7)
	ds_write_b32 v61, v75
	v_add_u32_e32 v61, v98, v129
	s_waitcnt vmcnt(6)
	ds_write_b32 v61, v77
	v_add_u32_e32 v61, v98, v130
	s_waitcnt vmcnt(5)
	ds_write_b32 v61, v68
	v_add_u32_e32 v61, v98, v131
	s_waitcnt vmcnt(4)
	ds_write_b32 v61, v66
	v_add_u32_e32 v61, v98, v132
	s_waitcnt vmcnt(3)
	ds_write_b32 v61, v67
	v_add_u32_e32 v61, v98, v133
	s_waitcnt vmcnt(2)
	ds_write_b32 v61, v69
	v_add_u32_e32 v61, v98, v134
	s_waitcnt vmcnt(1)
	ds_write_b32 v61, v64
	v_add_u32_e32 v61, v98, v135
	s_waitcnt vmcnt(0)
	ds_write_b32 v61, v60
	s_waitcnt lgkmcnt(0)
	ds_read2_b32 v[64:65], v100 offset0:33 offset1:41
	ds_read2_b32 v[66:67], v100 offset1:8
	ds_read2_b32 v[68:69], v100 offset0:66 offset1:74
	ds_read2_b32 v[70:71], v100 offset0:99 offset1:107
	ds_read2_b32 v[72:73], v100 offset0:132 offset1:140
	ds_read2_b32 v[74:75], v100 offset0:165 offset1:173
	ds_read2_b32 v[76:77], v100 offset0:198 offset1:206
	ds_read2_b32 v[78:79], v100 offset0:231 offset1:239
	s_waitcnt lgkmcnt(6)
	v_cvt_pk_bf16_f32 v60, v66, v64
	v_add_u32_e32 v64, s6, v101
	s_waitcnt lgkmcnt(4)
	v_cvt_pk_bf16_f32 v61, v68, v70
	s_waitcnt lgkmcnt(2)
	v_cvt_pk_bf16_f32 v62, v72, v74
	s_waitcnt lgkmcnt(0)
	v_cvt_pk_bf16_f32 v63, v76, v78
	global_store_dwordx4 v[82:83], v[60:63], off sc1
	s_nop 1
	v_cvt_pk_bf16_f32 v60, v67, v65
	v_ashrrev_i32_e32 v65, 31, v64
	v_lshlrev_b64 v[64:65], 11, v[64:65]
	v_cvt_pk_bf16_f32 v61, v69, v71
	v_cvt_pk_bf16_f32 v62, v73, v75
	v_cvt_pk_bf16_f32 v63, v77, v79
	v_lshl_add_u64 v[64:65], v[80:81], 0, v[64:65]
	ds_read2_b32 v[66:67], v100 offset0:16 offset1:24
	ds_read2_b32 v[68:69], v100 offset0:49 offset1:57
	ds_read2_b32 v[70:71], v100 offset0:82 offset1:90
	ds_read2_b32 v[72:73], v100 offset0:115 offset1:123
	ds_read2_b32 v[74:75], v100 offset0:148 offset1:156
	ds_read2_b32 v[76:77], v100 offset0:181 offset1:189
	ds_read2_b32 v[78:79], v100 offset0:214 offset1:222
	ds_read2_b32 v[82:83], v100 offset0:247 offset1:255
	global_store_dwordx4 v[64:65], v[60:63], off sc1
	v_add_u32_e32 v64, s6, v102
	v_ashrrev_i32_e32 v65, 31, v64
	v_lshlrev_b64 v[64:65], 11, v[64:65]
	v_lshl_add_u64 v[64:65], v[80:81], 0, v[64:65]
	s_waitcnt lgkmcnt(6)
	v_cvt_pk_bf16_f32 v60, v66, v68
	s_waitcnt lgkmcnt(4)
	v_cvt_pk_bf16_f32 v61, v70, v72
	s_waitcnt lgkmcnt(2)
	v_cvt_pk_bf16_f32 v62, v74, v76
	s_waitcnt lgkmcnt(0)
	v_cvt_pk_bf16_f32 v63, v78, v82
	global_store_dwordx4 v[64:65], v[60:63], off sc1
	v_add_u32_e32 v64, s6, v103
	v_ashrrev_i32_e32 v65, 31, v64
	v_lshlrev_b64 v[64:65], 11, v[64:65]
	v_lshl_add_u64 v[64:65], v[80:81], 0, v[64:65]
	v_cvt_pk_bf16_f32 v60, v67, v69
	v_cvt_pk_bf16_f32 v61, v71, v73
	v_cvt_pk_bf16_f32 v62, v75, v77
	v_cvt_pk_bf16_f32 v63, v79, v83
	global_store_dwordx4 v[64:65], v[60:63], off sc1
	s_waitcnt lgkmcnt(0)

; __device__ __forceinline__ unsigned cvt_pk(float lo, float hi) { unsigned r; asm("v_cvt_pk_bf16_f32 %0, %1, %2" : "=v"(r) : "v"(lo), "v"(hi)); return r; }
; __device__ __forceinline__ void convert_flat(const float* src, bf16* dst, size_t n, size_t gtid, size_t gthreads) {
;     for (size_t i = gtid * 8; i < n; i += gthreads * 8) {
;         const f32x4 a = *(const f32x4*)(src + i), b = *(const f32x4*)(src + i + 4);
;         v4u w; w.x = cvt_pk(a[0], a[1]); w.y = cvt_pk(a[2], a[3]); w.z = cvt_pk(b[0], b[1]); w.w = cvt_pk(b[2], b[3]);
;         *(v4u*)(dst + i) = w;
;     }
.LBB0_619:
	global_load_dwordx4 v[12:15], v[6:7], off nt
	global_load_dwordx4 v[16:19], v[6:7], off offset:16 nt
	v_lshl_add_u64 v[10:11], v[10:11], 0, s[6:7]
	v_cmp_lt_u64_e32 vcc, s[42:43], v[10:11]
	v_lshl_add_u64 v[6:7], v[6:7], 0, s[14:15]
	s_or_b64 s[30:31], vcc, s[30:31]
	s_waitcnt vmcnt(1)
	v_cvt_pk_bf16_f32 v12, v12, v13
	v_cvt_pk_bf16_f32 v13, v14, v15
	s_waitcnt vmcnt(0)
	v_cvt_pk_bf16_f32 v14, v16, v17
	v_cvt_pk_bf16_f32 v15, v18, v19
	global_store_dwordx4 v[8:9], v[12:15], off sc1
	v_lshl_add_u64 v[8:9], v[8:9], 0, s[16:17]
	s_andn2_b64 exec, exec, s[30:31]
	s_cbranch_execnz .LBB0_619

; __device__ __forceinline__ unsigned cvt_pk(float lo, float hi) { unsigned r; asm("v_cvt_pk_bf16_f32 %0, %1, %2" : "=v"(r) : "v"(lo), "v"(hi)); return r; }
; __device__ __forceinline__ void convert_flat(const float* src, bf16* dst, size_t n, size_t gtid, size_t gthreads) {
;     for (size_t i = gtid * 8; i < n; i += gthreads * 8) {
;         const f32x4 a = *(const f32x4*)(src + i), b = *(const f32x4*)(src + i + 4);
;         v4u w; w.x = cvt_pk(a[0], a[1]); w.y = cvt_pk(a[2], a[3]); w.z = cvt_pk(b[0], b[1]); w.w = cvt_pk(b[2], b[3]);
;         *(v4u*)(dst + i) = w;
;     }
.LBB0_622:
	global_load_dwordx4 v[6:9], v[4:5], off nt
	global_load_dwordx4 v[10:13], v[4:5], off offset:16 nt
	v_lshl_add_u64 v[0:1], v[0:1], 0, s[6:7]
	v_cmp_lt_u64_e32 vcc, s[18:19], v[0:1]
	v_lshl_add_u64 v[4:5], v[4:5], 0, s[14:15]
	s_or_b64 s[16:17], vcc, s[16:17]
	s_waitcnt vmcnt(1)
	v_cvt_pk_bf16_f32 v6, v6, v7
	v_cvt_pk_bf16_f32 v7, v8, v9
	s_waitcnt vmcnt(0)
	v_cvt_pk_bf16_f32 v8, v10, v11
	v_cvt_pk_bf16_f32 v9, v12, v13
	global_store_dwordx4 v[2:3], v[6:9], off sc1
	v_lshl_add_u64 v[2:3], v[2:3], 0, s[10:11]
	s_andn2_b64 exec, exec, s[16:17]
	s_cbranch_execnz .LBB0_622

; #define LAS __attribute__((address_space(3)))
; __device__ __forceinline__ unsigned cvt_pk(float lo, float hi) { unsigned r; asm("v_cvt_pk_bf16_f32 %0, %1, %2" : "=v"(r) : "v"(lo), "v"(hi)); return r; }
; template <bool GU>
; __device__ __forceinline__ void transpose_item(const float* W, int K, int N, bf16* WT, const float* gs, LAS float* scr, int item, int lane) {
;     ...
;     const int c = lane & 7;
; #pragma unroll
;     for (int j = 0; j < 4; ++j) { const int n = (lane >> 3) + 8 * j; const LAS float* s = scr + (8 * c) * 33 + n;
;         v4u o; o.x = cvt_pk(s[0 * 33], s[1 * 33]); o.y = cvt_pk(s[2 * 33], s[3 * 33]); o.z = cvt_pk(s[4 * 33], s[5 * 33]); o.w = cvt_pk(s[6 * 33], s[7 * 33]);
;         *(v4u*)(WT + (size_t)(d0 + n) * K + k0 + 8 * c) = o; }
;     asm volatile("s_waitcnt lgkmcnt(0)" ::: "memory");
.LBB0_703:
	s_waitcnt lgkmcnt(0)
	ds_read2_b32 v[66:67], v128 offset0:33 offset1:41
	ds_read2_b32 v[68:69], v128 offset1:8
	ds_read2_b32 v[70:71], v128 offset0:66 offset1:74
	ds_read2_b32 v[72:73], v128 offset0:99 offset1:107
	ds_read2_b32 v[74:75], v128 offset0:132 offset1:140
	ds_read2_b32 v[76:77], v128 offset0:165 offset1:173
	ds_read2_b32 v[78:79], v128 offset0:198 offset1:206
	ds_read2_b32 v[80:81], v128 offset0:231 offset1:239
	v_add_u32_e32 v84, s48, v127
	v_ashrrev_i32_e32 v85, 31, v84
	v_lshl_add_u64 v[82:83], s[50:51], 1, v[14:15]
	v_lshlrev_b64 v[84:85], 11, v[84:85]
	s_waitcnt lgkmcnt(6)
	v_cvt_pk_bf16_f32 v62, v68, v66
	v_lshl_add_u64 v[84:85], v[82:83], 0, v[84:85]
	v_add_u32_e32 v66, s48, v129
	s_waitcnt lgkmcnt(4)
	v_cvt_pk_bf16_f32 v63, v70, v72
	s_waitcnt lgkmcnt(2)
	v_cvt_pk_bf16_f32 v64, v74, v76
	s_waitcnt lgkmcnt(0)
	v_cvt_pk_bf16_f32 v65, v78, v80
	global_store_dwordx4 v[84:85], v[62:65], off sc1
	s_nop 1
	v_cvt_pk_bf16_f32 v62, v69, v67
	v_ashrrev_i32_e32 v67, 31, v66
	v_lshlrev_b64 v[66:67], 11, v[66:67]
	v_cvt_pk_bf16_f32 v63, v71, v73
	v_cvt_pk_bf16_f32 v64, v75, v77
	v_cvt_pk_bf16_f32 v65, v79, v81
	v_lshl_add_u64 v[66:67], v[82:83], 0, v[66:67]
	ds_read2_b32 v[68:69], v128 offset0:16 offset1:24
	ds_read2_b32 v[70:71], v128 offset0:49 offset1:57
	ds_read2_b32 v[72:73], v128 offset0:82 offset1:90
	ds_read2_b32 v[74:75], v128 offset0:115 offset1:123
	ds_read2_b32 v[76:77], v128 offset0:148 offset1:156
	ds_read2_b32 v[78:79], v128 offset0:181 offset1:189
	ds_read2_b32 v[80:81], v128 offset0:214 offset1:222
	ds_read2_b32 v[84:85], v128 offset0:247 offset1:255
	global_store_dwordx4 v[66:67], v[62:65], off sc1
	v_add_u32_e32 v66, s48, v130
	v_ashrrev_i32_e32 v67, 31, v66
	v_lshlrev_b64 v[66:67], 11, v[66:67]
	v_lshl_add_u64 v[66:67], v[82:83], 0, v[66:67]
	s_waitcnt lgkmcnt(6)
	v_cvt_pk_bf16_f32 v62, v68, v70
	s_waitcnt lgkmcnt(4)
	v_cvt_pk_bf16_f32 v63, v72, v74
	s_waitcnt lgkmcnt(2)
	v_cvt_pk_bf16_f32 v64, v76, v78
	s_waitcnt lgkmcnt(0)
	v_cvt_pk_bf16_f32 v65, v80, v84
	global_store_dwordx4 v[66:67], v[62:65], off sc1
	v_add_u32_e32 v66, s48, v131
	v_ashrrev_i32_e32 v67, 31, v66
	v_lshlrev_b64 v[66:67], 11, v[66:67]
	v_lshl_add_u64 v[66:67], v[82:83], 0, v[66:67]
	v_cvt_pk_bf16_f32 v62, v69, v71
	v_cvt_pk_bf16_f32 v63, v73, v75
	v_cvt_pk_bf16_f32 v64, v77, v79
	v_cvt_pk_bf16_f32 v65, v81, v85
	global_store_dwordx4 v[66:67], v[62:65], off sc1
	s_waitcnt lgkmcnt(0)

; template <bool GU>
; __device__ __forceinline__ void transpose_item(const float* W, int K, int N, bf16* WT, const float* gs, LAS float* scr, int item, int lane) {
;     const int nblk = N / 32, kb = item / nblk, nb = item % nblk, k0 = 64 * kb, n0 = 32 * nb;
; #pragma unroll 16
;     for (int i = 0; i < 32; ++i) { const int kk = 2 * i + (lane >> 5); float w = W[(size_t)(k0 + kk) * N + n0 + (lane & 31)]; if (gs) w *= gs[k0 + kk]; scr[kk * 33 + (lane & 31)] = w; }
;     asm volatile("s_waitcnt lgkmcnt(0)" ::: "memory");
; __device__ __forceinline__ void conv_weights(LAS unsigned char* lds, unsigned char* ws, const PIn& I, const int l, const int wave, const int lane, const int gw, const int NGW, const int r_lo, const int r_hi) {
;     ...
;     for (int it = r_lo + gw; it < (r_hi < I_LAYER ? r_hi : I_LAYER); it += NGW) {
;         int r = it;
;         if (r < I_IN) { transpose_item<false>(I.w_in + (size_t)l * DM * NIN, DM, NIN, (bf16*)(wb + W_IN), I.g_mix + l * DM, scr, r, lane); continue; } r -= I_IN;
;         if (r < I_OUT) { transpose_item<false>(I.w_out + (size_t)l * DM * DM, DM, DM, (bf16*)(wb + W_OUT), nullptr, scr, r, lane); continue; } r -= I_OUT;
;         if (r < I_GU) { transpose_item<true>(I.w_gu + (size_t)l * DM * 2 * FF, DM, 2 * FF, (bf16*)(wb + W_GU), I.g_ffn + l * DM, scr, r, lane); continue; } r -= I_GU;
;         if (r < I_D) { transpose_item<false>(I.w_d + (size_t)l * FF * DM, FF, DM, (bf16*)(wb + W_D), nullptr, scr, r, lane); continue; } r -= I_D;
;         if (r < I_PP) { transpose_item<false>(I.w_pp + (size_t)l * DPLE * DM, DPLE, DM, (bf16*)(wb + W_PP), nullptr, scr, r, lane); continue; } r -= I_PP;
;         transpose_item<false>(I.w_pg + (size_t)l * DM * DM, DM, DM, (bf16*)(wb + W_PG), nullptr, scr, r, lane);
.LBB0_707:
	s_cmpk_gt_u32 s0, 0x67f
	s_cbranch_scc0 .LBB0_755
	s_cmpk_gt_u32 s0, 0x117f
	s_cbranch_scc0 .LBB0_718
	s_cmpk_gt_u32 s0, 0x16ff
	s_cbranch_scc0 .LBB0_715
	s_lshl_b32 s40, s0, 1
	s_cmpk_gt_u32 s0, 0x177f
	s_cbranch_scc0 .LBB0_712
	s_add_i32 s6, s40, 0x1d100
	s_and_b32 s7, s6, 0x1ffc0
	s_lshl_b32 s6, s0, 5
	s_and_b32 s6, s6, 0x3e0
	v_add_u32_e32 v66, s7, v0
	s_lshl_b32 s10, s6, 2
	v_add_u32_e32 v64, s7, v1
	v_ashrrev_i32_e32 v67, 31, v66
	v_add_u32_e32 v68, s7, v27
	v_add_u32_e32 v70, s7, v26
	v_add_u32_e32 v72, s7, v29
	v_add_u32_e32 v74, s7, v28
	v_add_u32_e32 v76, s7, v31
	v_add_u32_e32 v78, s7, v30
	v_lshl_add_u64 v[62:63], v[16:17], 0, s[10:11]
	v_ashrrev_i32_e32 v65, 31, v64
	v_lshlrev_b64 v[66:67], 12, v[66:67]
	v_ashrrev_i32_e32 v71, 31, v70
	v_ashrrev_i32_e32 v69, 31, v68
	v_ashrrev_i32_e32 v75, 31, v74
	v_ashrrev_i32_e32 v73, 31, v72
	v_ashrrev_i32_e32 v79, 31, v78
	v_ashrrev_i32_e32 v77, 31, v76
	v_lshlrev_b64 v[64:65], 12, v[64:65]
	v_lshl_add_u64 v[66:67], v[62:63], 0, v[66:67]
	v_lshlrev_b64 v[68:69], 12, v[68:69]
	v_lshlrev_b64 v[70:71], 12, v[70:71]
	v_lshlrev_b64 v[72:73], 12, v[72:73]
	v_lshlrev_b64 v[74:75], 12, v[74:75]
	v_lshlrev_b64 v[76:77], 12, v[76:77]
	v_lshlrev_b64 v[78:79], 12, v[78:79]
	v_lshl_add_u64 v[64:65], v[62:63], 0, v[64:65]
	v_lshl_add_u64 v[70:71], v[62:63], 0, v[70:71]
	v_lshl_add_u64 v[68:69], v[62:63], 0, v[68:69]
	v_lshl_add_u64 v[74:75], v[62:63], 0, v[74:75]
	v_lshl_add_u64 v[72:73], v[62:63], 0, v[72:73]
	v_lshl_add_u64 v[78:79], v[62:63], 0, v[78:79]
	v_lshl_add_u64 v[76:77], v[62:63], 0, v[76:77]
	global_load_dword v80, v[66:67], off nt
	global_load_dword v81, v[64:65], off nt
	global_load_dword v82, v[70:71], off nt
	global_load_dword v83, v[68:69], off nt
	global_load_dword v84, v[74:75], off nt
	global_load_dword v85, v[72:73], off nt
	global_load_dword v86, v[78:79], off nt
	global_load_dword v87, v[76:77], off nt
	v_add_u32_e32 v66, s7, v32
	v_add_u32_e32 v64, s7, v33
	v_ashrrev_i32_e32 v67, 31, v66
	v_add_u32_e32 v68, s7, v35
	v_add_u32_e32 v70, s7, v34
	v_add_u32_e32 v72, s7, v37
	v_add_u32_e32 v74, s7, v36
	v_add_u32_e32 v76, s7, v39
	v_add_u32_e32 v78, s7, v38
	v_ashrrev_i32_e32 v65, 31, v64
	v_lshlrev_b64 v[66:67], 12, v[66:67]
	v_ashrrev_i32_e32 v71, 31, v70
	v_ashrrev_i32_e32 v69, 31, v68
	v_ashrrev_i32_e32 v75, 31, v74
	v_ashrrev_i32_e32 v73, 31, v72
	v_ashrrev_i32_e32 v79, 31, v78
	v_ashrrev_i32_e32 v77, 31, v76
	v_lshlrev_b64 v[64:65], 12, v[64:65]
	v_lshl_add_u64 v[66:67], v[62:63], 0, v[66:67]
	v_lshlrev_b64 v[68:69], 12, v[68:69]
	v_lshlrev_b64 v[70:71], 12, v[70:71]
	v_lshlrev_b64 v[72:73], 12, v[72:73]
	v_lshlrev_b64 v[74:75], 12, v[74:75]
	v_lshlrev_b64 v[76:77], 12, v[76:77]
	v_lshlrev_b64 v[78:79], 12, v[78:79]
	v_lshl_add_u64 v[64:65], v[62:63], 0, v[64:65]
	v_lshl_add_u64 v[70:71], v[62:63], 0, v[70:71]
	v_lshl_add_u64 v[68:69], v[62:63], 0, v[68:69]
	v_lshl_add_u64 v[74:75], v[62:63], 0, v[74:75]
	v_lshl_add_u64 v[72:73], v[62:63], 0, v[72:73]
	v_lshl_add_u64 v[78:79], v[62:63], 0, v[78:79]
	v_lshl_add_u64 v[76:77], v[62:63], 0, v[76:77]
	global_load_dword v88, v[66:67], off nt
	global_load_dword v89, v[64:65], off nt
	global_load_dword v90, v[70:71], off nt
	global_load_dword v91, v[68:69], off nt
	global_load_dword v92, v[74:75], off nt
	global_load_dword v93, v[72:73], off nt
	global_load_dword v94, v[78:79], off nt
	global_load_dword v95, v[76:77], off nt
	v_add_u32_e32 v66, s7, v40
	v_add_u32_e32 v68, s7, v43
	v_add_u32_e32 v70, s7, v42
	v_add_u32_e32 v76, s7, v47
	v_add_u32_e32 v78, s7, v46
	v_add_u32_e32 v64, s7, v41
	v_ashrrev_i32_e32 v67, 31, v66
	v_ashrrev_i32_e32 v71, 31, v70
	v_ashrrev_i32_e32 v69, 31, v68
	v_add_u32_e32 v72, s7, v45
	v_add_u32_e32 v74, s7, v44
	v_ashrrev_i32_e32 v79, 31, v78
	v_ashrrev_i32_e32 v77, 31, v76
	v_ashrrev_i32_e32 v65, 31, v64
	v_lshlrev_b64 v[66:67], 12, v[66:67]
	v_lshlrev_b64 v[68:69], 12, v[68:69]
	v_lshlrev_b64 v[70:71], 12, v[70:71]
	v_ashrrev_i32_e32 v75, 31, v74
	v_ashrrev_i32_e32 v73, 31, v72
	v_lshlrev_b64 v[76:77], 12, v[76:77]
	v_lshlrev_b64 v[78:79], 12, v[78:79]
	v_lshlrev_b64 v[64:65], 12, v[64:65]
	v_lshl_add_u64 v[66:67], v[62:63], 0, v[66:67]
	v_lshl_add_u64 v[70:71], v[62:63], 0, v[70:71]
	v_lshl_add_u64 v[68:69], v[62:63], 0, v[68:69]
	v_lshlrev_b64 v[72:73], 12, v[72:73]
	v_lshlrev_b64 v[74:75], 12, v[74:75]
	v_lshl_add_u64 v[78:79], v[62:63], 0, v[78:79]
	v_lshl_add_u64 v[76:77], v[62:63], 0, v[76:77]
	v_lshl_add_u64 v[64:65], v[62:63], 0, v[64:65]
	v_lshl_add_u64 v[74:75], v[62:63], 0, v[74:75]
	v_lshl_add_u64 v[72:73], v[62:63], 0, v[72:73]
	global_load_dword v96, v[66:67], off nt
	global_load_dword v97, v[64:65], off nt
	global_load_dword v98, v[70:71], off nt
	global_load_dword v99, v[68:69], off nt
	global_load_dword v100, v[74:75], off nt
	global_load_dword v101, v[72:73], off nt
	s_nop 0
	global_load_dword v78, v[78:79], off nt
	s_nop 0
	global_load_dword v76, v[76:77], off nt
	v_add_u32_e32 v66, s7, v48
	v_add_u32_e32 v68, s7, v51
	v_add_u32_e32 v70, s7, v50
	v_add_u32_e32 v64, s7, v49
	v_ashrrev_i32_e32 v67, 31, v66
	v_ashrrev_i32_e32 v71, 31, v70
	v_ashrrev_i32_e32 v69, 31, v68
	v_add_u32_e32 v72, s7, v53
	v_add_u32_e32 v74, s7, v52
	v_ashrrev_i32_e32 v65, 31, v64
	v_lshlrev_b64 v[66:67], 12, v[66:67]
	v_lshlrev_b64 v[68:69], 12, v[68:69]
	v_lshlrev_b64 v[70:71], 12, v[70:71]
	v_ashrrev_i32_e32 v75, 31, v74
	v_ashrrev_i32_e32 v73, 31, v72
	v_lshlrev_b64 v[64:65], 12, v[64:65]
	v_lshl_add_u64 v[66:67], v[62:63], 0, v[66:67]
	v_lshl_add_u64 v[70:71], v[62:63], 0, v[70:71]
	v_lshl_add_u64 v[68:69], v[62:63], 0, v[68:69]
	v_lshlrev_b64 v[72:73], 12, v[72:73]
	v_lshlrev_b64 v[74:75], 12, v[74:75]
	v_lshl_add_u64 v[64:65], v[62:63], 0, v[64:65]
	v_lshl_add_u64 v[74:75], v[62:63], 0, v[74:75]
	v_lshl_add_u64 v[72:73], v[62:63], 0, v[72:73]
	global_load_dword v77, v[66:67], off nt
	global_load_dword v79, v[64:65], off nt
	s_nop 0
	global_load_dword v70, v[70:71], off nt
	s_nop 0
	global_load_dword v68, v[68:69], off nt
	s_nop 0
	global_load_dword v69, v[74:75], off nt
	global_load_dword v71, v[72:73], off nt
	v_add_u32_e32 v66, s7, v54
	v_add_u32_e32 v64, s7, v55
	v_ashrrev_i32_e32 v67, 31, v66
	v_ashrrev_i32_e32 v65, 31, v64
	v_lshlrev_b64 v[66:67], 12, v[66:67]
	v_lshlrev_b64 v[64:65], 12, v[64:65]
	v_lshl_add_u64 v[66:67], v[62:63], 0, v[66:67]
	global_load_dword v66, v[66:67], off nt
	v_lshl_add_u64 v[62:63], v[62:63], 0, v[64:65]
	global_load_dword v62, v[62:63], off nt
	v_add_u32_e32 v63, v126, v132
	s_waitcnt vmcnt(31)
; #define LAS __attribute__((address_space(3)))
; __device__ __forceinline__ unsigned cvt_pk(float lo, float hi) { unsigned r; asm("v_cvt_pk_bf16_f32 %0, %1, %2" : "=v"(r) : "v"(lo), "v"(hi)); return r; }
; template <bool GU>
; __device__ __forceinline__ void transpose_item(const float* W, int K, int N, bf16* WT, const float* gs, LAS float* scr, int item, int lane) {
;     ...
;     for (int i = 0; i < 32; ++i) { const int kk = 2 * i + (lane >> 5); float w = W[(size_t)(k0 + kk) * N + n0 + (lane & 31)]; if (gs) w *= gs[k0 + kk]; scr[kk * 33 + (lane & 31)] = w; }
;     asm volatile("s_waitcnt lgkmcnt(0)" ::: "memory");
;     int d0 = n0;
;     if (GU) { const int f = (n0 < FF) ? n0 : n0 - FF; d0 = 256 * (f >> 7) + (f & 127) + ((n0 < FF) ? 0 : 128); }
;     const int c = lane & 7;
; #pragma unroll
;     for (int j = 0; j < 4; ++j) { const int n = (lane >> 3) + 8 * j; const LAS float* s = scr + (8 * c) * 33 + n;
;         v4u o; o.x = cvt_pk(s[0 * 33], s[1 * 33]); o.y = cvt_pk(s[2 * 33], s[3 * 33]); o.z = cvt_pk(s[4 * 33], s[5 * 33]); o.w = cvt_pk(s[6 * 33], s[7 * 33]);
;         *(v4u*)(WT + (size_t)(d0 + n) * K + k0 + 8 * c) = o; }
;     asm volatile("s_waitcnt lgkmcnt(0)" ::: "memory");
	ds_write_b32 v63, v80
	v_add_u32_e32 v63, v126, v133
	s_waitcnt vmcnt(30)
	ds_write_b32 v63, v81
	v_add_u32_e32 v63, v126, v134
	s_waitcnt vmcnt(29)
	ds_write_b32 v63, v82
	v_add_u32_e32 v63, v126, v135
	s_waitcnt vmcnt(28)
	ds_write_b32 v63, v83
	v_add_u32_e32 v63, v126, v136
	s_waitcnt vmcnt(27)
	ds_write_b32 v63, v84
	v_add_u32_e32 v63, v126, v137
	s_waitcnt vmcnt(26)
	ds_write_b32 v63, v85
	v_add_u32_e32 v63, v126, v138
	s_waitcnt vmcnt(25)
	ds_write_b32 v63, v86
	v_add_u32_e32 v63, v126, v139
	s_waitcnt vmcnt(24)
	ds_write_b32 v63, v87
	v_add_u32_e32 v63, v126, v140
	s_waitcnt vmcnt(23)
	ds_write_b32 v63, v88
	v_add_u32_e32 v63, v126, v141
	s_waitcnt vmcnt(22)
	ds_write_b32 v63, v89
	v_add_u32_e32 v63, v126, v142
	s_waitcnt vmcnt(21)
	ds_write_b32 v63, v90
	v_add_u32_e32 v63, v126, v143
	s_waitcnt vmcnt(20)
	ds_write_b32 v63, v91
	v_add_u32_e32 v63, v126, v144
	s_waitcnt vmcnt(19)
	ds_write_b32 v63, v92
	v_add_u32_e32 v63, v126, v145
	s_waitcnt vmcnt(18)
	ds_write_b32 v63, v93
	v_add_u32_e32 v63, v126, v146
	s_waitcnt vmcnt(17)
	ds_write_b32 v63, v94
	v_add_u32_e32 v63, v126, v147
	s_waitcnt vmcnt(16)
	ds_write_b32 v63, v95
	v_add_u32_e32 v63, v126, v148
	v_add_u32_e32 v84, s6, v127
	s_lshl_b32 s10, s7, 1
	v_ashrrev_i32_e32 v85, 31, v84
	v_lshl_add_u64 v[82:83], v[4:5], 0, s[10:11]
	s_waitcnt vmcnt(15)
	ds_write_b32 v63, v96
	v_add_u32_e32 v63, v126, v149
	s_waitcnt vmcnt(14)
	ds_write_b32 v63, v97
	v_add_u32_e32 v63, v126, v150
	s_waitcnt vmcnt(13)
	ds_write_b32 v63, v98
	v_add_u32_e32 v63, v126, v151
	s_waitcnt vmcnt(12)
	ds_write_b32 v63, v99
	v_add_u32_e32 v63, v126, v152
	s_waitcnt vmcnt(11)
	ds_write_b32 v63, v100
	v_add_u32_e32 v63, v126, v153
	s_waitcnt vmcnt(10)
	ds_write_b32 v63, v101
	v_add_u32_e32 v63, v126, v154
	s_waitcnt vmcnt(9)
	ds_write_b32 v63, v78
	v_add_u32_e32 v63, v126, v155
	s_waitcnt vmcnt(8)
	ds_write_b32 v63, v76
	v_add_u32_e32 v63, v126, v156
	v_lshlrev_b64 v[84:85], 11, v[84:85]
	v_lshl_add_u64 v[84:85], v[82:83], 0, v[84:85]
	s_waitcnt vmcnt(7)
	ds_write_b32 v63, v77
	v_add_u32_e32 v63, v126, v157
	s_waitcnt vmcnt(6)
	ds_write_b32 v63, v79
	v_add_u32_e32 v63, v126, v158
	s_waitcnt vmcnt(5)
	ds_write_b32 v63, v70
	v_add_u32_e32 v63, v126, v159
	s_waitcnt vmcnt(4)
	ds_write_b32 v63, v68
	v_add_u32_e32 v63, v126, v160
	s_waitcnt vmcnt(3)
	ds_write_b32 v63, v69
	v_add_u32_e32 v63, v126, v161
	s_waitcnt vmcnt(2)
	ds_write_b32 v63, v71
	v_add_u32_e32 v63, v126, v162
	s_waitcnt vmcnt(1)
	ds_write_b32 v63, v66
	v_add_u32_e32 v63, v126, v163
	s_waitcnt vmcnt(0)
	ds_write_b32 v63, v62
	s_waitcnt lgkmcnt(0)
	ds_read2_b32 v[66:67], v128 offset0:33 offset1:41
	ds_read2_b32 v[68:69], v128 offset1:8
	ds_read2_b32 v[70:71], v128 offset0:66 offset1:74
	ds_read2_b32 v[72:73], v128 offset0:99 offset1:107
	ds_read2_b32 v[74:75], v128 offset0:132 offset1:140
	ds_read2_b32 v[76:77], v128 offset0:165 offset1:173
	ds_read2_b32 v[78:79], v128 offset0:198 offset1:206
	ds_read2_b32 v[80:81], v128 offset0:231 offset1:239
	s_waitcnt lgkmcnt(6)
	v_cvt_pk_bf16_f32 v62, v68, v66
	v_add_u32_e32 v66, s6, v129
	s_waitcnt lgkmcnt(4)
	v_cvt_pk_bf16_f32 v63, v70, v72
	s_waitcnt lgkmcnt(2)
	v_cvt_pk_bf16_f32 v64, v74, v76
	s_waitcnt lgkmcnt(0)
	v_cvt_pk_bf16_f32 v65, v78, v80
	global_store_dwordx4 v[84:85], v[62:65], off sc1
	s_nop 1
	v_cvt_pk_bf16_f32 v62, v69, v67
	v_ashrrev_i32_e32 v67, 31, v66
	v_lshlrev_b64 v[66:67], 11, v[66:67]
	v_cvt_pk_bf16_f32 v63, v71, v73
	v_cvt_pk_bf16_f32 v64, v75, v77
	v_cvt_pk_bf16_f32 v65, v79, v81
	v_lshl_add_u64 v[66:67], v[82:83], 0, v[66:67]
	ds_read2_b32 v[68:69], v128 offset0:16 offset1:24
	ds_read2_b32 v[70:71], v128 offset0:49 offset1:57
	ds_read2_b32 v[72:73], v128 offset0:82 offset1:90
	ds_read2_b32 v[74:75], v128 offset0:115 offset1:123
	ds_read2_b32 v[76:77], v128 offset0:148 offset1:156
	ds_read2_b32 v[78:79], v128 offset0:181 offset1:189
	ds_read2_b32 v[80:81], v128 offset0:214 offset1:222
	ds_read2_b32 v[84:85], v128 offset0:247 offset1:255
	global_store_dwordx4 v[66:67], v[62:65], off sc1
	v_add_u32_e32 v66, s6, v130
	v_ashrrev_i32_e32 v67, 31, v66
	v_lshlrev_b64 v[66:67], 11, v[66:67]
	v_lshl_add_u64 v[66:67], v[82:83], 0, v[66:67]
	s_waitcnt lgkmcnt(6)
	v_cvt_pk_bf16_f32 v62, v68, v70
	s_waitcnt lgkmcnt(4)
	v_cvt_pk_bf16_f32 v63, v72, v74
	s_waitcnt lgkmcnt(2)
	v_cvt_pk_bf16_f32 v64, v76, v78
	s_waitcnt lgkmcnt(0)
	v_cvt_pk_bf16_f32 v65, v80, v84
	global_store_dwordx4 v[66:67], v[62:65], off sc1
	v_add_u32_e32 v66, s6, v131
	v_ashrrev_i32_e32 v67, 31, v66
	v_lshlrev_b64 v[66:67], 11, v[66:67]
	v_lshl_add_u64 v[66:67], v[82:83], 0, v[66:67]
	v_cvt_pk_bf16_f32 v62, v69, v71
	v_cvt_pk_bf16_f32 v63, v73, v75
	v_cvt_pk_bf16_f32 v64, v77, v79
	v_cvt_pk_bf16_f32 v65, v81, v85
	global_store_dwordx4 v[66:67], v[62:65], off sc1
	s_waitcnt lgkmcnt(0)
	s_mov_b64 s[6:7], 0
; template <bool GU>
; __device__ __forceinline__ void transpose_item(const float* W, int K, int N, bf16* WT, const float* gs, LAS float* scr, int item, int lane) {
;     const int nblk = N / 32, kb = item / nblk, nb = item % nblk, k0 = 64 * kb, n0 = 32 * nb;
; #pragma unroll 16
;     for (int i = 0; i < 32; ++i) { const int kk = 2 * i + (lane >> 5); float w = W[(size_t)(k0 + kk) * N + n0 + (lane & 31)]; if (gs) w *= gs[k0 + kk]; scr[kk * 33 + (lane & 31)] = w; }
; __device__ __forceinline__ void conv_weights(LAS unsigned char* lds, unsigned char* ws, const PIn& I, const int l, const int wave, const int lane, const int gw, const int NGW, const int r_lo, const int r_hi) {
;     ...
;         if (r < I_PP) { transpose_item<false>(I.w_pp + (size_t)l * DPLE * DM, DPLE, DM, (bf16*)(wb + W_PP), nullptr, scr, r, lane); continue; } r -= I_PP;
.LBB0_712:
	s_andn2_b64 vcc, exec, s[6:7]
	s_cbranch_vccnz .LBB0_714
	s_and_b32 s7, s40, 0x1c0
	s_lshl_b32 s6, s0, 5
	s_and_b32 s6, s6, 0x3e0
	v_add_u32_e32 v66, s7, v0
	s_lshl_b32 s10, s6, 2
	v_add_u32_e32 v64, s7, v1
	v_ashrrev_i32_e32 v67, 31, v66
	v_add_u32_e32 v68, s7, v27
	v_add_u32_e32 v70, s7, v26
	v_add_u32_e32 v72, s7, v29
	v_add_u32_e32 v74, s7, v28
	v_add_u32_e32 v76, s7, v31
	v_add_u32_e32 v78, s7, v30
	v_lshl_add_u64 v[62:63], v[18:19], 0, s[10:11]
	v_ashrrev_i32_e32 v65, 31, v64
	v_lshlrev_b64 v[66:67], 12, v[66:67]
	v_ashrrev_i32_e32 v71, 31, v70
	v_ashrrev_i32_e32 v69, 31, v68
	v_ashrrev_i32_e32 v75, 31, v74
	v_ashrrev_i32_e32 v73, 31, v72
	v_ashrrev_i32_e32 v79, 31, v78
	v_ashrrev_i32_e32 v77, 31, v76
	v_lshlrev_b64 v[64:65], 12, v[64:65]
	v_lshl_add_u64 v[66:67], v[62:63], 0, v[66:67]
	v_lshlrev_b64 v[68:69], 12, v[68:69]
	v_lshlrev_b64 v[70:71], 12, v[70:71]
	v_lshlrev_b64 v[72:73], 12, v[72:73]
	v_lshlrev_b64 v[74:75], 12, v[74:75]
	v_lshlrev_b64 v[76:77], 12, v[76:77]
	v_lshlrev_b64 v[78:79], 12, v[78:79]
	v_lshl_add_u64 v[64:65], v[62:63], 0, v[64:65]
	v_lshl_add_u64 v[70:71], v[62:63], 0, v[70:71]
	v_lshl_add_u64 v[68:69], v[62:63], 0, v[68:69]
	v_lshl_add_u64 v[74:75], v[62:63], 0, v[74:75]
	v_lshl_add_u64 v[72:73], v[62:63], 0, v[72:73]
	v_lshl_add_u64 v[78:79], v[62:63], 0, v[78:79]
	v_lshl_add_u64 v[76:77], v[62:63], 0, v[76:77]
	global_load_dword v80, v[66:67], off nt
	global_load_dword v81, v[64:65], off nt
	global_load_dword v82, v[70:71], off nt
	global_load_dword v83, v[68:69], off nt
	global_load_dword v84, v[74:75], off nt
	global_load_dword v85, v[72:73], off nt
	global_load_dword v86, v[78:79], off nt
	global_load_dword v87, v[76:77], off nt
	v_add_u32_e32 v66, s7, v32
	v_add_u32_e32 v64, s7, v33
	v_ashrrev_i32_e32 v67, 31, v66
	v_add_u32_e32 v68, s7, v35
	v_add_u32_e32 v70, s7, v34
	v_add_u32_e32 v72, s7, v37
	v_add_u32_e32 v74, s7, v36
	v_add_u32_e32 v76, s7, v39
	v_add_u32_e32 v78, s7, v38
	v_ashrrev_i32_e32 v65, 31, v64
	v_lshlrev_b64 v[66:67], 12, v[66:67]
	v_ashrrev_i32_e32 v71, 31, v70
	v_ashrrev_i32_e32 v69, 31, v68
	v_ashrrev_i32_e32 v75, 31, v74
	v_ashrrev_i32_e32 v73, 31, v72
	v_ashrrev_i32_e32 v79, 31, v78
	v_ashrrev_i32_e32 v77, 31, v76
	v_lshlrev_b64 v[64:65], 12, v[64:65]
	v_lshl_add_u64 v[66:67], v[62:63], 0, v[66:67]
	v_lshlrev_b64 v[68:69], 12, v[68:69]
	v_lshlrev_b64 v[70:71], 12, v[70:71]
	v_lshlrev_b64 v[72:73], 12, v[72:73]
	v_lshlrev_b64 v[74:75], 12, v[74:75]
	v_lshlrev_b64 v[76:77], 12, v[76:77]
	v_lshlrev_b64 v[78:79], 12, v[78:79]
	v_lshl_add_u64 v[64:65], v[62:63], 0, v[64:65]
	v_lshl_add_u64 v[70:71], v[62:63], 0, v[70:71]
	v_lshl_add_u64 v[68:69], v[62:63], 0, v[68:69]
	v_lshl_add_u64 v[74:75], v[62:63], 0, v[74:75]
	v_lshl_add_u64 v[72:73], v[62:63], 0, v[72:73]
	v_lshl_add_u64 v[78:79], v[62:63], 0, v[78:79]
	v_lshl_add_u64 v[76:77], v[62:63], 0, v[76:77]
	global_load_dword v88, v[66:67], off nt
	global_load_dword v89, v[64:65], off nt
	global_load_dword v90, v[70:71], off nt
	global_load_dword v91, v[68:69], off nt
	global_load_dword v92, v[74:75], off nt
	global_load_dword v93, v[72:73], off nt
	global_load_dword v94, v[78:79], off nt
	global_load_dword v95, v[76:77], off nt
	v_add_u32_e32 v66, s7, v40
	v_add_u32_e32 v68, s7, v43
	v_add_u32_e32 v70, s7, v42
	v_add_u32_e32 v76, s7, v47
	v_add_u32_e32 v78, s7, v46
	v_add_u32_e32 v64, s7, v41
	v_ashrrev_i32_e32 v67, 31, v66
	v_ashrrev_i32_e32 v71, 31, v70
	v_ashrrev_i32_e32 v69, 31, v68
	v_add_u32_e32 v72, s7, v45
	v_add_u32_e32 v74, s7, v44
	v_ashrrev_i32_e32 v79, 31, v78
	v_ashrrev_i32_e32 v77, 31, v76
	v_ashrrev_i32_e32 v65, 31, v64
	v_lshlrev_b64 v[66:67], 12, v[66:67]
	v_lshlrev_b64 v[68:69], 12, v[68:69]
	v_lshlrev_b64 v[70:71], 12, v[70:71]
	v_ashrrev_i32_e32 v75, 31, v74
	v_ashrrev_i32_e32 v73, 31, v72
	v_lshlrev_b64 v[76:77], 12, v[76:77]
	v_lshlrev_b64 v[78:79], 12, v[78:79]
	v_lshlrev_b64 v[64:65], 12, v[64:65]
	v_lshl_add_u64 v[66:67], v[62:63], 0, v[66:67]
	v_lshl_add_u64 v[70:71], v[62:63], 0, v[70:71]
	v_lshl_add_u64 v[68:69], v[62:63], 0, v[68:69]
	v_lshlrev_b64 v[72:73], 12, v[72:73]
	v_lshlrev_b64 v[74:75], 12, v[74:75]
	v_lshl_add_u64 v[78:79], v[62:63], 0, v[78:79]
	v_lshl_add_u64 v[76:77], v[62:63], 0, v[76:77]
	v_lshl_add_u64 v[64:65], v[62:63], 0, v[64:65]
	v_lshl_add_u64 v[74:75], v[62:63], 0, v[74:75]
	v_lshl_add_u64 v[72:73], v[62:63], 0, v[72:73]
	global_load_dword v96, v[66:67], off nt
	global_load_dword v97, v[64:65], off nt
	global_load_dword v98, v[70:71], off nt
	global_load_dword v99, v[68:69], off nt
	global_load_dword v100, v[74:75], off nt
	global_load_dword v101, v[72:73], off nt
	s_nop 0
	global_load_dword v78, v[78:79], off nt
	s_nop 0
	global_load_dword v76, v[76:77], off nt
	v_add_u32_e32 v66, s7, v48
	v_add_u32_e32 v68, s7, v51
	v_add_u32_e32 v70, s7, v50
	v_add_u32_e32 v64, s7, v49
	v_ashrrev_i32_e32 v67, 31, v66
	v_ashrrev_i32_e32 v71, 31, v70
	v_ashrrev_i32_e32 v69, 31, v68
	v_add_u32_e32 v72, s7, v53
	v_add_u32_e32 v74, s7, v52
	v_ashrrev_i32_e32 v65, 31, v64
	v_lshlrev_b64 v[66:67], 12, v[66:67]
	v_lshlrev_b64 v[68:69], 12, v[68:69]
	v_lshlrev_b64 v[70:71], 12, v[70:71]
	v_ashrrev_i32_e32 v75, 31, v74
	v_ashrrev_i32_e32 v73, 31, v72
	v_lshlrev_b64 v[64:65], 12, v[64:65]
	v_lshl_add_u64 v[66:67], v[62:63], 0, v[66:67]
	v_lshl_add_u64 v[70:71], v[62:63], 0, v[70:71]
	v_lshl_add_u64 v[68:69], v[62:63], 0, v[68:69]
	v_lshlrev_b64 v[72:73], 12, v[72:73]
	v_lshlrev_b64 v[74:75], 12, v[74:75]
	v_lshl_add_u64 v[64:65], v[62:63], 0, v[64:65]
	v_lshl_add_u64 v[74:75], v[62:63], 0, v[74:75]
	v_lshl_add_u64 v[72:73], v[62:63], 0, v[72:73]
	global_load_dword v77, v[66:67], off nt
	global_load_dword v79, v[64:65], off nt
	s_nop 0
	global_load_dword v70, v[70:71], off nt
	s_nop 0
	global_load_dword v68, v[68:69], off nt
	s_nop 0
	global_load_dword v69, v[74:75], off nt
	global_load_dword v71, v[72:73], off nt
	v_add_u32_e32 v66, s7, v54
	v_add_u32_e32 v64, s7, v55
	v_ashrrev_i32_e32 v67, 31, v66
	v_ashrrev_i32_e32 v65, 31, v64
	v_lshlrev_b64 v[66:67], 12, v[66:67]
	v_lshlrev_b64 v[64:65], 12, v[64:65]
	v_lshl_add_u64 v[66:67], v[62:63], 0, v[66:67]
	global_load_dword v66, v[66:67], off nt
	v_lshl_add_u64 v[62:63], v[62:63], 0, v[64:65]
	global_load_dword v62, v[62:63], off nt
	v_add_u32_e32 v63, v126, v132
	s_waitcnt vmcnt(31)
; #define LAS __attribute__((address_space(3)))
; __device__ __forceinline__ unsigned cvt_pk(float lo, float hi) { unsigned r; asm("v_cvt_pk_bf16_f32 %0, %1, %2" : "=v"(r) : "v"(lo), "v"(hi)); return r; }
; template <bool GU>
; __device__ __forceinline__ void transpose_item(const float* W, int K, int N, bf16* WT, const float* gs, LAS float* scr, int item, int lane) {
;     ...
;     for (int i = 0; i < 32; ++i) { const int kk = 2 * i + (lane >> 5); float w = W[(size_t)(k0 + kk) * N + n0 + (lane & 31)]; if (gs) w *= gs[k0 + kk]; scr[kk * 33 + (lane & 31)] = w; }
;     asm volatile("s_waitcnt lgkmcnt(0)" ::: "memory");
;     int d0 = n0;
;     if (GU) { const int f = (n0 < FF) ? n0 : n0 - FF; d0 = 256 * (f >> 7) + (f & 127) + ((n0 < FF) ? 0 : 128); }
;     const int c = lane & 7;
; #pragma unroll
;     for (int j = 0; j < 4; ++j) { const int n = (lane >> 3) + 8 * j; const LAS float* s = scr + (8 * c) * 33 + n;
;         v4u o; o.x = cvt_pk(s[0 * 33], s[1 * 33]); o.y = cvt_pk(s[2 * 33], s[3 * 33]); o.z = cvt_pk(s[4 * 33], s[5 * 33]); o.w = cvt_pk(s[6 * 33], s[7 * 33]);
;         *(v4u*)(WT + (size_t)(d0 + n) * K + k0 + 8 * c) = o; }
;     asm volatile("s_waitcnt lgkmcnt(0)" ::: "memory");
	ds_write_b32 v63, v80
	v_add_u32_e32 v63, v126, v133
	s_waitcnt vmcnt(30)
	ds_write_b32 v63, v81
	v_add_u32_e32 v63, v126, v134
	s_waitcnt vmcnt(29)
	ds_write_b32 v63, v82
	v_add_u32_e32 v63, v126, v135
	s_waitcnt vmcnt(28)
	ds_write_b32 v63, v83
	v_add_u32_e32 v63, v126, v136
	s_waitcnt vmcnt(27)
	ds_write_b32 v63, v84
	v_add_u32_e32 v63, v126, v137
	s_waitcnt vmcnt(26)
	ds_write_b32 v63, v85
	v_add_u32_e32 v63, v126, v138
	s_waitcnt vmcnt(25)
	ds_write_b32 v63, v86
	v_add_u32_e32 v63, v126, v139
	s_waitcnt vmcnt(24)
	ds_write_b32 v63, v87
	v_add_u32_e32 v63, v126, v140
	s_waitcnt vmcnt(23)
	ds_write_b32 v63, v88
	v_add_u32_e32 v63, v126, v141
	s_waitcnt vmcnt(22)
	ds_write_b32 v63, v89
	v_add_u32_e32 v63, v126, v142
	s_waitcnt vmcnt(21)
	ds_write_b32 v63, v90
	v_add_u32_e32 v63, v126, v143
	s_waitcnt vmcnt(20)
	ds_write_b32 v63, v91
	v_add_u32_e32 v63, v126, v144
	s_waitcnt vmcnt(19)
	ds_write_b32 v63, v92
	v_add_u32_e32 v63, v126, v145
	s_waitcnt vmcnt(18)
	ds_write_b32 v63, v93
	v_add_u32_e32 v63, v126, v146
	s_waitcnt vmcnt(17)
	ds_write_b32 v63, v94
	v_add_u32_e32 v63, v126, v147
	s_waitcnt vmcnt(16)
	ds_write_b32 v63, v95
	v_add_u32_e32 v63, v126, v148
	v_add_u32_e32 v84, s6, v127
	s_lshl_b32 s10, s7, 1
	v_ashrrev_i32_e32 v85, 31, v84
	v_lshl_add_u64 v[82:83], v[6:7], 0, s[10:11]
	s_waitcnt vmcnt(15)
	ds_write_b32 v63, v96
	v_add_u32_e32 v63, v126, v149
	s_waitcnt vmcnt(14)
	ds_write_b32 v63, v97
	v_add_u32_e32 v63, v126, v150
	s_waitcnt vmcnt(13)
	ds_write_b32 v63, v98
	v_add_u32_e32 v63, v126, v151
	s_waitcnt vmcnt(12)
	ds_write_b32 v63, v99
	v_add_u32_e32 v63, v126, v152
	s_waitcnt vmcnt(11)
	ds_write_b32 v63, v100
	v_add_u32_e32 v63, v126, v153
	s_waitcnt vmcnt(10)
	ds_write_b32 v63, v101
	v_add_u32_e32 v63, v126, v154
	s_waitcnt vmcnt(9)
	ds_write_b32 v63, v78
	v_add_u32_e32 v63, v126, v155
	s_waitcnt vmcnt(8)
	ds_write_b32 v63, v76
	v_add_u32_e32 v63, v126, v156
	v_lshlrev_b64 v[84:85], 9, v[84:85]
	v_lshl_add_u64 v[84:85], v[82:83], 0, v[84:85]
	s_waitcnt vmcnt(7)
	ds_write_b32 v63, v77
	v_add_u32_e32 v63, v126, v157
	s_waitcnt vmcnt(6)
	ds_write_b32 v63, v79
	v_add_u32_e32 v63, v126, v158
	s_waitcnt vmcnt(5)
	ds_write_b32 v63, v70
	v_add_u32_e32 v63, v126, v159
	s_waitcnt vmcnt(4)
	ds_write_b32 v63, v68
	v_add_u32_e32 v63, v126, v160
	s_waitcnt vmcnt(3)
	ds_write_b32 v63, v69
	v_add_u32_e32 v63, v126, v161
	s_waitcnt vmcnt(2)
	ds_write_b32 v63, v71
	v_add_u32_e32 v63, v126, v162
	s_waitcnt vmcnt(1)
	ds_write_b32 v63, v66
	v_add_u32_e32 v63, v126, v163
	s_waitcnt vmcnt(0)
	ds_write_b32 v63, v62
	s_waitcnt lgkmcnt(0)
	ds_read2_b32 v[66:67], v128 offset0:33 offset1:41
	ds_read2_b32 v[68:69], v128 offset1:8
	ds_read2_b32 v[70:71], v128 offset0:66 offset1:74
	ds_read2_b32 v[72:73], v128 offset0:99 offset1:107
	ds_read2_b32 v[74:75], v128 offset0:132 offset1:140
	ds_read2_b32 v[76:77], v128 offset0:165 offset1:173
	ds_read2_b32 v[78:79], v128 offset0:198 offset1:206
	ds_read2_b32 v[80:81], v128 offset0:231 offset1:239
	s_waitcnt lgkmcnt(6)
	v_cvt_pk_bf16_f32 v62, v68, v66
	v_add_u32_e32 v66, s6, v129
	s_waitcnt lgkmcnt(4)
	v_cvt_pk_bf16_f32 v63, v70, v72
	s_waitcnt lgkmcnt(2)
	v_cvt_pk_bf16_f32 v64, v74, v76
	s_waitcnt lgkmcnt(0)
	v_cvt_pk_bf16_f32 v65, v78, v80
	global_store_dwordx4 v[84:85], v[62:65], off sc1
	s_nop 1
	v_cvt_pk_bf16_f32 v62, v69, v67
	v_ashrrev_i32_e32 v67, 31, v66
	v_lshlrev_b64 v[66:67], 9, v[66:67]
	v_cvt_pk_bf16_f32 v63, v71, v73
	v_cvt_pk_bf16_f32 v64, v75, v77
	v_cvt_pk_bf16_f32 v65, v79, v81
	v_lshl_add_u64 v[66:67], v[82:83], 0, v[66:67]
	ds_read2_b32 v[68:69], v128 offset0:16 offset1:24
	ds_read2_b32 v[70:71], v128 offset0:49 offset1:57
	ds_read2_b32 v[72:73], v128 offset0:82 offset1:90
	ds_read2_b32 v[74:75], v128 offset0:115 offset1:123
	ds_read2_b32 v[76:77], v128 offset0:148 offset1:156
	ds_read2_b32 v[78:79], v128 offset0:181 offset1:189
	ds_read2_b32 v[80:81], v128 offset0:214 offset1:222
	ds_read2_b32 v[84:85], v128 offset0:247 offset1:255
	global_store_dwordx4 v[66:67], v[62:65], off sc1
	v_add_u32_e32 v66, s6, v130
	v_ashrrev_i32_e32 v67, 31, v66
	v_lshlrev_b64 v[66:67], 9, v[66:67]
	v_lshl_add_u64 v[66:67], v[82:83], 0, v[66:67]
	s_waitcnt lgkmcnt(6)
	v_cvt_pk_bf16_f32 v62, v68, v70
	s_waitcnt lgkmcnt(4)
	v_cvt_pk_bf16_f32 v63, v72, v74
	s_waitcnt lgkmcnt(2)
	v_cvt_pk_bf16_f32 v64, v76, v78
	s_waitcnt lgkmcnt(0)
	v_cvt_pk_bf16_f32 v65, v80, v84
	global_store_dwordx4 v[66:67], v[62:65], off sc1
	v_add_u32_e32 v66, s6, v131
	v_ashrrev_i32_e32 v67, 31, v66
	v_lshlrev_b64 v[66:67], 9, v[66:67]
	v_lshl_add_u64 v[66:67], v[82:83], 0, v[66:67]
	v_cvt_pk_bf16_f32 v62, v69, v71
	v_cvt_pk_bf16_f32 v63, v73, v75
	v_cvt_pk_bf16_f32 v64, v77, v79
	v_cvt_pk_bf16_f32 v65, v81, v85
	global_store_dwordx4 v[66:67], v[62:65], off sc1
	s_waitcnt lgkmcnt(0)

; template <bool GU>
; __device__ __forceinline__ void transpose_item(const float* W, int K, int N, bf16* WT, const float* gs, LAS float* scr, int item, int lane) {
;     const int nblk = N / 32, kb = item / nblk, nb = item % nblk, k0 = 64 * kb, n0 = 32 * nb;
; #pragma unroll 16
;     for (int i = 0; i < 32; ++i) { const int kk = 2 * i + (lane >> 5); float w = W[(size_t)(k0 + kk) * N + n0 + (lane & 31)]; if (gs) w *= gs[k0 + kk]; scr[kk * 33 + (lane & 31)] = w; }
; __device__ __forceinline__ void conv_weights(LAS unsigned char* lds, unsigned char* ws, const PIn& I, const int l, const int wave, const int lane, const int gw, const int NGW, const int r_lo, const int r_hi) {
;     ...
;         if (r < I_D) { transpose_item<false>(I.w_d + (size_t)l * FF * DM, FF, DM, (bf16*)(wb + W_D), nullptr, scr, r, lane); continue; } r -= I_D;
.LBB0_715:
	s_andn2_b64 vcc, exec, s[6:7]
	s_cbranch_vccnz .LBB0_717
	s_lshl_b32 s6, s0, 1
	s_add_i32 s6, s6, 0x1dd00
	s_and_b32 s7, s6, 0x1ffc0
	s_lshl_b32 s6, s0, 5
	s_and_b32 s6, s6, 0x3e0
	v_add_u32_e32 v66, s7, v0
	s_lshl_b32 s10, s6, 2
	v_add_u32_e32 v64, s7, v1
	v_ashrrev_i32_e32 v67, 31, v66
	v_add_u32_e32 v68, s7, v27
	v_add_u32_e32 v70, s7, v26
	v_add_u32_e32 v72, s7, v29
	v_add_u32_e32 v74, s7, v28
	v_add_u32_e32 v76, s7, v31
	v_add_u32_e32 v78, s7, v30
	v_lshl_add_u64 v[62:63], v[20:21], 0, s[10:11]
	v_ashrrev_i32_e32 v65, 31, v64
	v_lshlrev_b64 v[66:67], 12, v[66:67]
	v_ashrrev_i32_e32 v71, 31, v70
	v_ashrrev_i32_e32 v69, 31, v68
	v_ashrrev_i32_e32 v75, 31, v74
	v_ashrrev_i32_e32 v73, 31, v72
	v_ashrrev_i32_e32 v79, 31, v78
	v_ashrrev_i32_e32 v77, 31, v76
	v_lshlrev_b64 v[64:65], 12, v[64:65]
	v_lshl_add_u64 v[66:67], v[62:63], 0, v[66:67]
	v_lshlrev_b64 v[68:69], 12, v[68:69]
	v_lshlrev_b64 v[70:71], 12, v[70:71]
	v_lshlrev_b64 v[72:73], 12, v[72:73]
	v_lshlrev_b64 v[74:75], 12, v[74:75]
	v_lshlrev_b64 v[76:77], 12, v[76:77]
	v_lshlrev_b64 v[78:79], 12, v[78:79]
	v_lshl_add_u64 v[64:65], v[62:63], 0, v[64:65]
	v_lshl_add_u64 v[70:71], v[62:63], 0, v[70:71]
	v_lshl_add_u64 v[68:69], v[62:63], 0, v[68:69]
	v_lshl_add_u64 v[74:75], v[62:63], 0, v[74:75]
	v_lshl_add_u64 v[72:73], v[62:63], 0, v[72:73]
	v_lshl_add_u64 v[78:79], v[62:63], 0, v[78:79]
	v_lshl_add_u64 v[76:77], v[62:63], 0, v[76:77]
	global_load_dword v80, v[66:67], off nt
	global_load_dword v81, v[64:65], off nt
	global_load_dword v82, v[70:71], off nt
	global_load_dword v83, v[68:69], off nt
	global_load_dword v84, v[74:75], off nt
	global_load_dword v85, v[72:73], off nt
	global_load_dword v86, v[78:79], off nt
	global_load_dword v87, v[76:77], off nt
	v_add_u32_e32 v66, s7, v32
	v_add_u32_e32 v64, s7, v33
	v_ashrrev_i32_e32 v67, 31, v66
	v_add_u32_e32 v68, s7, v35
	v_add_u32_e32 v70, s7, v34
	v_add_u32_e32 v72, s7, v37
	v_add_u32_e32 v74, s7, v36
	v_add_u32_e32 v76, s7, v39
	v_add_u32_e32 v78, s7, v38
	v_ashrrev_i32_e32 v65, 31, v64
	v_lshlrev_b64 v[66:67], 12, v[66:67]
	v_ashrrev_i32_e32 v71, 31, v70
	v_ashrrev_i32_e32 v69, 31, v68
	v_ashrrev_i32_e32 v75, 31, v74
	v_ashrrev_i32_e32 v73, 31, v72
	v_ashrrev_i32_e32 v79, 31, v78
	v_ashrrev_i32_e32 v77, 31, v76
	v_lshlrev_b64 v[64:65], 12, v[64:65]
	v_lshl_add_u64 v[66:67], v[62:63], 0, v[66:67]
	v_lshlrev_b64 v[68:69], 12, v[68:69]
	v_lshlrev_b64 v[70:71], 12, v[70:71]
	v_lshlrev_b64 v[72:73], 12, v[72:73]
	v_lshlrev_b64 v[74:75], 12, v[74:75]
	v_lshlrev_b64 v[76:77], 12, v[76:77]
	v_lshlrev_b64 v[78:79], 12, v[78:79]
	v_lshl_add_u64 v[64:65], v[62:63], 0, v[64:65]
	v_lshl_add_u64 v[70:71], v[62:63], 0, v[70:71]
	v_lshl_add_u64 v[68:69], v[62:63], 0, v[68:69]
	v_lshl_add_u64 v[74:75], v[62:63], 0, v[74:75]
	v_lshl_add_u64 v[72:73], v[62:63], 0, v[72:73]
	v_lshl_add_u64 v[78:79], v[62:63], 0, v[78:79]
	v_lshl_add_u64 v[76:77], v[62:63], 0, v[76:77]
	global_load_dword v88, v[66:67], off nt
	global_load_dword v89, v[64:65], off nt
	global_load_dword v90, v[70:71], off nt
	global_load_dword v91, v[68:69], off nt
	global_load_dword v92, v[74:75], off nt
	global_load_dword v93, v[72:73], off nt
	global_load_dword v94, v[78:79], off nt
	global_load_dword v95, v[76:77], off nt
	v_add_u32_e32 v66, s7, v40
	v_add_u32_e32 v68, s7, v43
	v_add_u32_e32 v70, s7, v42
	v_add_u32_e32 v76, s7, v47
	v_add_u32_e32 v78, s7, v46
	v_add_u32_e32 v64, s7, v41
	v_ashrrev_i32_e32 v67, 31, v66
	v_ashrrev_i32_e32 v71, 31, v70
	v_ashrrev_i32_e32 v69, 31, v68
	v_add_u32_e32 v72, s7, v45
	v_add_u32_e32 v74, s7, v44
	v_ashrrev_i32_e32 v79, 31, v78
	v_ashrrev_i32_e32 v77, 31, v76
	v_ashrrev_i32_e32 v65, 31, v64
	v_lshlrev_b64 v[66:67], 12, v[66:67]
	v_lshlrev_b64 v[68:69], 12, v[68:69]
	v_lshlrev_b64 v[70:71], 12, v[70:71]
	v_ashrrev_i32_e32 v75, 31, v74
	v_ashrrev_i32_e32 v73, 31, v72
	v_lshlrev_b64 v[76:77], 12, v[76:77]
	v_lshlrev_b64 v[78:79], 12, v[78:79]
	v_lshlrev_b64 v[64:65], 12, v[64:65]
	v_lshl_add_u64 v[66:67], v[62:63], 0, v[66:67]
	v_lshl_add_u64 v[70:71], v[62:63], 0, v[70:71]
	v_lshl_add_u64 v[68:69], v[62:63], 0, v[68:69]
	v_lshlrev_b64 v[72:73], 12, v[72:73]
	v_lshlrev_b64 v[74:75], 12, v[74:75]
	v_lshl_add_u64 v[78:79], v[62:63], 0, v[78:79]
	v_lshl_add_u64 v[76:77], v[62:63], 0, v[76:77]
	v_lshl_add_u64 v[64:65], v[62:63], 0, v[64:65]
	v_lshl_add_u64 v[74:75], v[62:63], 0, v[74:75]
	v_lshl_add_u64 v[72:73], v[62:63], 0, v[72:73]
	global_load_dword v96, v[66:67], off nt
	global_load_dword v97, v[64:65], off nt
	global_load_dword v98, v[70:71], off nt
	global_load_dword v99, v[68:69], off nt
	global_load_dword v100, v[74:75], off nt
	global_load_dword v101, v[72:73], off nt
	s_nop 0
	global_load_dword v78, v[78:79], off nt
	s_nop 0
	global_load_dword v76, v[76:77], off nt
	v_add_u32_e32 v66, s7, v48
	v_add_u32_e32 v68, s7, v51
	v_add_u32_e32 v70, s7, v50
	v_add_u32_e32 v64, s7, v49
	v_ashrrev_i32_e32 v67, 31, v66
	v_ashrrev_i32_e32 v71, 31, v70
	v_ashrrev_i32_e32 v69, 31, v68
	v_add_u32_e32 v72, s7, v53
	v_add_u32_e32 v74, s7, v52
	v_ashrrev_i32_e32 v65, 31, v64
	v_lshlrev_b64 v[66:67], 12, v[66:67]
	v_lshlrev_b64 v[68:69], 12, v[68:69]
	v_lshlrev_b64 v[70:71], 12, v[70:71]
	v_ashrrev_i32_e32 v75, 31, v74
	v_ashrrev_i32_e32 v73, 31, v72
	v_lshlrev_b64 v[64:65], 12, v[64:65]
	v_lshl_add_u64 v[66:67], v[62:63], 0, v[66:67]
	v_lshl_add_u64 v[70:71], v[62:63], 0, v[70:71]
	v_lshl_add_u64 v[68:69], v[62:63], 0, v[68:69]
	v_lshlrev_b64 v[72:73], 12, v[72:73]
	v_lshlrev_b64 v[74:75], 12, v[74:75]
	v_lshl_add_u64 v[64:65], v[62:63], 0, v[64:65]
	v_lshl_add_u64 v[74:75], v[62:63], 0, v[74:75]
	v_lshl_add_u64 v[72:73], v[62:63], 0, v[72:73]
	global_load_dword v77, v[66:67], off nt
	global_load_dword v79, v[64:65], off nt
	s_nop 0
	global_load_dword v70, v[70:71], off nt
	s_nop 0
	global_load_dword v68, v[68:69], off nt
	s_nop 0
	global_load_dword v69, v[74:75], off nt
	global_load_dword v71, v[72:73], off nt
	v_add_u32_e32 v66, s7, v54
	v_add_u32_e32 v64, s7, v55
	v_ashrrev_i32_e32 v67, 31, v66
	v_ashrrev_i32_e32 v65, 31, v64
	v_lshlrev_b64 v[66:67], 12, v[66:67]
	v_lshlrev_b64 v[64:65], 12, v[64:65]
	v_lshl_add_u64 v[66:67], v[62:63], 0, v[66:67]
	global_load_dword v66, v[66:67], off nt
	v_lshl_add_u64 v[62:63], v[62:63], 0, v[64:65]
	global_load_dword v62, v[62:63], off nt
	v_add_u32_e32 v63, v126, v132
	s_waitcnt vmcnt(31)
; #define LAS __attribute__((address_space(3)))
; __device__ __forceinline__ unsigned cvt_pk(float lo, float hi) { unsigned r; asm("v_cvt_pk_bf16_f32 %0, %1, %2" : "=v"(r) : "v"(lo), "v"(hi)); return r; }
; template <bool GU>
; __device__ __forceinline__ void transpose_item(const float* W, int K, int N, bf16* WT, const float* gs, LAS float* scr, int item, int lane) {
;     ...
;     for (int i = 0; i < 32; ++i) { const int kk = 2 * i + (lane >> 5); float w = W[(size_t)(k0 + kk) * N + n0 + (lane & 31)]; if (gs) w *= gs[k0 + kk]; scr[kk * 33 + (lane & 31)] = w; }
;     asm volatile("s_waitcnt lgkmcnt(0)" ::: "memory");
;     int d0 = n0;
;     if (GU) { const int f = (n0 < FF) ? n0 : n0 - FF; d0 = 256 * (f >> 7) + (f & 127) + ((n0 < FF) ? 0 : 128); }
;     const int c = lane & 7;
; #pragma unroll
;     for (int j = 0; j < 4; ++j) { const int n = (lane >> 3) + 8 * j; const LAS float* s = scr + (8 * c) * 33 + n;
;         v4u o; o.x = cvt_pk(s[0 * 33], s[1 * 33]); o.y = cvt_pk(s[2 * 33], s[3 * 33]); o.z = cvt_pk(s[4 * 33], s[5 * 33]); o.w = cvt_pk(s[6 * 33], s[7 * 33]);
;         *(v4u*)(WT + (size_t)(d0 + n) * K + k0 + 8 * c) = o; }
;     asm volatile("s_waitcnt lgkmcnt(0)" ::: "memory");
	ds_write_b32 v63, v80
	v_add_u32_e32 v63, v126, v133
	s_waitcnt vmcnt(30)
	ds_write_b32 v63, v81
	v_add_u32_e32 v63, v126, v134
	s_waitcnt vmcnt(29)
	ds_write_b32 v63, v82
	v_add_u32_e32 v63, v126, v135
	s_waitcnt vmcnt(28)
	ds_write_b32 v63, v83
	v_add_u32_e32 v63, v126, v136
	s_waitcnt vmcnt(27)
	ds_write_b32 v63, v84
	v_add_u32_e32 v63, v126, v137
	s_waitcnt vmcnt(26)
	ds_write_b32 v63, v85
	v_add_u32_e32 v63, v126, v138
	s_waitcnt vmcnt(25)
	ds_write_b32 v63, v86
	v_add_u32_e32 v63, v126, v139
	s_waitcnt vmcnt(24)
	ds_write_b32 v63, v87
	v_add_u32_e32 v63, v126, v140
	s_waitcnt vmcnt(23)
	ds_write_b32 v63, v88
	v_add_u32_e32 v63, v126, v141
	s_waitcnt vmcnt(22)
	ds_write_b32 v63, v89
	v_add_u32_e32 v63, v126, v142
	s_waitcnt vmcnt(21)
	ds_write_b32 v63, v90
	v_add_u32_e32 v63, v126, v143
	s_waitcnt vmcnt(20)
	ds_write_b32 v63, v91
	v_add_u32_e32 v63, v126, v144
	s_waitcnt vmcnt(19)
	ds_write_b32 v63, v92
	v_add_u32_e32 v63, v126, v145
	s_waitcnt vmcnt(18)
	ds_write_b32 v63, v93
	v_add_u32_e32 v63, v126, v146
	s_waitcnt vmcnt(17)
	ds_write_b32 v63, v94
	v_add_u32_e32 v63, v126, v147
	s_waitcnt vmcnt(16)
	ds_write_b32 v63, v95
	v_add_u32_e32 v63, v126, v148
	s_lshl_b32 s10, s7, 1
	v_lshl_add_u64 v[82:83], v[8:9], 0, s[10:11]
	s_waitcnt vmcnt(15)
	ds_write_b32 v63, v96
	v_add_u32_e32 v63, v126, v149
	s_waitcnt vmcnt(14)
	ds_write_b32 v63, v97
	v_add_u32_e32 v63, v126, v150
	s_waitcnt vmcnt(13)
	ds_write_b32 v63, v98
	v_add_u32_e32 v63, v126, v151
	s_waitcnt vmcnt(12)
	ds_write_b32 v63, v99
	v_add_u32_e32 v63, v126, v152
	s_waitcnt vmcnt(11)
	ds_write_b32 v63, v100
	v_add_u32_e32 v63, v126, v153
	s_waitcnt vmcnt(10)
	ds_write_b32 v63, v101
	v_add_u32_e32 v63, v126, v154
	s_waitcnt vmcnt(9)
	ds_write_b32 v63, v78
	v_add_u32_e32 v63, v126, v155
	s_waitcnt vmcnt(8)
	ds_write_b32 v63, v76
	v_add_u32_e32 v63, v126, v156
	s_waitcnt vmcnt(7)
	ds_write_b32 v63, v77
	v_add_u32_e32 v63, v126, v157
	s_waitcnt vmcnt(6)
	ds_write_b32 v63, v79
	v_add_u32_e32 v63, v126, v158
	s_waitcnt vmcnt(5)
	ds_write_b32 v63, v70
	v_add_u32_e32 v63, v126, v159
	s_waitcnt vmcnt(4)
	ds_write_b32 v63, v68
	v_add_u32_e32 v63, v126, v160
	s_waitcnt vmcnt(3)
	ds_write_b32 v63, v69
	v_add_u32_e32 v63, v126, v161
	s_waitcnt vmcnt(2)
	ds_write_b32 v63, v71
	v_add_u32_e32 v63, v126, v162
	s_waitcnt vmcnt(1)
	ds_write_b32 v63, v66
	v_add_u32_e32 v63, v126, v163
	s_waitcnt vmcnt(0)
	ds_write_b32 v63, v62
	s_waitcnt lgkmcnt(0)
	ds_read2_b32 v[66:67], v128 offset0:33 offset1:41
	ds_read2_b32 v[68:69], v128 offset1:8
	ds_read2_b32 v[70:71], v128 offset0:66 offset1:74
	ds_read2_b32 v[72:73], v128 offset0:99 offset1:107
	ds_read2_b32 v[74:75], v128 offset0:132 offset1:140
	ds_read2_b32 v[76:77], v128 offset0:165 offset1:173
	ds_read2_b32 v[78:79], v128 offset0:198 offset1:206
	ds_read2_b32 v[80:81], v128 offset0:231 offset1:239
	s_waitcnt lgkmcnt(6)
	v_cvt_pk_bf16_f32 v62, v68, v66
	v_add_u32_e32 v66, s6, v127
	v_mad_i64_i32 v[84:85], s[40:41], v66, s19, v[82:83]
	s_waitcnt lgkmcnt(4)
	v_cvt_pk_bf16_f32 v63, v70, v72
	s_waitcnt lgkmcnt(2)
	v_cvt_pk_bf16_f32 v64, v74, v76
	s_waitcnt lgkmcnt(0)
	v_cvt_pk_bf16_f32 v65, v78, v80
	global_store_dwordx4 v[84:85], v[62:65], off sc1
	v_add_u32_e32 v66, s6, v129
	s_nop 0
	v_cvt_pk_bf16_f32 v62, v69, v67
	v_cvt_pk_bf16_f32 v63, v71, v73
	v_cvt_pk_bf16_f32 v64, v75, v77
	v_cvt_pk_bf16_f32 v65, v79, v81
	ds_read2_b32 v[68:69], v128 offset0:16 offset1:24
	ds_read2_b32 v[70:71], v128 offset0:49 offset1:57
	ds_read2_b32 v[72:73], v128 offset0:82 offset1:90
	ds_read2_b32 v[74:75], v128 offset0:115 offset1:123
	ds_read2_b32 v[76:77], v128 offset0:148 offset1:156
	ds_read2_b32 v[78:79], v128 offset0:181 offset1:189
	ds_read2_b32 v[80:81], v128 offset0:214 offset1:222
	ds_read2_b32 v[84:85], v128 offset0:247 offset1:255
	v_mad_i64_i32 v[66:67], s[40:41], v66, s19, v[82:83]
	global_store_dwordx4 v[66:67], v[62:65], off sc1
	v_add_u32_e32 v66, s6, v130
	v_mad_i64_i32 v[66:67], s[40:41], v66, s19, v[82:83]
	s_waitcnt lgkmcnt(6)
	v_cvt_pk_bf16_f32 v62, v68, v70
	s_waitcnt lgkmcnt(4)
	v_cvt_pk_bf16_f32 v63, v72, v74
	s_waitcnt lgkmcnt(2)
	v_cvt_pk_bf16_f32 v64, v76, v78
	s_waitcnt lgkmcnt(0)
	v_cvt_pk_bf16_f32 v65, v80, v84
	global_store_dwordx4 v[66:67], v[62:65], off sc1
	v_add_u32_e32 v66, s6, v131
	v_mad_i64_i32 v[66:67], s[6:7], v66, s19, v[82:83]
	v_cvt_pk_bf16_f32 v62, v69, v71
	v_cvt_pk_bf16_f32 v63, v73, v75
	v_cvt_pk_bf16_f32 v64, v77, v79
	v_cvt_pk_bf16_f32 v65, v81, v85
	global_store_dwordx4 v[66:67], v[62:65], off sc1
	s_waitcnt lgkmcnt(0)

; #define LAS __attribute__((address_space(3)))
; __device__ __forceinline__ unsigned cvt_pk(float lo, float hi) { unsigned r; asm("v_cvt_pk_bf16_f32 %0, %1, %2" : "=v"(r) : "v"(lo), "v"(hi)); return r; }
; template <bool GU>
; __device__ __forceinline__ void transpose_item(const float* W, int K, int N, bf16* WT, const float* gs, LAS float* scr, int item, int lane) {
;     ...
;     int d0 = n0;
;     if (GU) { const int f = (n0 < FF) ? n0 : n0 - FF; d0 = 256 * (f >> 7) + (f & 127) + ((n0 < FF) ? 0 : 128); }
;     const int c = lane & 7;
; #pragma unroll
;     for (int j = 0; j < 4; ++j) { const int n = (lane >> 3) + 8 * j; const LAS float* s = scr + (8 * c) * 33 + n;
;         v4u o; o.x = cvt_pk(s[0 * 33], s[1 * 33]); o.y = cvt_pk(s[2 * 33], s[3 * 33]); o.z = cvt_pk(s[4 * 33], s[5 * 33]); o.w = cvt_pk(s[6 * 33], s[7 * 33]);
;         *(v4u*)(WT + (size_t)(d0 + n) * K + k0 + 8 * c) = o; }
;     asm volatile("s_waitcnt lgkmcnt(0)" ::: "memory");
.LBB0_753:
	s_and_b32 s6, 0xffff, s50
	s_and_b32 s7, 0xffff, s41
	s_add_i32 s10, s6, 0xfffff500
	s_cmpk_lt_u32 s7, 0x58
	s_cselect_b32 s6, s6, s10
	s_cselect_b32 s7, 0, 0x80
	s_lshl_b32 s10, s6, 1
	s_and_b32 s6, s6, 0x60
	s_waitcnt lgkmcnt(0)
	s_and_b32 s10, s10, 0xffffff00
	s_or_b32 s6, s6, s7
	s_or_b32 s6, s6, s10
	ds_read2_b32 v[66:67], v128 offset0:33 offset1:41
	ds_read2_b32 v[68:69], v128 offset1:8
	ds_read2_b32 v[70:71], v128 offset0:66 offset1:74
	ds_read2_b32 v[72:73], v128 offset0:99 offset1:107
	ds_read2_b32 v[74:75], v128 offset0:132 offset1:140
	ds_read2_b32 v[76:77], v128 offset0:165 offset1:173
	ds_read2_b32 v[78:79], v128 offset0:198 offset1:206
	ds_read2_b32 v[80:81], v128 offset0:231 offset1:239
	s_and_b32 s7, 0xffff, s40
	v_add_u32_e32 v84, s6, v127
	s_lshl_b32 s10, s7, 1
	v_ashrrev_i32_e32 v85, 31, v84
	v_lshl_add_u64 v[82:83], v[10:11], 0, s[10:11]
	v_lshlrev_b64 v[84:85], 11, v[84:85]
	s_waitcnt lgkmcnt(6)
	v_cvt_pk_bf16_f32 v62, v68, v66
	v_lshl_add_u64 v[84:85], v[82:83], 0, v[84:85]
	v_add_u32_e32 v66, s6, v129
	s_waitcnt lgkmcnt(4)
	v_cvt_pk_bf16_f32 v63, v70, v72
	s_waitcnt lgkmcnt(2)
	v_cvt_pk_bf16_f32 v64, v74, v76
	s_waitcnt lgkmcnt(0)
	v_cvt_pk_bf16_f32 v65, v78, v80
	global_store_dwordx4 v[84:85], v[62:65], off sc1
	s_nop 1
	v_cvt_pk_bf16_f32 v62, v69, v67
	v_ashrrev_i32_e32 v67, 31, v66
	v_lshlrev_b64 v[66:67], 11, v[66:67]
	v_cvt_pk_bf16_f32 v63, v71, v73
	v_cvt_pk_bf16_f32 v64, v75, v77
	v_cvt_pk_bf16_f32 v65, v79, v81
	v_lshl_add_u64 v[66:67], v[82:83], 0, v[66:67]
	ds_read2_b32 v[68:69], v128 offset0:16 offset1:24
	ds_read2_b32 v[70:71], v128 offset0:49 offset1:57
	ds_read2_b32 v[72:73], v128 offset0:82 offset1:90
	ds_read2_b32 v[74:75], v128 offset0:115 offset1:123
	ds_read2_b32 v[76:77], v128 offset0:148 offset1:156
	ds_read2_b32 v[78:79], v128 offset0:181 offset1:189
	ds_read2_b32 v[80:81], v128 offset0:214 offset1:222
	ds_read2_b32 v[84:85], v128 offset0:247 offset1:255
	global_store_dwordx4 v[66:67], v[62:65], off sc1
	v_add_u32_e32 v66, s6, v130
	v_ashrrev_i32_e32 v67, 31, v66
	v_lshlrev_b64 v[66:67], 11, v[66:67]
	v_lshl_add_u64 v[66:67], v[82:83], 0, v[66:67]
	s_waitcnt lgkmcnt(6)
	v_cvt_pk_bf16_f32 v62, v68, v70
	s_waitcnt lgkmcnt(4)
	v_cvt_pk_bf16_f32 v63, v72, v74
	s_waitcnt lgkmcnt(2)
	v_cvt_pk_bf16_f32 v64, v76, v78
	s_waitcnt lgkmcnt(0)
	v_cvt_pk_bf16_f32 v65, v80, v84
	global_store_dwordx4 v[66:67], v[62:65], off sc1
	v_add_u32_e32 v66, s6, v131
	v_ashrrev_i32_e32 v67, 31, v66
	v_lshlrev_b64 v[66:67], 11, v[66:67]
	v_lshl_add_u64 v[66:67], v[82:83], 0, v[66:67]
	v_cvt_pk_bf16_f32 v62, v69, v71
	v_cvt_pk_bf16_f32 v63, v73, v75
	v_cvt_pk_bf16_f32 v64, v77, v79
	v_cvt_pk_bf16_f32 v65, v81, v85
	global_store_dwordx4 v[66:67], v[62:65], off sc1
	s_waitcnt lgkmcnt(0)

; template <bool GU>
; __device__ __forceinline__ void transpose_item(const float* W, int K, int N, bf16* WT, const float* gs, LAS float* scr, int item, int lane) {
;     const int nblk = N / 32, kb = item / nblk, nb = item % nblk, k0 = 64 * kb, n0 = 32 * nb;
; #pragma unroll 16
;     for (int i = 0; i < 32; ++i) { const int kk = 2 * i + (lane >> 5); float w = W[(size_t)(k0 + kk) * N + n0 + (lane & 31)]; if (gs) w *= gs[k0 + kk]; scr[kk * 33 + (lane & 31)] = w; }
; __device__ __forceinline__ void conv_weights(LAS unsigned char* lds, unsigned char* ws, const PIn& I, const int l, const int wave, const int lane, const int gw, const int NGW, const int r_lo, const int r_hi) {
;     ...
;         if (r < I_OUT) { transpose_item<false>(I.w_out + (size_t)l * DM * DM, DM, DM, (bf16*)(wb + W_OUT), nullptr, scr, r, lane); continue; } r -= I_OUT;
.LBB0_755:
	s_andn2_b64 vcc, exec, s[6:7]
	s_cbranch_vccnz .LBB0_757
	s_lshl_b32 s6, s0, 1
	s_add_i32 s6, s6, 0x1f700
	s_and_b32 s7, s6, 0x1ffc0
	s_lshl_b32 s6, s0, 5
	s_and_b32 s6, s6, 0x3e0
	v_add_u32_e32 v66, s7, v0
	s_lshl_b32 s10, s6, 2
	v_add_u32_e32 v64, s7, v1
	v_ashrrev_i32_e32 v67, 31, v66
	v_add_u32_e32 v68, s7, v27
	v_add_u32_e32 v70, s7, v26
	v_add_u32_e32 v72, s7, v29
	v_add_u32_e32 v74, s7, v28
	v_add_u32_e32 v76, s7, v31
	v_add_u32_e32 v78, s7, v30
	v_lshl_add_u64 v[62:63], v[22:23], 0, s[10:11]
	v_ashrrev_i32_e32 v65, 31, v64
	v_lshlrev_b64 v[66:67], 12, v[66:67]
	v_ashrrev_i32_e32 v71, 31, v70
	v_ashrrev_i32_e32 v69, 31, v68
	v_ashrrev_i32_e32 v75, 31, v74
	v_ashrrev_i32_e32 v73, 31, v72
	v_ashrrev_i32_e32 v79, 31, v78
	v_ashrrev_i32_e32 v77, 31, v76
	v_lshlrev_b64 v[64:65], 12, v[64:65]
	v_lshl_add_u64 v[66:67], v[62:63], 0, v[66:67]
	v_lshlrev_b64 v[68:69], 12, v[68:69]
	v_lshlrev_b64 v[70:71], 12, v[70:71]
	v_lshlrev_b64 v[72:73], 12, v[72:73]
	v_lshlrev_b64 v[74:75], 12, v[74:75]
	v_lshlrev_b64 v[76:77], 12, v[76:77]
	v_lshlrev_b64 v[78:79], 12, v[78:79]
	v_lshl_add_u64 v[64:65], v[62:63], 0, v[64:65]
	v_lshl_add_u64 v[70:71], v[62:63], 0, v[70:71]
	v_lshl_add_u64 v[68:69], v[62:63], 0, v[68:69]
	v_lshl_add_u64 v[74:75], v[62:63], 0, v[74:75]
	v_lshl_add_u64 v[72:73], v[62:63], 0, v[72:73]
	v_lshl_add_u64 v[78:79], v[62:63], 0, v[78:79]
	v_lshl_add_u64 v[76:77], v[62:63], 0, v[76:77]
	global_load_dword v80, v[66:67], off nt
	global_load_dword v81, v[64:65], off nt
	global_load_dword v82, v[70:71], off nt
	global_load_dword v83, v[68:69], off nt
	global_load_dword v84, v[74:75], off nt
	global_load_dword v85, v[72:73], off nt
	global_load_dword v86, v[78:79], off nt
	global_load_dword v87, v[76:77], off nt
	v_add_u32_e32 v66, s7, v32
	v_add_u32_e32 v64, s7, v33
	v_ashrrev_i32_e32 v67, 31, v66
	v_add_u32_e32 v68, s7, v35
	v_add_u32_e32 v70, s7, v34
	v_add_u32_e32 v72, s7, v37
	v_add_u32_e32 v74, s7, v36
	v_add_u32_e32 v76, s7, v39
	v_add_u32_e32 v78, s7, v38
	v_ashrrev_i32_e32 v65, 31, v64
	v_lshlrev_b64 v[66:67], 12, v[66:67]
	v_ashrrev_i32_e32 v71, 31, v70
	v_ashrrev_i32_e32 v69, 31, v68
	v_ashrrev_i32_e32 v75, 31, v74
	v_ashrrev_i32_e32 v73, 31, v72
	v_ashrrev_i32_e32 v79, 31, v78
	v_ashrrev_i32_e32 v77, 31, v76
	v_lshlrev_b64 v[64:65], 12, v[64:65]
	v_lshl_add_u64 v[66:67], v[62:63], 0, v[66:67]
	v_lshlrev_b64 v[68:69], 12, v[68:69]
	v_lshlrev_b64 v[70:71], 12, v[70:71]
	v_lshlrev_b64 v[72:73], 12, v[72:73]
	v_lshlrev_b64 v[74:75], 12, v[74:75]
	v_lshlrev_b64 v[76:77], 12, v[76:77]
	v_lshlrev_b64 v[78:79], 12, v[78:79]
	v_lshl_add_u64 v[64:65], v[62:63], 0, v[64:65]
	v_lshl_add_u64 v[70:71], v[62:63], 0, v[70:71]
	v_lshl_add_u64 v[68:69], v[62:63], 0, v[68:69]
	v_lshl_add_u64 v[74:75], v[62:63], 0, v[74:75]
	v_lshl_add_u64 v[72:73], v[62:63], 0, v[72:73]
	v_lshl_add_u64 v[78:79], v[62:63], 0, v[78:79]
	v_lshl_add_u64 v[76:77], v[62:63], 0, v[76:77]
	global_load_dword v88, v[66:67], off nt
	global_load_dword v89, v[64:65], off nt
	global_load_dword v90, v[70:71], off nt
	global_load_dword v91, v[68:69], off nt
	global_load_dword v92, v[74:75], off nt
	global_load_dword v93, v[72:73], off nt
	global_load_dword v94, v[78:79], off nt
	global_load_dword v95, v[76:77], off nt
	v_add_u32_e32 v66, s7, v40
	v_add_u32_e32 v68, s7, v43
	v_add_u32_e32 v70, s7, v42
	v_add_u32_e32 v76, s7, v47
	v_add_u32_e32 v78, s7, v46
	v_add_u32_e32 v64, s7, v41
	v_ashrrev_i32_e32 v67, 31, v66
	v_ashrrev_i32_e32 v71, 31, v70
	v_ashrrev_i32_e32 v69, 31, v68
	v_add_u32_e32 v72, s7, v45
	v_add_u32_e32 v74, s7, v44
	v_ashrrev_i32_e32 v79, 31, v78
	v_ashrrev_i32_e32 v77, 31, v76
	v_ashrrev_i32_e32 v65, 31, v64
	v_lshlrev_b64 v[66:67], 12, v[66:67]
	v_lshlrev_b64 v[68:69], 12, v[68:69]
	v_lshlrev_b64 v[70:71], 12, v[70:71]
	v_ashrrev_i32_e32 v75, 31, v74
	v_ashrrev_i32_e32 v73, 31, v72
	v_lshlrev_b64 v[76:77], 12, v[76:77]
	v_lshlrev_b64 v[78:79], 12, v[78:79]
	v_lshlrev_b64 v[64:65], 12, v[64:65]
	v_lshl_add_u64 v[66:67], v[62:63], 0, v[66:67]
	v_lshl_add_u64 v[70:71], v[62:63], 0, v[70:71]
	v_lshl_add_u64 v[68:69], v[62:63], 0, v[68:69]
	v_lshlrev_b64 v[72:73], 12, v[72:73]
	v_lshlrev_b64 v[74:75], 12, v[74:75]
	v_lshl_add_u64 v[78:79], v[62:63], 0, v[78:79]
	v_lshl_add_u64 v[76:77], v[62:63], 0, v[76:77]
	v_lshl_add_u64 v[64:65], v[62:63], 0, v[64:65]
	v_lshl_add_u64 v[74:75], v[62:63], 0, v[74:75]
	v_lshl_add_u64 v[72:73], v[62:63], 0, v[72:73]
	global_load_dword v96, v[66:67], off nt
	global_load_dword v97, v[64:65], off nt
	global_load_dword v98, v[70:71], off nt
	global_load_dword v99, v[68:69], off nt
	global_load_dword v100, v[74:75], off nt
	global_load_dword v101, v[72:73], off nt
	s_nop 0
	global_load_dword v78, v[78:79], off nt
	s_nop 0
	global_load_dword v76, v[76:77], off nt
	v_add_u32_e32 v66, s7, v48
	v_add_u32_e32 v68, s7, v51
	v_add_u32_e32 v70, s7, v50
	v_add_u32_e32 v64, s7, v49
	v_ashrrev_i32_e32 v67, 31, v66
	v_ashrrev_i32_e32 v71, 31, v70
	v_ashrrev_i32_e32 v69, 31, v68
	v_add_u32_e32 v72, s7, v53
	v_add_u32_e32 v74, s7, v52
	v_ashrrev_i32_e32 v65, 31, v64
	v_lshlrev_b64 v[66:67], 12, v[66:67]
	v_lshlrev_b64 v[68:69], 12, v[68:69]
	v_lshlrev_b64 v[70:71], 12, v[70:71]
	v_ashrrev_i32_e32 v75, 31, v74
	v_ashrrev_i32_e32 v73, 31, v72
	v_lshlrev_b64 v[64:65], 12, v[64:65]
	v_lshl_add_u64 v[66:67], v[62:63], 0, v[66:67]
	v_lshl_add_u64 v[70:71], v[62:63], 0, v[70:71]
	v_lshl_add_u64 v[68:69], v[62:63], 0, v[68:69]
	v_lshlrev_b64 v[72:73], 12, v[72:73]
	v_lshlrev_b64 v[74:75], 12, v[74:75]
	v_lshl_add_u64 v[64:65], v[62:63], 0, v[64:65]
	v_lshl_add_u64 v[74:75], v[62:63], 0, v[74:75]
	v_lshl_add_u64 v[72:73], v[62:63], 0, v[72:73]
	global_load_dword v77, v[66:67], off nt
	global_load_dword v79, v[64:65], off nt
	s_nop 0
	global_load_dword v70, v[70:71], off nt
	s_nop 0
	global_load_dword v68, v[68:69], off nt
	s_nop 0
	global_load_dword v69, v[74:75], off nt
	global_load_dword v71, v[72:73], off nt
	v_add_u32_e32 v66, s7, v54
	v_add_u32_e32 v64, s7, v55
	v_ashrrev_i32_e32 v67, 31, v66
	v_ashrrev_i32_e32 v65, 31, v64
	v_lshlrev_b64 v[66:67], 12, v[66:67]
	v_lshlrev_b64 v[64:65], 12, v[64:65]
	v_lshl_add_u64 v[66:67], v[62:63], 0, v[66:67]
	global_load_dword v66, v[66:67], off nt
	v_lshl_add_u64 v[62:63], v[62:63], 0, v[64:65]
	global_load_dword v62, v[62:63], off nt
	v_add_u32_e32 v63, v126, v132
	s_waitcnt vmcnt(31)
; #define LAS __attribute__((address_space(3)))
; __device__ __forceinline__ unsigned cvt_pk(float lo, float hi) { unsigned r; asm("v_cvt_pk_bf16_f32 %0, %1, %2" : "=v"(r) : "v"(lo), "v"(hi)); return r; }
; template <bool GU>
; __device__ __forceinline__ void transpose_item(const float* W, int K, int N, bf16* WT, const float* gs, LAS float* scr, int item, int lane) {
;     ...
;     for (int i = 0; i < 32; ++i) { const int kk = 2 * i + (lane >> 5); float w = W[(size_t)(k0 + kk) * N + n0 + (lane & 31)]; if (gs) w *= gs[k0 + kk]; scr[kk * 33 + (lane & 31)] = w; }
;     asm volatile("s_waitcnt lgkmcnt(0)" ::: "memory");
;     int d0 = n0;
;     if (GU) { const int f = (n0 < FF) ? n0 : n0 - FF; d0 = 256 * (f >> 7) + (f & 127) + ((n0 < FF) ? 0 : 128); }
;     const int c = lane & 7;
; #pragma unroll
;     for (int j = 0; j < 4; ++j) { const int n = (lane >> 3) + 8 * j; const LAS float* s = scr + (8 * c) * 33 + n;
;         v4u o; o.x = cvt_pk(s[0 * 33], s[1 * 33]); o.y = cvt_pk(s[2 * 33], s[3 * 33]); o.z = cvt_pk(s[4 * 33], s[5 * 33]); o.w = cvt_pk(s[6 * 33], s[7 * 33]);
;         *(v4u*)(WT + (size_t)(d0 + n) * K + k0 + 8 * c) = o; }
;     asm volatile("s_waitcnt lgkmcnt(0)" ::: "memory");
	ds_write_b32 v63, v80
	v_add_u32_e32 v63, v126, v133
	s_waitcnt vmcnt(30)
	ds_write_b32 v63, v81
	v_add_u32_e32 v63, v126, v134
	s_waitcnt vmcnt(29)
	ds_write_b32 v63, v82
	v_add_u32_e32 v63, v126, v135
	s_waitcnt vmcnt(28)
	ds_write_b32 v63, v83
	v_add_u32_e32 v63, v126, v136
	s_waitcnt vmcnt(27)
	ds_write_b32 v63, v84
	v_add_u32_e32 v63, v126, v137
	s_waitcnt vmcnt(26)
	ds_write_b32 v63, v85
	v_add_u32_e32 v63, v126, v138
	s_waitcnt vmcnt(25)
	ds_write_b32 v63, v86
	v_add_u32_e32 v63, v126, v139
	s_waitcnt vmcnt(24)
	ds_write_b32 v63, v87
	v_add_u32_e32 v63, v126, v140
	s_waitcnt vmcnt(23)
	ds_write_b32 v63, v88
	v_add_u32_e32 v63, v126, v141
	s_waitcnt vmcnt(22)
	ds_write_b32 v63, v89
	v_add_u32_e32 v63, v126, v142
	s_waitcnt vmcnt(21)
	ds_write_b32 v63, v90
	v_add_u32_e32 v63, v126, v143
	s_waitcnt vmcnt(20)
	ds_write_b32 v63, v91
	v_add_u32_e32 v63, v126, v144
	s_waitcnt vmcnt(19)
	ds_write_b32 v63, v92
	v_add_u32_e32 v63, v126, v145
	s_waitcnt vmcnt(18)
	ds_write_b32 v63, v93
	v_add_u32_e32 v63, v126, v146
	s_waitcnt vmcnt(17)
	ds_write_b32 v63, v94
	v_add_u32_e32 v63, v126, v147
	s_waitcnt vmcnt(16)
	ds_write_b32 v63, v95
	v_add_u32_e32 v63, v126, v148
	v_add_u32_e32 v84, s6, v127
	s_lshl_b32 s10, s7, 1
	v_ashrrev_i32_e32 v85, 31, v84
	v_lshl_add_u64 v[82:83], v[12:13], 0, s[10:11]
	s_waitcnt vmcnt(15)
	ds_write_b32 v63, v96
	v_add_u32_e32 v63, v126, v149
	s_waitcnt vmcnt(14)
	ds_write_b32 v63, v97
	v_add_u32_e32 v63, v126, v150
	s_waitcnt vmcnt(13)
	ds_write_b32 v63, v98
	v_add_u32_e32 v63, v126, v151
	s_waitcnt vmcnt(12)
	ds_write_b32 v63, v99
	v_add_u32_e32 v63, v126, v152
	s_waitcnt vmcnt(11)
	ds_write_b32 v63, v100
	v_add_u32_e32 v63, v126, v153
	s_waitcnt vmcnt(10)
	ds_write_b32 v63, v101
	v_add_u32_e32 v63, v126, v154
	s_waitcnt vmcnt(9)
	ds_write_b32 v63, v78
	v_add_u32_e32 v63, v126, v155
	s_waitcnt vmcnt(8)
	ds_write_b32 v63, v76
	v_add_u32_e32 v63, v126, v156
	v_lshlrev_b64 v[84:85], 11, v[84:85]
	v_lshl_add_u64 v[84:85], v[82:83], 0, v[84:85]
	s_waitcnt vmcnt(7)
	ds_write_b32 v63, v77
	v_add_u32_e32 v63, v126, v157
	s_waitcnt vmcnt(6)
	ds_write_b32 v63, v79
	v_add_u32_e32 v63, v126, v158
	s_waitcnt vmcnt(5)
	ds_write_b32 v63, v70
	v_add_u32_e32 v63, v126, v159
	s_waitcnt vmcnt(4)
	ds_write_b32 v63, v68
	v_add_u32_e32 v63, v126, v160
	s_waitcnt vmcnt(3)
	ds_write_b32 v63, v69
	v_add_u32_e32 v63, v126, v161
	s_waitcnt vmcnt(2)
	ds_write_b32 v63, v71
	v_add_u32_e32 v63, v126, v162
	s_waitcnt vmcnt(1)
	ds_write_b32 v63, v66
	v_add_u32_e32 v63, v126, v163
	s_waitcnt vmcnt(0)
	ds_write_b32 v63, v62
	s_waitcnt lgkmcnt(0)
	ds_read2_b32 v[66:67], v128 offset0:33 offset1:41
	ds_read2_b32 v[68:69], v128 offset1:8
	ds_read2_b32 v[70:71], v128 offset0:66 offset1:74
	ds_read2_b32 v[72:73], v128 offset0:99 offset1:107
	ds_read2_b32 v[74:75], v128 offset0:132 offset1:140
	ds_read2_b32 v[76:77], v128 offset0:165 offset1:173
	ds_read2_b32 v[78:79], v128 offset0:198 offset1:206
	ds_read2_b32 v[80:81], v128 offset0:231 offset1:239
	s_waitcnt lgkmcnt(6)
	v_cvt_pk_bf16_f32 v62, v68, v66
	v_add_u32_e32 v66, s6, v129
	s_waitcnt lgkmcnt(4)
	v_cvt_pk_bf16_f32 v63, v70, v72
	s_waitcnt lgkmcnt(2)
	v_cvt_pk_bf16_f32 v64, v74, v76
	s_waitcnt lgkmcnt(0)
	v_cvt_pk_bf16_f32 v65, v78, v80
	global_store_dwordx4 v[84:85], v[62:65], off sc1
	s_nop 1
	v_cvt_pk_bf16_f32 v62, v69, v67
	v_ashrrev_i32_e32 v67, 31, v66
	v_lshlrev_b64 v[66:67], 11, v[66:67]
	v_cvt_pk_bf16_f32 v63, v71, v73
	v_cvt_pk_bf16_f32 v64, v75, v77
	v_cvt_pk_bf16_f32 v65, v79, v81
	v_lshl_add_u64 v[66:67], v[82:83], 0, v[66:67]
	ds_read2_b32 v[68:69], v128 offset0:16 offset1:24
	ds_read2_b32 v[70:71], v128 offset0:49 offset1:57
	ds_read2_b32 v[72:73], v128 offset0:82 offset1:90
	ds_read2_b32 v[74:75], v128 offset0:115 offset1:123
	ds_read2_b32 v[76:77], v128 offset0:148 offset1:156
	ds_read2_b32 v[78:79], v128 offset0:181 offset1:189
	ds_read2_b32 v[80:81], v128 offset0:214 offset1:222
	ds_read2_b32 v[84:85], v128 offset0:247 offset1:255
	global_store_dwordx4 v[66:67], v[62:65], off sc1
	v_add_u32_e32 v66, s6, v130
	v_ashrrev_i32_e32 v67, 31, v66
	v_lshlrev_b64 v[66:67], 11, v[66:67]
	v_lshl_add_u64 v[66:67], v[82:83], 0, v[66:67]
	s_waitcnt lgkmcnt(6)
	v_cvt_pk_bf16_f32 v62, v68, v70
	s_waitcnt lgkmcnt(4)
	v_cvt_pk_bf16_f32 v63, v72, v74
	s_waitcnt lgkmcnt(2)
	v_cvt_pk_bf16_f32 v64, v76, v78
	s_waitcnt lgkmcnt(0)
	v_cvt_pk_bf16_f32 v65, v80, v84
	global_store_dwordx4 v[66:67], v[62:65], off sc1
	v_add_u32_e32 v66, s6, v131
	v_ashrrev_i32_e32 v67, 31, v66
	v_lshlrev_b64 v[66:67], 11, v[66:67]
	v_lshl_add_u64 v[66:67], v[82:83], 0, v[66:67]
	v_cvt_pk_bf16_f32 v62, v69, v71
	v_cvt_pk_bf16_f32 v63, v73, v75
	v_cvt_pk_bf16_f32 v64, v77, v79
	v_cvt_pk_bf16_f32 v65, v81, v85
	global_store_dwordx4 v[66:67], v[62:65], off sc1
	s_waitcnt lgkmcnt(0)

; __device__ __forceinline__ unsigned cvt_pk(float lo, float hi) { unsigned r; asm("v_cvt_pk_bf16_f32 %0, %1, %2" : "=v"(r) : "v"(lo), "v"(hi)); return r; }
;     ...
;     for (size_t i = gtid * 8; i < NA; i += gth * 8) {
;         const size_t gi = (size_t)l * NA + i;
;         const f32x4 a = *(const f32x4*)(I.cak + gi), b = *(const f32x4*)(I.cak + gi + 4), c = *(const f32x4*)(I.cav + gi), d = *(const f32x4*)(I.cav + gi + 4);
;         v4u w; w.x = cvt_pk(a[0], a[1]); w.y = cvt_pk(a[2], a[3]); w.z = cvt_pk(b[0], b[1]); w.w = cvt_pk(b[2], b[3]);
;         *(v4u*)((bf16*)(ws + WS_CKA) + gi) = w;
;         w.x = cvt_pk(c[0], c[1]); w.y = cvt_pk(c[2], c[3]); w.z = cvt_pk(d[0], d[1]); w.w = cvt_pk(d[2], d[3]);
;         *(v4u*)((bf16*)(ws + WS_CVA) + gi) = w;
;         if (((i >> 9) & 511) >= 64) { float* dk = out + O_AKS + gi - 32768; float* dv = out + O_AVS + gi - 32768;
;             *(f32x4*)dk = a; *(f32x4*)(dk + 4) = b; *(f32x4*)dv = c; *(f32x4*)(dv + 4) = d; }
;     }
.LBB0_857:
	v_lshl_add_u64 v[0:1], s[20:21], 0, v[18:19]
	v_lshl_add_u64 v[4:5], v[0:1], 0, s[16:17]
	v_add_co_u32_e32 v0, vcc, 0x1000000, v0
	v_lshl_add_u64 v[12:13], s[22:23], 0, v[18:19]
	s_nop 0
	v_addc_co_u32_e32 v1, vcc, 0, v1, vcc
	v_add_co_u32_e32 v8, vcc, s2, v12
	global_load_dwordx4 v[0:3], v[0:1], off nt
	s_nop 0
	global_load_dwordx4 v[4:7], v[4:5], off offset:16 nt
	v_addc_co_u32_e32 v9, vcc, 0, v13, vcc
	v_lshl_add_u64 v[12:13], v[12:13], 0, s[16:17]
	global_load_dwordx4 v[8:11], v[8:9], off nt
	v_add_co_u32_e32 v32, vcc, s3, v22
	global_load_dwordx4 v[12:15], v[12:13], off offset:16 nt
	v_and_b32_e32 v24, 0x38000, v26
	v_addc_co_u32_e32 v33, vcc, -1, v23, vcc
	v_cmp_ne_u64_e32 vcc, 0, v[24:25]
	s_waitcnt vmcnt(3)
	v_cvt_pk_bf16_f32 v28, v0, v1
	v_cvt_pk_bf16_f32 v29, v2, v3
	s_waitcnt vmcnt(2)
	v_cvt_pk_bf16_f32 v30, v4, v5
	v_cvt_pk_bf16_f32 v31, v6, v7
	global_store_dwordx4 v[32:33], v[28:31], off sc1
	s_waitcnt vmcnt(2)
	s_nop 0
	v_cvt_pk_bf16_f32 v28, v8, v9
	v_cvt_pk_bf16_f32 v29, v10, v11
	s_waitcnt vmcnt(1)
	v_cvt_pk_bf16_f32 v30, v12, v13
	v_cvt_pk_bf16_f32 v31, v14, v15
	global_store_dwordx4 v[22:23], v[28:31], off sc1
	s_and_saveexec_b64 s[38:39], vcc
	s_cbranch_execz .LBB0_856
	v_lshl_add_u64 v[28:29], s[36:37], 0, v[18:19]
	v_add_co_u32_e32 v30, vcc, 0x9c60000, v28
	s_nop 1
	v_addc_co_u32_e32 v31, vcc, 0, v29, vcc
	global_store_dwordx4 v[30:31], v[0:3], off sc1
	global_store_dwordx4 v[30:31], v[4:7], off offset:16 sc1
	s_nop 0
	v_add_co_u32_e32 v0, vcc, 0xbc60000, v28
	s_nop 1
	v_addc_co_u32_e32 v1, vcc, 0, v29, vcc
	global_store_dwordx4 v[0:1], v[8:11], off sc1
	global_store_dwordx4 v[0:1], v[12:15], off offset:16 sc1
	s_branch .LBB0_856

; __device__ __forceinline__ unsigned cvt_pk(float lo, float hi) { unsigned r; asm("v_cvt_pk_bf16_f32 %0, %1, %2" : "=v"(r) : "v"(lo), "v"(hi)); return r; }
;     ...
;     for (size_t i = gtid * 8; i < NB; i += gth * 8) {
;         const size_t gi = (size_t)l * NB + i;
;         const f32x4 a = *(const f32x4*)(I.cbk + gi), b = *(const f32x4*)(I.cbk + gi + 4), c = *(const f32x4*)(I.cbv + gi), d = *(const f32x4*)(I.cbv + gi + 4);
;         v4u w; w.x = cvt_pk(a[0], a[1]); w.y = cvt_pk(a[2], a[3]); w.z = cvt_pk(b[0], b[1]); w.w = cvt_pk(b[2], b[3]);
;         *(v4u*)((bf16*)(ws + WS_CKB) + gi) = w;
;         w.x = cvt_pk(c[0], c[1]); w.y = cvt_pk(c[2], c[3]); w.z = cvt_pk(d[0], d[1]); w.w = cvt_pk(d[2], d[3]);
;         *(v4u*)((bf16*)(ws + WS_CVB) + gi) = w;
;         if (((i >> 7) & 127) >= 64) { float* dk = out + O_BKS + gi - 8192; float* dv = out + O_BVS + gi - 8192;
;             *(f32x4*)dk = a; *(f32x4*)(dk + 4) = b; *(f32x4*)dv = c; *(f32x4*)(dv + 4) = d; }
;     }
.LBB0_862:
	v_lshl_add_u64 v[0:1], s[24:25], 0, v[18:19]
	v_lshl_add_u64 v[4:5], v[0:1], 0, s[14:15]
	v_add_co_u32_e32 v0, vcc, 0x100000, v0
	v_lshl_add_u64 v[12:13], s[26:27], 0, v[18:19]
	s_nop 0
	v_addc_co_u32_e32 v1, vcc, 0, v1, vcc
	v_add_co_u32_e32 v8, vcc, s2, v12
	global_load_dwordx4 v[0:3], v[0:1], off nt
	s_nop 0
	global_load_dwordx4 v[4:7], v[4:5], off offset:16 nt
	v_addc_co_u32_e32 v9, vcc, 0, v13, vcc
	v_lshl_add_u64 v[12:13], v[12:13], 0, s[14:15]
	global_load_dwordx4 v[8:11], v[8:9], off nt
	v_add_co_u32_e32 v26, vcc, s3, v20
	global_load_dwordx4 v[12:15], v[12:13], off offset:16 nt
	v_and_b32_e32 v28, 0x2000, v16
	v_addc_co_u32_e32 v27, vcc, -1, v21, vcc
	v_cmp_ne_u32_e32 vcc, 0, v28
	s_waitcnt vmcnt(3)
	v_cvt_pk_bf16_f32 v22, v0, v1
	v_cvt_pk_bf16_f32 v23, v2, v3
	s_waitcnt vmcnt(2)
	v_cvt_pk_bf16_f32 v24, v4, v5
	v_cvt_pk_bf16_f32 v25, v6, v7
	global_store_dwordx4 v[26:27], v[22:25], off sc1
	s_waitcnt vmcnt(2)
	s_nop 0
	v_cvt_pk_bf16_f32 v22, v8, v9
	v_cvt_pk_bf16_f32 v23, v10, v11
	s_waitcnt vmcnt(1)
	v_cvt_pk_bf16_f32 v24, v12, v13
	v_cvt_pk_bf16_f32 v25, v14, v15
	global_store_dwordx4 v[20:21], v[22:25], off sc1
	s_and_saveexec_b64 s[20:21], vcc
	s_cbranch_execz .LBB0_861
	v_lshl_add_u64 v[22:23], s[46:47], 0, v[18:19]
	v_add_co_u32_e32 v24, vcc, 0xcd78000, v22
	s_nop 1
	v_addc_co_u32_e32 v25, vcc, 0, v23, vcc
	global_store_dwordx4 v[24:25], v[0:3], off sc1
	global_store_dwordx4 v[24:25], v[4:7], off offset:16 sc1
	s_nop 0
	v_add_co_u32_e32 v0, vcc, 0xcf78000, v22
	s_nop 1
	v_addc_co_u32_e32 v1, vcc, 0, v23, vcc
	global_store_dwordx4 v[0:1], v[8:11], off sc1
	global_store_dwordx4 v[0:1], v[12:15], off offset:16 sc1
	s_branch .LBB0_861

; __global__ void __launch_bounds__(NWAVES * 64, 2) mega_fwd(Args args) {
;     ...
;         for (int m = gw; m < MT; m += NGW) {
;             const float rstd = __builtin_amdgcn_rsqf(ssq[m] * (1.0f / DM) + EPS);
;             float* yr = H + (size_t)m * DM;
; #pragma unroll
;             for (int j = 0; j < 2; ++j) {
;                 const v4u w = *(const v4u*)(XB + (size_t)m * DM + j * 512 + lane * 8);
;                 const f32x4 a = (f32x4){bf_lo(w.x), bf_hi(w.x), bf_lo(w.y), bf_hi(w.y)}, b2 = (f32x4){bf_lo(w.z), bf_hi(w.z), bf_lo(w.w), bf_hi(w.w)};
;                 *(f32x4*)(yr + j * 512 + lane * 8) = a * rstd * gf[j][0]; *(f32x4*)(yr + j * 512 + lane * 8 + 4) = b2 * rstd * gf[j][1];
;             }
;         }
.Lfin_np1:
	s_cmp_gt_i32 s34, 0x83ff
	s_cbranch_scc1 .Lfin_tailA
	global_load_dword v35, v20, s[0:1]
	global_load_dwordx4 v[44:47], v[16:17], off nt
	global_load_dwordx4 v[48:51], v[16:17], off offset:1024 nt
	s_waitcnt vmcnt(3)
	v_fmamk_f32 v30, v34, 0x3a800000, v21
	v_rsq_f32_e32 v30, v30
	v_lshlrev_b32_e32 v26, 16, v36
	v_and_b32_e32 v27, 0xffff0000, v36
	v_lshlrev_b32_e32 v22, 16, v37
	v_and_b32_e32 v23, 0xffff0000, v37
	v_lshlrev_b32_e32 v28, 16, v38
	v_and_b32_e32 v29, 0xffff0000, v38
	v_lshlrev_b32_e32 v24, 16, v39
	v_and_b32_e32 v25, 0xffff0000, v39
	v_pk_mul_f32 v[26:27], v[30:31], v[26:27] op_sel_hi:[0,1]
	v_pk_mul_f32 v[22:23], v[30:31], v[22:23] op_sel_hi:[0,1]
	v_pk_mul_f32 v[32:33], v[30:31], v[28:29] op_sel_hi:[0,1]
	v_pk_mul_f32 v[28:29], v[30:31], v[24:25] op_sel_hi:[0,1]
	v_pk_mul_f32 v[24:25], v[2:3], v[22:23]
	v_pk_mul_f32 v[22:23], v[0:1], v[26:27]
	v_pk_mul_f32 v[28:29], v[10:11], v[28:29]
	v_pk_mul_f32 v[26:27], v[8:9], v[32:33]
	global_store_dwordx4 v[18:19], v[22:25], off offset:-2048 sc1
	global_store_dwordx4 v[18:19], v[26:29], off offset:-2032 sc1
	v_lshlrev_b32_e32 v56, 16, v40
	v_and_b32_e32 v57, 0xffff0000, v40
	v_lshlrev_b32_e32 v52, 16, v41
	v_and_b32_e32 v53, 0xffff0000, v41
	v_lshlrev_b32_e32 v58, 16, v42
	v_and_b32_e32 v59, 0xffff0000, v42
	v_lshlrev_b32_e32 v54, 16, v43
	v_and_b32_e32 v55, 0xffff0000, v43
	v_pk_mul_f32 v[56:57], v[30:31], v[56:57] op_sel_hi:[0,1]
	v_pk_mul_f32 v[52:53], v[30:31], v[52:53] op_sel_hi:[0,1]
	v_pk_mul_f32 v[62:63], v[30:31], v[58:59] op_sel_hi:[0,1]
	v_pk_mul_f32 v[58:59], v[30:31], v[54:55] op_sel_hi:[0,1]
	v_pk_mul_f32 v[54:55], v[14:15], v[52:53]
	v_pk_mul_f32 v[52:53], v[12:13], v[56:57]
	v_pk_mul_f32 v[58:59], v[6:7], v[58:59]
	v_pk_mul_f32 v[56:57], v[4:5], v[62:63]
	global_store_dwordx4 v[18:19], v[52:55], off sc1
	global_store_dwordx4 v[18:19], v[56:59], off offset:16 sc1
	v_lshl_add_u64 v[18:19], v[18:19], 0, s[6:7]

; __global__ void __launch_bounds__(NWAVES * 64, 2) mega_fwd(Args args) {
;     ...
;         for (int m = gw; m < MT; m += NGW) {
;             const float rstd = __builtin_amdgcn_rsqf(ssq[m] * (1.0f / DM) + EPS);
;             float* yr = H + (size_t)m * DM;
; #pragma unroll
;             for (int j = 0; j < 2; ++j) {
;                 const v4u w = *(const v4u*)(XB + (size_t)m * DM + j * 512 + lane * 8);
;                 const f32x4 a = (f32x4){bf_lo(w.x), bf_hi(w.x), bf_lo(w.y), bf_hi(w.y)}, b2 = (f32x4){bf_lo(w.z), bf_hi(w.z), bf_lo(w.w), bf_hi(w.w)};
;                 *(f32x4*)(yr + j * 512 + lane * 8) = a * rstd * gf[j][0]; *(f32x4*)(yr + j * 512 + lane * 8 + 4) = b2 * rstd * gf[j][1];
;             }
;         }
.Lfin_np2:
	s_cmp_gt_i32 s34, 0x83ff
	s_cbranch_scc1 .Lfin_tailB
	global_load_dword v34, v20, s[0:1]
	global_load_dwordx4 v[36:39], v[16:17], off nt
	global_load_dwordx4 v[40:43], v[16:17], off offset:1024 nt
	s_waitcnt vmcnt(7)
	v_fmamk_f32 v30, v35, 0x3a800000, v21
	v_rsq_f32_e32 v30, v30
	v_lshlrev_b32_e32 v26, 16, v44
	v_and_b32_e32 v27, 0xffff0000, v44
	v_lshlrev_b32_e32 v22, 16, v45
	v_and_b32_e32 v23, 0xffff0000, v45
	v_lshlrev_b32_e32 v28, 16, v46
	v_and_b32_e32 v29, 0xffff0000, v46
	v_lshlrev_b32_e32 v24, 16, v47
	v_and_b32_e32 v25, 0xffff0000, v47
	v_pk_mul_f32 v[26:27], v[30:31], v[26:27] op_sel_hi:[0,1]
	v_pk_mul_f32 v[22:23], v[30:31], v[22:23] op_sel_hi:[0,1]
	v_pk_mul_f32 v[32:33], v[30:31], v[28:29] op_sel_hi:[0,1]
	v_pk_mul_f32 v[28:29], v[30:31], v[24:25] op_sel_hi:[0,1]
	v_pk_mul_f32 v[24:25], v[2:3], v[22:23]
	v_pk_mul_f32 v[22:23], v[0:1], v[26:27]
	v_pk_mul_f32 v[28:29], v[10:11], v[28:29]
	v_pk_mul_f32 v[26:27], v[8:9], v[32:33]
	global_store_dwordx4 v[18:19], v[22:25], off offset:-2048 sc1
	global_store_dwordx4 v[18:19], v[26:29], off offset:-2032 sc1
	v_lshlrev_b32_e32 v56, 16, v48
	v_and_b32_e32 v57, 0xffff0000, v48
	v_lshlrev_b32_e32 v52, 16, v49
	v_and_b32_e32 v53, 0xffff0000, v49
	v_lshlrev_b32_e32 v58, 16, v50
	v_and_b32_e32 v59, 0xffff0000, v50
	v_lshlrev_b32_e32 v54, 16, v51
	v_and_b32_e32 v55, 0xffff0000, v51
	v_pk_mul_f32 v[56:57], v[30:31], v[56:57] op_sel_hi:[0,1]
	v_pk_mul_f32 v[52:53], v[30:31], v[52:53] op_sel_hi:[0,1]
	v_pk_mul_f32 v[62:63], v[30:31], v[58:59] op_sel_hi:[0,1]
	v_pk_mul_f32 v[58:59], v[30:31], v[54:55] op_sel_hi:[0,1]
	v_pk_mul_f32 v[54:55], v[14:15], v[52:53]
	v_pk_mul_f32 v[52:53], v[12:13], v[56:57]
	v_pk_mul_f32 v[58:59], v[6:7], v[58:59]
	v_pk_mul_f32 v[56:57], v[4:5], v[62:63]
	global_store_dwordx4 v[18:19], v[52:55], off sc1
	global_store_dwordx4 v[18:19], v[56:59], off offset:16 sc1
	v_lshl_add_u64 v[18:19], v[18:19], 0, s[6:7]
	s_add_i32 s34, s34, s12
	s_add_u32 s0, s0, s2
	s_addc_u32 s1, s1, s3
	v_lshl_add_u64 v[16:17], v[16:17], 0, s[4:5]
	s_cmp_lt_u32 s34, 0x8000
	s_cbranch_scc1 .Lfin_np3
	s_cmp_gt_u32 s34, 0x83ff
	s_cbranch_scc1 .Lfin_np3
	s_cmp_lg_u32 s64, 0x100
	s_cbranch_scc1 .Lfin_np3
	v_readlane_b32 s14, v249, 1
	v_readlane_b32 s15, v249, 2
	s_nop 4

; __global__ void __launch_bounds__(NWAVES * 64, 2) mega_fwd(Args args) {
;     ...
;         for (int m = gw; m < MT; m += NGW) {
;             const float rstd = __builtin_amdgcn_rsqf(ssq[m] * (1.0f / DM) + EPS);
;             float* yr = H + (size_t)m * DM;
; #pragma unroll
;             for (int j = 0; j < 2; ++j) {
;                 const v4u w = *(const v4u*)(XB + (size_t)m * DM + j * 512 + lane * 8);
;                 const f32x4 a = (f32x4){bf_lo(w.x), bf_hi(w.x), bf_lo(w.y), bf_hi(w.y)}, b2 = (f32x4){bf_lo(w.z), bf_hi(w.z), bf_lo(w.w), bf_hi(w.w)};
;                 *(f32x4*)(yr + j * 512 + lane * 8) = a * rstd * gf[j][0]; *(f32x4*)(yr + j * 512 + lane * 8 + 4) = b2 * rstd * gf[j][1];
;             }
;         }
.Lfin_np3:
	s_cmp_gt_i32 s34, 0x83ff
	s_cbranch_scc1 .Lfin_tailA
	global_load_dword v35, v20, s[0:1]
	global_load_dwordx4 v[44:47], v[16:17], off nt
	global_load_dwordx4 v[48:51], v[16:17], off offset:1024 nt
	s_waitcnt vmcnt(7)
	v_fmamk_f32 v30, v34, 0x3a800000, v21
	v_rsq_f32_e32 v30, v30
	v_lshlrev_b32_e32 v26, 16, v36
	v_and_b32_e32 v27, 0xffff0000, v36
	v_lshlrev_b32_e32 v22, 16, v37
	v_and_b32_e32 v23, 0xffff0000, v37
	v_lshlrev_b32_e32 v28, 16, v38
	v_and_b32_e32 v29, 0xffff0000, v38
	v_lshlrev_b32_e32 v24, 16, v39
	v_and_b32_e32 v25, 0xffff0000, v39
	v_pk_mul_f32 v[26:27], v[30:31], v[26:27] op_sel_hi:[0,1]
	v_pk_mul_f32 v[22:23], v[30:31], v[22:23] op_sel_hi:[0,1]
	v_pk_mul_f32 v[32:33], v[30:31], v[28:29] op_sel_hi:[0,1]
	v_pk_mul_f32 v[28:29], v[30:31], v[24:25] op_sel_hi:[0,1]
	v_pk_mul_f32 v[24:25], v[2:3], v[22:23]
	v_pk_mul_f32 v[22:23], v[0:1], v[26:27]
	v_pk_mul_f32 v[28:29], v[10:11], v[28:29]
	v_pk_mul_f32 v[26:27], v[8:9], v[32:33]
	global_store_dwordx4 v[18:19], v[22:25], off offset:-2048 sc1
	global_store_dwordx4 v[18:19], v[26:29], off offset:-2032 sc1
	v_lshlrev_b32_e32 v56, 16, v40
	v_and_b32_e32 v57, 0xffff0000, v40
	v_lshlrev_b32_e32 v52, 16, v41
	v_and_b32_e32 v53, 0xffff0000, v41
	v_lshlrev_b32_e32 v58, 16, v42
	v_and_b32_e32 v59, 0xffff0000, v42
	v_lshlrev_b32_e32 v54, 16, v43
	v_and_b32_e32 v55, 0xffff0000, v43
	v_pk_mul_f32 v[56:57], v[30:31], v[56:57] op_sel_hi:[0,1]
	v_pk_mul_f32 v[52:53], v[30:31], v[52:53] op_sel_hi:[0,1]
	v_pk_mul_f32 v[62:63], v[30:31], v[58:59] op_sel_hi:[0,1]
	v_pk_mul_f32 v[58:59], v[30:31], v[54:55] op_sel_hi:[0,1]
	v_pk_mul_f32 v[54:55], v[14:15], v[52:53]
	v_pk_mul_f32 v[52:53], v[12:13], v[56:57]
	v_pk_mul_f32 v[58:59], v[6:7], v[58:59]
	v_pk_mul_f32 v[56:57], v[4:5], v[62:63]
	global_store_dwordx4 v[18:19], v[52:55], off sc1
	global_store_dwordx4 v[18:19], v[56:59], off offset:16 sc1
	v_lshl_add_u64 v[18:19], v[18:19], 0, s[6:7]
	s_branch .Lfin_loop
.Lfin_tailA:
	s_waitcnt vmcnt(0)
	v_fmamk_f32 v30, v34, 0x3a800000, v21
	v_rsq_f32_e32 v30, v30
	v_lshlrev_b32_e32 v26, 16, v36
	v_and_b32_e32 v27, 0xffff0000, v36
	v_lshlrev_b32_e32 v22, 16, v37
	v_and_b32_e32 v23, 0xffff0000, v37
	v_lshlrev_b32_e32 v28, 16, v38
	v_and_b32_e32 v29, 0xffff0000, v38
	v_lshlrev_b32_e32 v24, 16, v39
	v_and_b32_e32 v25, 0xffff0000, v39
	v_pk_mul_f32 v[26:27], v[30:31], v[26:27] op_sel_hi:[0,1]
	v_pk_mul_f32 v[22:23], v[30:31], v[22:23] op_sel_hi:[0,1]
	v_pk_mul_f32 v[32:33], v[30:31], v[28:29] op_sel_hi:[0,1]
	v_pk_mul_f32 v[28:29], v[30:31], v[24:25] op_sel_hi:[0,1]
	v_pk_mul_f32 v[24:25], v[2:3], v[22:23]
	v_pk_mul_f32 v[22:23], v[0:1], v[26:27]
	v_pk_mul_f32 v[28:29], v[10:11], v[28:29]
	v_pk_mul_f32 v[26:27], v[8:9], v[32:33]
	global_store_dwordx4 v[18:19], v[22:25], off offset:-2048 sc1
	global_store_dwordx4 v[18:19], v[26:29], off offset:-2032 sc1
	v_lshlrev_b32_e32 v56, 16, v40
	v_and_b32_e32 v57, 0xffff0000, v40
	v_lshlrev_b32_e32 v52, 16, v41
	v_and_b32_e32 v53, 0xffff0000, v41
	v_lshlrev_b32_e32 v58, 16, v42
	v_and_b32_e32 v59, 0xffff0000, v42
	v_lshlrev_b32_e32 v54, 16, v43
	v_and_b32_e32 v55, 0xffff0000, v43
	v_pk_mul_f32 v[56:57], v[30:31], v[56:57] op_sel_hi:[0,1]
	v_pk_mul_f32 v[52:53], v[30:31], v[52:53] op_sel_hi:[0,1]
	v_pk_mul_f32 v[62:63], v[30:31], v[58:59] op_sel_hi:[0,1]
	v_pk_mul_f32 v[58:59], v[30:31], v[54:55] op_sel_hi:[0,1]
	v_pk_mul_f32 v[54:55], v[14:15], v[52:53]
	v_pk_mul_f32 v[52:53], v[12:13], v[56:57]
	v_pk_mul_f32 v[58:59], v[6:7], v[58:59]
	v_pk_mul_f32 v[56:57], v[4:5], v[62:63]
	global_store_dwordx4 v[18:19], v[52:55], off sc1
	global_store_dwordx4 v[18:19], v[56:59], off offset:16 sc1
	v_lshl_add_u64 v[18:19], v[18:19], 0, s[6:7]
	s_branch .LBB0_1412
.Lfin_tailB:
	s_waitcnt vmcnt(0)
	v_fmamk_f32 v30, v35, 0x3a800000, v21
	v_rsq_f32_e32 v30, v30
	v_lshlrev_b32_e32 v26, 16, v44
	v_and_b32_e32 v27, 0xffff0000, v44
	v_lshlrev_b32_e32 v22, 16, v45
	v_and_b32_e32 v23, 0xffff0000, v45
	v_lshlrev_b32_e32 v28, 16, v46
	v_and_b32_e32 v29, 0xffff0000, v46
	v_lshlrev_b32_e32 v24, 16, v47
	v_and_b32_e32 v25, 0xffff0000, v47
	v_pk_mul_f32 v[26:27], v[30:31], v[26:27] op_sel_hi:[0,1]
	v_pk_mul_f32 v[22:23], v[30:31], v[22:23] op_sel_hi:[0,1]
	v_pk_mul_f32 v[32:33], v[30:31], v[28:29] op_sel_hi:[0,1]
	v_pk_mul_f32 v[28:29], v[30:31], v[24:25] op_sel_hi:[0,1]
	v_pk_mul_f32 v[24:25], v[2:3], v[22:23]
	v_pk_mul_f32 v[22:23], v[0:1], v[26:27]
	v_pk_mul_f32 v[28:29], v[10:11], v[28:29]
	v_pk_mul_f32 v[26:27], v[8:9], v[32:33]
	global_store_dwordx4 v[18:19], v[22:25], off offset:-2048 sc1
	global_store_dwordx4 v[18:19], v[26:29], off offset:-2032 sc1
	v_lshlrev_b32_e32 v56, 16, v48
	v_and_b32_e32 v57, 0xffff0000, v48
	v_lshlrev_b32_e32 v52, 16, v49
	v_and_b32_e32 v53, 0xffff0000, v49
	v_lshlrev_b32_e32 v58, 16, v50
	v_and_b32_e32 v59, 0xffff0000, v50
	v_lshlrev_b32_e32 v54, 16, v51
	v_and_b32_e32 v55, 0xffff0000, v51
	v_pk_mul_f32 v[56:57], v[30:31], v[56:57] op_sel_hi:[0,1]
	v_pk_mul_f32 v[52:53], v[30:31], v[52:53] op_sel_hi:[0,1]
	v_pk_mul_f32 v[62:63], v[30:31], v[58:59] op_sel_hi:[0,1]
	v_pk_mul_f32 v[58:59], v[30:31], v[54:55] op_sel_hi:[0,1]
	v_pk_mul_f32 v[54:55], v[14:15], v[52:53]
	v_pk_mul_f32 v[52:53], v[12:13], v[56:57]
	v_pk_mul_f32 v[58:59], v[6:7], v[58:59]
	v_pk_mul_f32 v[56:57], v[4:5], v[62:63]
	global_store_dwordx4 v[18:19], v[52:55], off sc1
	global_store_dwordx4 v[18:19], v[56:59], off offset:16 sc1
	v_lshl_add_u64 v[18:19], v[18:19], 0, s[6:7]
